# v2: + fused top-k rank loop (64-bit key compare), permlane-swap max all-reduce in sel/win loops, batched loads in compressed branch, relaxed store waits in in-proj rope epilogue
# speedup vs baseline: 1.0777x; 1.0047x over previous
.LBB0_259:
	s_add_u32 s38, s18, s38
	s_addc_u32 s39, s19, s39
	v_lshl_add_u64 v[234:235], v[232:233], 1, s[38:39]
	s_ashr_i32 s38, s29, 12
	s_mul_i32 s38, s40, s38
	s_add_i32 s38, s38, s31
	s_ashr_i32 s39, s38, 31
	s_lshl_b64 s[38:39], s[38:39], 19
	v_cvt_pk_bf16_f32 v128, v128, v129
	v_cvt_pk_bf16_f32 v129, v130, v131
	v_cvt_pk_bf16_f32 v130, v132, v133
	v_lshlrev_b32_e32 v132, 7, v228
	v_lshl_add_u64 v[204:205], v[234:235], 0, s[38:39]
	v_and_b32_e32 v136, 0x7e780, v132
	v_cvt_pk_bf16_f32 v131, v134, v135
	v_lshl_add_u64 v[236:237], v[204:205], 0, v[136:137]
	global_store_dwordx4 v[236:237], v[128:131], off nt
	v_mov_b64_e32 v[134:135], v[118:119]
	s_and_b64 vcc, exec, s[8:9]
	v_mov_b64_e32 v[132:133], v[116:117]
	v_mov_b64_e32 v[130:131], v[114:115]
	v_mov_b64_e32 v[128:129], v[112:113]
	s_cbranch_vccnz .LBB0_261
	ds_bpermute_b32 v128, v202, v112
	ds_bpermute_b32 v129, v202, v113
	ds_bpermute_b32 v130, v202, v114
	ds_bpermute_b32 v131, v202, v115
	ds_bpermute_b32 v132, v202, v116
	ds_bpermute_b32 v133, v202, v117
	ds_bpermute_b32 v134, v202, v118
	ds_bpermute_b32 v135, v202, v119
	s_waitcnt lgkmcnt(0)
	v_mul_f32_e32 v128, v182, v128
	v_mul_f32_e32 v129, v183, v129
	v_mul_f32_e32 v130, v184, v130
	v_mul_f32_e32 v131, v185, v131
	v_mul_f32_e32 v132, v174, v132
	v_mul_f32_e32 v133, v175, v133
	v_mul_f32_e32 v134, v176, v134
	v_mul_f32_e32 v135, v177, v135
	v_cndmask_b32_e64 v128, v128, -v128, s[6:7]
	v_cndmask_b32_e64 v129, v129, -v129, s[6:7]
	v_cndmask_b32_e64 v130, v130, -v130, s[6:7]
	v_cndmask_b32_e64 v131, v131, -v131, s[6:7]
	v_cndmask_b32_e64 v132, v132, -v132, s[6:7]
	v_cndmask_b32_e64 v133, v133, -v133, s[6:7]
	v_cndmask_b32_e64 v134, v134, -v134, s[6:7]
	v_cndmask_b32_e64 v135, v135, -v135, s[6:7]
	v_fmac_f32_e32 v128, v112, v178
	v_fmac_f32_e32 v129, v179, v113
	v_fmac_f32_e32 v130, v180, v114
	v_fmac_f32_e32 v131, v181, v115
	v_fmac_f32_e32 v132, v170, v116
	v_fmac_f32_e32 v133, v171, v117
	v_fmac_f32_e32 v134, v172, v118
	v_fmac_f32_e32 v135, v173, v119
	v_cndmask_b32_e64 v128, v112, v128, s[4:5]
	v_cndmask_b32_e64 v135, v119, v135, s[4:5]
	v_cndmask_b32_e64 v134, v118, v134, s[4:5]
	v_cndmask_b32_e64 v133, v117, v133, s[4:5]
	v_cndmask_b32_e64 v132, v116, v132, s[4:5]
	v_cndmask_b32_e64 v131, v115, v131, s[4:5]
	v_cndmask_b32_e64 v130, v114, v130, s[4:5]
	v_cndmask_b32_e64 v129, v113, v129, s[4:5]
.LBB0_261:
	v_cvt_pk_bf16_f32 v128, v128, v129
	v_cvt_pk_bf16_f32 v129, v130, v131
	v_cvt_pk_bf16_f32 v130, v132, v133
	v_cvt_pk_bf16_f32 v131, v134, v135
	global_store_dwordx4 v[236:237], v[128:131], off offset:2048 nt
	v_mov_b64_e32 v[134:135], v[110:111]
	s_and_b64 vcc, exec, s[8:9]
	v_mov_b64_e32 v[132:133], v[108:109]
	v_mov_b64_e32 v[130:131], v[106:107]
	v_mov_b64_e32 v[128:129], v[104:105]
	s_cbranch_vccnz .LBB0_263
	ds_bpermute_b32 v128, v202, v104
	ds_bpermute_b32 v129, v202, v105
	ds_bpermute_b32 v130, v202, v106
	ds_bpermute_b32 v131, v202, v107
	ds_bpermute_b32 v132, v202, v108
	ds_bpermute_b32 v133, v202, v109
	ds_bpermute_b32 v134, v202, v110
	ds_bpermute_b32 v135, v202, v111
	s_waitcnt lgkmcnt(0)
	v_mul_f32_e32 v128, v162, v128
	v_mul_f32_e32 v129, v163, v129
	v_mul_f32_e32 v130, v164, v130
	v_mul_f32_e32 v131, v165, v131
	v_mul_f32_e32 v132, v158, v132
	v_mul_f32_e32 v133, v159, v133
	v_mul_f32_e32 v134, v160, v134
	v_mul_f32_e32 v135, v161, v135
	v_cndmask_b32_e64 v128, v128, -v128, s[6:7]
	v_cndmask_b32_e64 v129, v129, -v129, s[6:7]
	v_cndmask_b32_e64 v130, v130, -v130, s[6:7]
	v_cndmask_b32_e64 v131, v131, -v131, s[6:7]
	v_cndmask_b32_e64 v132, v132, -v132, s[6:7]
	v_cndmask_b32_e64 v133, v133, -v133, s[6:7]
	v_cndmask_b32_e64 v134, v134, -v134, s[6:7]
	v_cndmask_b32_e64 v135, v135, -v135, s[6:7]
	v_fmac_f32_e32 v128, v104, v166
	v_fmac_f32_e32 v129, v167, v105
	v_fmac_f32_e32 v130, v168, v106
	v_fmac_f32_e32 v131, v169, v107
	v_fmac_f32_e32 v132, v154, v108
	v_fmac_f32_e32 v133, v155, v109
	v_fmac_f32_e32 v134, v156, v110
	v_fmac_f32_e32 v135, v157, v111
	v_cndmask_b32_e64 v128, v104, v128, s[4:5]
	v_cndmask_b32_e64 v135, v111, v135, s[4:5]
	v_cndmask_b32_e64 v134, v110, v134, s[4:5]
	v_cndmask_b32_e64 v133, v109, v133, s[4:5]
	v_cndmask_b32_e64 v132, v108, v132, s[4:5]
	v_cndmask_b32_e64 v131, v107, v131, s[4:5]
	v_cndmask_b32_e64 v130, v106, v130, s[4:5]
	v_cndmask_b32_e64 v129, v105, v129, s[4:5]
.LBB0_263:
	v_cvt_pk_bf16_f32 v128, v128, v129
	v_cvt_pk_bf16_f32 v129, v130, v131
	v_cvt_pk_bf16_f32 v130, v132, v133
	v_add_co_u32_e32 v132, vcc, 0x1000, v236
	v_cvt_pk_bf16_f32 v131, v134, v135
	s_nop 0
	v_addc_co_u32_e32 v133, vcc, 0, v237, vcc
	global_store_dwordx4 v[132:133], v[128:131], off nt
	v_mov_b64_e32 v[134:135], v[102:103]
	s_and_b64 vcc, exec, s[8:9]
	v_mov_b64_e32 v[132:133], v[100:101]
	v_mov_b64_e32 v[130:131], v[98:99]
	v_mov_b64_e32 v[128:129], v[96:97]
	s_cbranch_vccnz .LBB0_265
	ds_bpermute_b32 v128, v202, v96
	ds_bpermute_b32 v129, v202, v97
	ds_bpermute_b32 v130, v202, v98
	ds_bpermute_b32 v131, v202, v99
	ds_bpermute_b32 v132, v202, v100
	ds_bpermute_b32 v133, v202, v101
	ds_bpermute_b32 v134, v202, v102
	ds_bpermute_b32 v135, v202, v103
	s_waitcnt lgkmcnt(0)
	v_mul_f32_e32 v128, v150, v128
	v_mul_f32_e32 v129, v151, v129
	v_mul_f32_e32 v130, v152, v130
	v_mul_f32_e32 v131, v153, v131
	v_mul_f32_e32 v132, v142, v132
	v_mul_f32_e32 v133, v143, v133
	v_mul_f32_e32 v134, v144, v134
	v_mul_f32_e32 v135, v145, v135
	v_cndmask_b32_e64 v128, v128, -v128, s[6:7]
	v_cndmask_b32_e64 v129, v129, -v129, s[6:7]
	v_cndmask_b32_e64 v130, v130, -v130, s[6:7]
	v_cndmask_b32_e64 v131, v131, -v131, s[6:7]
	v_cndmask_b32_e64 v132, v132, -v132, s[6:7]
	v_cndmask_b32_e64 v133, v133, -v133, s[6:7]
	v_cndmask_b32_e64 v134, v134, -v134, s[6:7]
	v_cndmask_b32_e64 v135, v135, -v135, s[6:7]
	v_fmac_f32_e32 v128, v96, v146
	v_fmac_f32_e32 v129, v147, v97
	v_fmac_f32_e32 v130, v148, v98
	v_fmac_f32_e32 v131, v149, v99
	v_fmac_f32_e32 v132, v138, v100
	v_fmac_f32_e32 v133, v139, v101
	v_fmac_f32_e32 v134, v140, v102
	v_fmac_f32_e32 v135, v141, v103
	v_cndmask_b32_e64 v128, v96, v128, s[4:5]
	v_cndmask_b32_e64 v135, v103, v135, s[4:5]
	v_cndmask_b32_e64 v134, v102, v134, s[4:5]
	v_cndmask_b32_e64 v133, v101, v133, s[4:5]
	v_cndmask_b32_e64 v132, v100, v132, s[4:5]
	v_cndmask_b32_e64 v131, v99, v131, s[4:5]
	v_cndmask_b32_e64 v130, v98, v130, s[4:5]
	v_cndmask_b32_e64 v129, v97, v129, s[4:5]
.LBB0_265:
	v_cvt_pk_bf16_f32 v128, v128, v129
	v_cvt_pk_bf16_f32 v129, v130, v131
	v_cvt_pk_bf16_f32 v130, v132, v133
	v_add_co_u32_e32 v132, vcc, 0x1000, v236
	v_cvt_pk_bf16_f32 v131, v134, v135
	s_nop 0
	v_addc_co_u32_e32 v133, vcc, 0, v237, vcc
	s_and_b64 vcc, exec, s[8:9]
	v_add_u32_e32 v236, 0x80, v228
	global_store_dwordx4 v[132:133], v[128:131], off offset:2048 nt
	s_cbranch_vccnz .LBB0_267
	v_ashrrev_i32_e32 v237, 31, v236
	v_lshlrev_b64 v[128:129], 6, v[236:237]
	v_lshl_add_u64 v[128:129], s[20:21], 0, v[128:129]
	v_ashrrev_i32_e32 v229, 31, v228
	s_waitcnt lgkmcnt(0)
	flat_load_dwordx4 v[194:197], v[128:129]
	flat_load_dwordx4 v[186:189], v[128:129] offset:16
	flat_load_dwordx4 v[198:201], v[128:129] offset:32
	flat_load_dwordx4 v[190:193], v[128:129] offset:48
	v_lshlrev_b64 v[128:129], 6, v[228:229]
	v_lshl_add_u64 v[128:129], s[20:21], 0, v[128:129]
	s_mov_b64 s[38:39], 0x2400
	v_lshl_add_u64 v[130:131], v[128:129], 0, s[38:39]
	v_add_co_u32_e32 v132, vcc, 0x2000, v128
	s_mov_b64 s[38:39], 0x2800
	s_nop 0
	v_addc_co_u32_e32 v133, vcc, 0, v129, vcc
	flat_load_dwordx4 v[170:173], v[130:131] offset:16
	flat_load_dwordx4 v[182:185], v[130:131] offset:32
	flat_load_dwordx4 v[178:181], v[132:133] offset:1024
	flat_load_dwordx4 v[174:177], v[130:131] offset:48
	v_lshl_add_u64 v[130:131], v[128:129], 0, s[38:39]
	s_mov_b64 s[38:39], 0x2c00
	flat_load_dwordx4 v[154:157], v[130:131] offset:16
	flat_load_dwordx4 v[162:165], v[130:131] offset:32
	v_lshl_add_u64 v[128:129], v[128:129], 0, s[38:39]
	flat_load_dwordx4 v[166:169], v[132:133] offset:2048
	flat_load_dwordx4 v[146:149], v[132:133] offset:3072
	flat_load_dwordx4 v[158:161], v[130:131] offset:48
	flat_load_dwordx4 v[138:141], v[128:129] offset:16
	flat_load_dwordx4 v[150:153], v[128:129] offset:32
	flat_load_dwordx4 v[142:145], v[128:129] offset:48

.LBB0_269:
	v_ashrrev_i32_e32 v136, 12, v236
	v_mov_b32_e32 v203, s31
	v_mad_i32_i24 v204, s40, v136, v203
	v_ashrrev_i32_e32 v205, 31, v204
	v_lshlrev_b64 v[204:205], 19, v[204:205]
	v_cvt_pk_bf16_f32 v128, v128, v129
	v_cvt_pk_bf16_f32 v129, v130, v131
	v_cvt_pk_bf16_f32 v130, v132, v133
	v_lshlrev_b32_e32 v132, 7, v236
	v_lshl_add_u64 v[204:205], v[234:235], 0, v[204:205]
	v_and_b32_e32 v136, 0x7e780, v132
	v_cvt_pk_bf16_f32 v131, v134, v135
	v_lshl_add_u64 v[234:235], v[204:205], 0, v[136:137]
	global_store_dwordx4 v[234:235], v[128:131], off nt
	v_mov_b64_e32 v[134:135], v[86:87]
	s_and_b64 vcc, exec, s[8:9]
	v_mov_b64_e32 v[132:133], v[84:85]
	v_mov_b64_e32 v[130:131], v[82:83]
	v_mov_b64_e32 v[128:129], v[80:81]
	s_cbranch_vccnz .LBB0_271
	ds_bpermute_b32 v128, v202, v80
	ds_bpermute_b32 v129, v202, v81
	ds_bpermute_b32 v130, v202, v82
	ds_bpermute_b32 v131, v202, v83
	ds_bpermute_b32 v132, v202, v84
	ds_bpermute_b32 v133, v202, v85
	ds_bpermute_b32 v134, v202, v86
	ds_bpermute_b32 v135, v202, v87
	s_waitcnt lgkmcnt(0)
	v_mul_f32_e32 v128, v182, v128
	v_mul_f32_e32 v129, v183, v129
	v_mul_f32_e32 v130, v184, v130
	v_mul_f32_e32 v131, v185, v131
	v_mul_f32_e32 v132, v174, v132
	v_mul_f32_e32 v133, v175, v133
	v_mul_f32_e32 v134, v176, v134
	v_mul_f32_e32 v135, v177, v135
	v_cndmask_b32_e64 v128, v128, -v128, s[6:7]
	v_cndmask_b32_e64 v129, v129, -v129, s[6:7]
	v_cndmask_b32_e64 v130, v130, -v130, s[6:7]
	v_cndmask_b32_e64 v131, v131, -v131, s[6:7]
	v_cndmask_b32_e64 v132, v132, -v132, s[6:7]
	v_cndmask_b32_e64 v133, v133, -v133, s[6:7]
	v_cndmask_b32_e64 v134, v134, -v134, s[6:7]
	v_cndmask_b32_e64 v135, v135, -v135, s[6:7]
	v_fmac_f32_e32 v128, v80, v178
	v_fmac_f32_e32 v129, v179, v81
	v_fmac_f32_e32 v130, v180, v82
	v_fmac_f32_e32 v131, v181, v83
	v_fmac_f32_e32 v132, v170, v84
	v_fmac_f32_e32 v133, v171, v85
	v_fmac_f32_e32 v134, v172, v86
	v_fmac_f32_e32 v135, v173, v87
	v_cndmask_b32_e64 v128, v80, v128, s[4:5]
	v_cndmask_b32_e64 v135, v87, v135, s[4:5]
	v_cndmask_b32_e64 v134, v86, v134, s[4:5]
	v_cndmask_b32_e64 v133, v85, v133, s[4:5]
	v_cndmask_b32_e64 v132, v84, v132, s[4:5]
	v_cndmask_b32_e64 v131, v83, v131, s[4:5]
	v_cndmask_b32_e64 v130, v82, v130, s[4:5]
	v_cndmask_b32_e64 v129, v81, v129, s[4:5]
.LBB0_271:
	v_cvt_pk_bf16_f32 v128, v128, v129
	v_cvt_pk_bf16_f32 v129, v130, v131
	v_cvt_pk_bf16_f32 v130, v132, v133
	v_cvt_pk_bf16_f32 v131, v134, v135
	global_store_dwordx4 v[234:235], v[128:131], off offset:2048 nt
	v_mov_b64_e32 v[134:135], v[78:79]
	s_and_b64 vcc, exec, s[8:9]
	v_mov_b64_e32 v[132:133], v[76:77]
	v_mov_b64_e32 v[130:131], v[74:75]
	v_mov_b64_e32 v[128:129], v[72:73]
	s_cbranch_vccnz .LBB0_273
	ds_bpermute_b32 v128, v202, v72
	ds_bpermute_b32 v129, v202, v73
	ds_bpermute_b32 v130, v202, v74
	ds_bpermute_b32 v131, v202, v75
	ds_bpermute_b32 v132, v202, v76
	ds_bpermute_b32 v133, v202, v77
	ds_bpermute_b32 v134, v202, v78
	ds_bpermute_b32 v135, v202, v79
	s_waitcnt lgkmcnt(0)
	v_mul_f32_e32 v128, v162, v128
	v_mul_f32_e32 v129, v163, v129
	v_mul_f32_e32 v130, v164, v130
	v_mul_f32_e32 v131, v165, v131
	v_mul_f32_e32 v132, v158, v132
	v_mul_f32_e32 v133, v159, v133
	v_mul_f32_e32 v134, v160, v134
	v_mul_f32_e32 v135, v161, v135
	v_cndmask_b32_e64 v128, v128, -v128, s[6:7]
	v_cndmask_b32_e64 v129, v129, -v129, s[6:7]
	v_cndmask_b32_e64 v130, v130, -v130, s[6:7]
	v_cndmask_b32_e64 v131, v131, -v131, s[6:7]
	v_cndmask_b32_e64 v132, v132, -v132, s[6:7]
	v_cndmask_b32_e64 v133, v133, -v133, s[6:7]
	v_cndmask_b32_e64 v134, v134, -v134, s[6:7]
	v_cndmask_b32_e64 v135, v135, -v135, s[6:7]
	v_fmac_f32_e32 v128, v72, v166
	v_fmac_f32_e32 v129, v167, v73
	v_fmac_f32_e32 v130, v168, v74
	v_fmac_f32_e32 v131, v169, v75
	v_fmac_f32_e32 v132, v154, v76
	v_fmac_f32_e32 v133, v155, v77
	v_fmac_f32_e32 v134, v156, v78
	v_fmac_f32_e32 v135, v157, v79
	v_cndmask_b32_e64 v128, v72, v128, s[4:5]
	v_cndmask_b32_e64 v135, v79, v135, s[4:5]
	v_cndmask_b32_e64 v134, v78, v134, s[4:5]
	v_cndmask_b32_e64 v133, v77, v133, s[4:5]
	v_cndmask_b32_e64 v132, v76, v132, s[4:5]
	v_cndmask_b32_e64 v131, v75, v131, s[4:5]
	v_cndmask_b32_e64 v130, v74, v130, s[4:5]
	v_cndmask_b32_e64 v129, v73, v129, s[4:5]
.LBB0_273:
	v_cvt_pk_bf16_f32 v128, v128, v129
	v_cvt_pk_bf16_f32 v129, v130, v131
	v_cvt_pk_bf16_f32 v130, v132, v133
	v_add_co_u32_e32 v132, vcc, 0x1000, v234
	v_cvt_pk_bf16_f32 v131, v134, v135
	s_nop 0
	v_addc_co_u32_e32 v133, vcc, 0, v235, vcc
	global_store_dwordx4 v[132:133], v[128:131], off nt
	v_mov_b64_e32 v[134:135], v[70:71]
	s_and_b64 vcc, exec, s[8:9]
	v_mov_b64_e32 v[132:133], v[68:69]
	v_mov_b64_e32 v[130:131], v[66:67]
	v_mov_b64_e32 v[128:129], v[64:65]
	s_cbranch_vccnz .LBB0_275
	ds_bpermute_b32 v128, v202, v64
	ds_bpermute_b32 v129, v202, v65
	ds_bpermute_b32 v130, v202, v66
	ds_bpermute_b32 v131, v202, v67
	ds_bpermute_b32 v132, v202, v68
	ds_bpermute_b32 v133, v202, v69
	ds_bpermute_b32 v134, v202, v70
	ds_bpermute_b32 v135, v202, v71
	s_waitcnt lgkmcnt(0)
	v_mul_f32_e32 v128, v150, v128
	v_mul_f32_e32 v129, v151, v129
	v_mul_f32_e32 v130, v152, v130
	v_mul_f32_e32 v131, v153, v131
	v_mul_f32_e32 v132, v142, v132
	v_mul_f32_e32 v133, v143, v133
	v_mul_f32_e32 v134, v144, v134
	v_mul_f32_e32 v135, v145, v135
	v_cndmask_b32_e64 v128, v128, -v128, s[6:7]
	v_cndmask_b32_e64 v129, v129, -v129, s[6:7]
	v_cndmask_b32_e64 v130, v130, -v130, s[6:7]
	v_cndmask_b32_e64 v131, v131, -v131, s[6:7]
	v_cndmask_b32_e64 v132, v132, -v132, s[6:7]
	v_cndmask_b32_e64 v133, v133, -v133, s[6:7]
	v_cndmask_b32_e64 v134, v134, -v134, s[6:7]
	v_cndmask_b32_e64 v135, v135, -v135, s[6:7]
	v_fmac_f32_e32 v128, v64, v146
	v_fmac_f32_e32 v129, v147, v65
	v_fmac_f32_e32 v130, v148, v66
	v_fmac_f32_e32 v131, v149, v67
	v_fmac_f32_e32 v132, v138, v68
	v_fmac_f32_e32 v133, v139, v69
	v_fmac_f32_e32 v134, v140, v70
	v_fmac_f32_e32 v135, v141, v71
	v_cndmask_b32_e64 v128, v64, v128, s[4:5]
	v_cndmask_b32_e64 v135, v71, v135, s[4:5]
	v_cndmask_b32_e64 v134, v70, v134, s[4:5]
	v_cndmask_b32_e64 v133, v69, v133, s[4:5]
	v_cndmask_b32_e64 v132, v68, v132, s[4:5]
	v_cndmask_b32_e64 v131, v67, v131, s[4:5]
	v_cndmask_b32_e64 v130, v66, v130, s[4:5]
	v_cndmask_b32_e64 v129, v65, v129, s[4:5]
.LBB0_275:
	v_cvt_pk_bf16_f32 v128, v128, v129
	v_cvt_pk_bf16_f32 v129, v130, v131
	v_cvt_pk_bf16_f32 v130, v132, v133
	v_add_co_u32_e32 v132, vcc, 0x1000, v234
	v_cvt_pk_bf16_f32 v131, v134, v135
	s_nop 0
	v_addc_co_u32_e32 v133, vcc, 0, v235, vcc
	s_mov_b64 s[8:9], 0
	global_store_dwordx4 v[132:133], v[128:131], off offset:2048 nt
.LBB0_276:
	s_and_b64 vcc, exec, s[8:9]
	s_cbranch_vccz .LBB0_278
	v_mul_f32_e32 v124, 0xbfb8aa3b, v124
	v_exp_f32_e32 v124, v124
	v_mul_f32_e32 v125, 0xbfb8aa3b, v125
	v_exp_f32_e32 v125, v125
	v_mul_f32_e32 v120, 0xbfb8aa3b, v120
	v_add_f32_e32 v124, 1.0, v124
	v_mul_f32_e32 v121, 0xbfb8aa3b, v121
	v_rcp_f32_e32 v128, v124
	v_add_f32_e32 v124, 1.0, v125
	v_mul_f32_e32 v125, 0xbfb8aa3b, v126
	v_exp_f32_e32 v120, v120
	v_exp_f32_e32 v121, v121
	v_mul_f32_e32 v122, 0xbfb8aa3b, v122
	v_mul_f32_e32 v123, 0xbfb8aa3b, v123
	v_exp_f32_e32 v125, v125
	v_mul_f32_e32 v126, 0xbfb8aa3b, v127
	v_exp_f32_e32 v122, v122
	v_exp_f32_e32 v123, v123
	v_exp_f32_e32 v126, v126
	v_add_f32_e32 v120, 1.0, v120
	v_add_f32_e32 v121, 1.0, v121
	v_rcp_f32_e32 v127, v124
	v_add_f32_e32 v124, 1.0, v125
	v_rcp_f32_e32 v120, v120
	v_rcp_f32_e32 v121, v121
	v_add_f32_e32 v122, 1.0, v122
	v_add_f32_e32 v123, 1.0, v123
	v_rcp_f32_e32 v129, v124
	v_add_f32_e32 v124, 1.0, v126
	v_mul_f32_e32 v112, 0xbfb8aa3b, v112
	v_mul_f32_e32 v113, 0xbfb8aa3b, v113
	v_mul_f32_e32 v114, 0xbfb8aa3b, v114
	v_mul_f32_e32 v115, 0xbfb8aa3b, v115
	v_mul_f32_e32 v116, 0xbfb8aa3b, v116
	v_mul_f32_e32 v117, 0xbfb8aa3b, v117
	s_lshl_b64 s[8:9], s[92:93], 1
	v_rcp_f32_e32 v122, v122
	v_rcp_f32_e32 v123, v123
	v_rcp_f32_e32 v130, v124
	v_exp_f32_e32 v112, v112
	v_exp_f32_e32 v113, v113
	v_exp_f32_e32 v114, v114
	v_exp_f32_e32 v115, v115
	v_exp_f32_e32 v116, v116
	v_exp_f32_e32 v117, v117
	s_add_u32 s8, s18, s8
	s_addc_u32 s9, s19, s9
	v_mul_f32_e32 v118, 0xbfb8aa3b, v118
	v_mul_f32_e32 v119, 0xbfb8aa3b, v119
	v_cvt_pk_bf16_f32 v124, v120, v121
	v_mov_b64_e32 v[120:121], s[8:9]
	s_movk_i32 s31, 0x1800
	v_exp_f32_e32 v118, v118
	v_exp_f32_e32 v119, v119
	v_cvt_pk_bf16_f32 v125, v122, v123
	v_cvt_pk_bf16_f32 v126, v128, v127
	v_cvt_pk_bf16_f32 v127, v129, v130
	v_mad_i64_i32 v[128:129], s[8:9], v228, s31, v[120:121]
	v_lshlrev_b64 v[122:123], 1, v[230:231]
	v_add_f32_e32 v112, 1.0, v112
	v_add_f32_e32 v113, 1.0, v113
	v_add_f32_e32 v114, 1.0, v114
	v_add_f32_e32 v115, 1.0, v115
	v_add_f32_e32 v116, 1.0, v116
	v_add_f32_e32 v117, 1.0, v117
	v_mul_f32_e32 v104, 0xbfb8aa3b, v104
	v_mul_f32_e32 v105, 0xbfb8aa3b, v105
	v_mul_f32_e32 v106, 0xbfb8aa3b, v106
	v_mul_f32_e32 v107, 0xbfb8aa3b, v107
	v_mul_f32_e32 v108, 0xbfb8aa3b, v108
	v_mul_f32_e32 v109, 0xbfb8aa3b, v109
	v_lshl_add_u64 v[128:129], v[128:129], 0, v[122:123]
	s_mov_b32 s38, 0xc9fd000
	v_rcp_f32_e32 v112, v112
	v_rcp_f32_e32 v113, v113
	v_rcp_f32_e32 v114, v114
	v_rcp_f32_e32 v115, v115
	v_rcp_f32_e32 v116, v116
	v_rcp_f32_e32 v117, v117
	v_exp_f32_e32 v104, v104
	v_exp_f32_e32 v105, v105
	v_exp_f32_e32 v106, v106
	v_exp_f32_e32 v107, v107
	v_exp_f32_e32 v108, v108
	v_exp_f32_e32 v109, v109
	v_add_co_u32_e32 v128, vcc, s38, v128
	v_add_f32_e32 v118, 1.0, v118
	s_nop 0
	v_addc_co_u32_e32 v129, vcc, 0, v129, vcc
	v_add_f32_e32 v119, 1.0, v119
	v_mul_f32_e32 v110, 0xbfb8aa3b, v110
	v_mul_f32_e32 v111, 0xbfb8aa3b, v111
	global_store_dwordx4 v[128:129], v[124:127], off nt
	v_rcp_f32_e32 v118, v118
	v_rcp_f32_e32 v119, v119
	v_or_b32_e32 v124, 16, v228
	v_exp_f32_e32 v110, v110
	v_exp_f32_e32 v111, v111
	v_cvt_pk_bf16_f32 v112, v112, v113
	v_cvt_pk_bf16_f32 v113, v114, v115
	v_cvt_pk_bf16_f32 v114, v116, v117
	v_mad_i64_i32 v[116:117], s[8:9], v124, s31, v[120:121]
	v_add_f32_e32 v104, 1.0, v104
	v_add_f32_e32 v105, 1.0, v105
	v_add_f32_e32 v106, 1.0, v106
	v_add_f32_e32 v107, 1.0, v107
	v_add_f32_e32 v108, 1.0, v108
	v_add_f32_e32 v109, 1.0, v109
	v_mul_f32_e32 v96, 0xbfb8aa3b, v96
	v_mul_f32_e32 v97, 0xbfb8aa3b, v97
	v_mul_f32_e32 v98, 0xbfb8aa3b, v98
	v_mul_f32_e32 v99, 0xbfb8aa3b, v99
	v_mul_f32_e32 v100, 0xbfb8aa3b, v100
	v_mul_f32_e32 v101, 0xbfb8aa3b, v101
	v_lshl_add_u64 v[116:117], v[116:117], 0, v[122:123]
	v_rcp_f32_e32 v104, v104
	v_rcp_f32_e32 v105, v105
	v_rcp_f32_e32 v106, v106
	v_rcp_f32_e32 v107, v107
	v_rcp_f32_e32 v108, v108
	v_rcp_f32_e32 v109, v109
	v_exp_f32_e32 v96, v96
	v_exp_f32_e32 v97, v97
	v_exp_f32_e32 v98, v98
	v_exp_f32_e32 v99, v99
	v_exp_f32_e32 v100, v100
	v_exp_f32_e32 v101, v101
	v_add_co_u32_e32 v116, vcc, s38, v116
	v_cvt_pk_bf16_f32 v115, v118, v119
	s_nop 0
	v_addc_co_u32_e32 v117, vcc, 0, v117, vcc
	v_add_f32_e32 v110, 1.0, v110
	v_add_f32_e32 v111, 1.0, v111
	v_mul_f32_e32 v102, 0xbfb8aa3b, v102
	v_mul_f32_e32 v103, 0xbfb8aa3b, v103
	global_store_dwordx4 v[116:117], v[112:115], off nt
	v_rcp_f32_e32 v110, v110
	v_rcp_f32_e32 v111, v111
	v_or_b32_e32 v112, 32, v228
	v_exp_f32_e32 v102, v102
	v_exp_f32_e32 v103, v103
	v_cvt_pk_bf16_f32 v104, v104, v105
	v_cvt_pk_bf16_f32 v105, v106, v107
	v_cvt_pk_bf16_f32 v106, v108, v109
	v_mad_i64_i32 v[108:109], s[8:9], v112, s31, v[120:121]
	v_add_f32_e32 v96, 1.0, v96
	v_add_f32_e32 v97, 1.0, v97
	v_add_f32_e32 v98, 1.0, v98
	v_add_f32_e32 v99, 1.0, v99
	v_add_f32_e32 v100, 1.0, v100
	v_add_f32_e32 v101, 1.0, v101
	v_mul_f32_e32 v88, 0xbfb8aa3b, v88
	v_mul_f32_e32 v89, 0xbfb8aa3b, v89
	v_mul_f32_e32 v90, 0xbfb8aa3b, v90
	v_mul_f32_e32 v91, 0xbfb8aa3b, v91
	v_mul_f32_e32 v92, 0xbfb8aa3b, v92
	v_mul_f32_e32 v93, 0xbfb8aa3b, v93
	v_lshl_add_u64 v[108:109], v[108:109], 0, v[122:123]
	v_rcp_f32_e32 v96, v96
	v_rcp_f32_e32 v97, v97
	v_rcp_f32_e32 v98, v98
	v_rcp_f32_e32 v99, v99
	v_rcp_f32_e32 v100, v100
	v_rcp_f32_e32 v101, v101
	v_exp_f32_e32 v88, v88
	v_exp_f32_e32 v89, v89
	v_exp_f32_e32 v90, v90
	v_exp_f32_e32 v91, v91
	v_exp_f32_e32 v92, v92
	v_exp_f32_e32 v93, v93
	v_add_co_u32_e32 v108, vcc, s38, v108
	v_cvt_pk_bf16_f32 v107, v110, v111
	s_nop 0
	v_addc_co_u32_e32 v109, vcc, 0, v109, vcc
	v_add_f32_e32 v102, 1.0, v102
	v_add_f32_e32 v103, 1.0, v103
	v_mul_f32_e32 v94, 0xbfb8aa3b, v94
	v_mul_f32_e32 v95, 0xbfb8aa3b, v95
	global_store_dwordx4 v[108:109], v[104:107], off nt
	v_rcp_f32_e32 v102, v102
	v_rcp_f32_e32 v103, v103
	v_or_b32_e32 v104, 48, v228
	v_exp_f32_e32 v94, v94
	v_exp_f32_e32 v95, v95
	v_cvt_pk_bf16_f32 v96, v96, v97
	v_cvt_pk_bf16_f32 v97, v98, v99
	v_cvt_pk_bf16_f32 v98, v100, v101
	v_mad_i64_i32 v[100:101], s[8:9], v104, s31, v[120:121]
	v_add_f32_e32 v88, 1.0, v88
	v_add_f32_e32 v89, 1.0, v89
	v_add_f32_e32 v90, 1.0, v90
	v_add_f32_e32 v91, 1.0, v91
	v_add_f32_e32 v92, 1.0, v92
	v_add_f32_e32 v93, 1.0, v93
	v_mul_f32_e32 v80, 0xbfb8aa3b, v80
	v_mul_f32_e32 v81, 0xbfb8aa3b, v81
	v_mul_f32_e32 v82, 0xbfb8aa3b, v82
	v_mul_f32_e32 v83, 0xbfb8aa3b, v83
	v_mul_f32_e32 v84, 0xbfb8aa3b, v84
	v_mul_f32_e32 v85, 0xbfb8aa3b, v85
	v_lshl_add_u64 v[100:101], v[100:101], 0, v[122:123]
	v_rcp_f32_e32 v88, v88
	v_rcp_f32_e32 v89, v89
	v_rcp_f32_e32 v90, v90
	v_rcp_f32_e32 v91, v91
	v_rcp_f32_e32 v92, v92
	v_rcp_f32_e32 v93, v93
	v_exp_f32_e32 v80, v80
	v_exp_f32_e32 v81, v81
	v_exp_f32_e32 v82, v82
	v_exp_f32_e32 v83, v83
	v_exp_f32_e32 v84, v84
	v_exp_f32_e32 v85, v85
	v_add_co_u32_e32 v100, vcc, s38, v100
	v_cvt_pk_bf16_f32 v99, v102, v103
	s_nop 0
	v_addc_co_u32_e32 v101, vcc, 0, v101, vcc
	v_add_f32_e32 v94, 1.0, v94
	v_add_f32_e32 v95, 1.0, v95
	v_mul_f32_e32 v86, 0xbfb8aa3b, v86
	v_mul_f32_e32 v87, 0xbfb8aa3b, v87
	global_store_dwordx4 v[100:101], v[96:99], off nt
	v_rcp_f32_e32 v94, v94
	v_rcp_f32_e32 v95, v95
	v_add_u32_e32 v96, 0x80, v228
	v_exp_f32_e32 v86, v86
	v_exp_f32_e32 v87, v87
	v_cvt_pk_bf16_f32 v88, v88, v89
	v_cvt_pk_bf16_f32 v89, v90, v91
	v_cvt_pk_bf16_f32 v90, v92, v93
	v_mad_i64_i32 v[92:93], s[8:9], v96, s31, v[120:121]
	v_add_f32_e32 v80, 1.0, v80
	v_add_f32_e32 v81, 1.0, v81
	v_add_f32_e32 v82, 1.0, v82
	v_add_f32_e32 v83, 1.0, v83
	v_add_f32_e32 v84, 1.0, v84
	v_add_f32_e32 v85, 1.0, v85
	v_mul_f32_e32 v72, 0xbfb8aa3b, v72
	v_mul_f32_e32 v73, 0xbfb8aa3b, v73
	v_mul_f32_e32 v74, 0xbfb8aa3b, v74
	v_mul_f32_e32 v75, 0xbfb8aa3b, v75
	v_mul_f32_e32 v76, 0xbfb8aa3b, v76
	v_mul_f32_e32 v77, 0xbfb8aa3b, v77
	v_lshl_add_u64 v[92:93], v[92:93], 0, v[122:123]
	v_rcp_f32_e32 v80, v80
	v_rcp_f32_e32 v81, v81
	v_rcp_f32_e32 v82, v82
	v_rcp_f32_e32 v83, v83
	v_rcp_f32_e32 v84, v84
	v_rcp_f32_e32 v85, v85
	v_exp_f32_e32 v72, v72
	v_exp_f32_e32 v73, v73
	v_exp_f32_e32 v74, v74
	v_exp_f32_e32 v75, v75
	v_exp_f32_e32 v76, v76
	v_exp_f32_e32 v77, v77
	v_add_co_u32_e32 v92, vcc, s38, v92
	v_cvt_pk_bf16_f32 v91, v94, v95
	s_nop 0
	v_addc_co_u32_e32 v93, vcc, 0, v93, vcc
	v_add_f32_e32 v86, 1.0, v86
	v_add_f32_e32 v87, 1.0, v87
	v_mul_f32_e32 v78, 0xbfb8aa3b, v78
	v_mul_f32_e32 v79, 0xbfb8aa3b, v79
	global_store_dwordx4 v[92:93], v[88:91], off nt
	v_rcp_f32_e32 v86, v86
	v_rcp_f32_e32 v87, v87
	v_add_u32_e32 v88, 0x90, v228
	v_exp_f32_e32 v78, v78
	v_exp_f32_e32 v79, v79
	v_cvt_pk_bf16_f32 v80, v80, v81
	v_cvt_pk_bf16_f32 v81, v82, v83
	v_cvt_pk_bf16_f32 v82, v84, v85
	v_mad_i64_i32 v[84:85], s[8:9], v88, s31, v[120:121]
	v_add_f32_e32 v72, 1.0, v72
	v_add_f32_e32 v73, 1.0, v73
	v_add_f32_e32 v74, 1.0, v74
	v_add_f32_e32 v75, 1.0, v75
	v_add_f32_e32 v76, 1.0, v76
	v_add_f32_e32 v77, 1.0, v77
	v_mul_f32_e32 v64, 0xbfb8aa3b, v64
	v_mul_f32_e32 v65, 0xbfb8aa3b, v65
	v_mul_f32_e32 v66, 0xbfb8aa3b, v66
	v_mul_f32_e32 v67, 0xbfb8aa3b, v67
	v_mul_f32_e32 v68, 0xbfb8aa3b, v68
	v_mul_f32_e32 v69, 0xbfb8aa3b, v69
	v_lshl_add_u64 v[84:85], v[84:85], 0, v[122:123]
	v_rcp_f32_e32 v72, v72
	v_rcp_f32_e32 v73, v73
	v_rcp_f32_e32 v74, v74
	v_rcp_f32_e32 v75, v75
	v_rcp_f32_e32 v76, v76
	v_rcp_f32_e32 v77, v77
	v_exp_f32_e32 v64, v64
	v_exp_f32_e32 v65, v65
	v_exp_f32_e32 v66, v66
	v_exp_f32_e32 v67, v67
	v_exp_f32_e32 v68, v68
	v_exp_f32_e32 v69, v69
	v_add_co_u32_e32 v84, vcc, s38, v84
	v_cvt_pk_bf16_f32 v83, v86, v87
	s_nop 0
	v_addc_co_u32_e32 v85, vcc, 0, v85, vcc
	v_add_f32_e32 v78, 1.0, v78
	v_add_f32_e32 v79, 1.0, v79
	v_mul_f32_e32 v70, 0xbfb8aa3b, v70
	v_mul_f32_e32 v71, 0xbfb8aa3b, v71
	global_store_dwordx4 v[84:85], v[80:83], off nt
	v_rcp_f32_e32 v78, v78
	v_rcp_f32_e32 v79, v79
	v_add_u32_e32 v80, 0xa0, v228
	v_exp_f32_e32 v70, v70
	v_exp_f32_e32 v71, v71
	v_cvt_pk_bf16_f32 v72, v72, v73
	v_cvt_pk_bf16_f32 v73, v74, v75
	v_cvt_pk_bf16_f32 v74, v76, v77
	v_mad_i64_i32 v[76:77], s[8:9], v80, s31, v[120:121]
	v_add_f32_e32 v64, 1.0, v64
	v_add_f32_e32 v65, 1.0, v65
	v_add_f32_e32 v66, 1.0, v66
	v_add_f32_e32 v67, 1.0, v67
	v_add_f32_e32 v68, 1.0, v68
	v_add_f32_e32 v69, 1.0, v69
	v_lshl_add_u64 v[76:77], v[76:77], 0, v[122:123]
	v_rcp_f32_e32 v64, v64
	v_rcp_f32_e32 v65, v65
	v_rcp_f32_e32 v66, v66
	v_rcp_f32_e32 v67, v67
	v_rcp_f32_e32 v68, v68
	v_rcp_f32_e32 v69, v69
	v_add_co_u32_e32 v76, vcc, s38, v76
	v_cvt_pk_bf16_f32 v75, v78, v79
	s_nop 0
	v_addc_co_u32_e32 v77, vcc, 0, v77, vcc
	v_add_f32_e32 v70, 1.0, v70
	v_add_f32_e32 v71, 1.0, v71
	global_store_dwordx4 v[76:77], v[72:75], off nt
	v_rcp_f32_e32 v70, v70
	v_rcp_f32_e32 v71, v71
	v_add_u32_e32 v72, 0xb0, v228
	v_cvt_pk_bf16_f32 v64, v64, v65
	v_cvt_pk_bf16_f32 v65, v66, v67
	v_cvt_pk_bf16_f32 v66, v68, v69
	v_mad_i64_i32 v[68:69], s[8:9], v72, s31, v[120:121]
	v_lshl_add_u64 v[68:69], v[68:69], 0, v[122:123]
	v_add_co_u32_e32 v68, vcc, 0xc9fd000, v68
	v_cvt_pk_bf16_f32 v67, v70, v71
	s_nop 0
	v_addc_co_u32_e32 v69, vcc, 0, v69, vcc
	global_store_dwordx4 v[68:69], v[64:67], off nt

.LBB0_292:
	s_and_b64 s[42:43], s[26:27], s[8:9]
	v_cndmask_b32_e64 v64, 0, 1, s[42:43]
	v_cmp_ne_u32_e64 s[8:9], 1, v64
	s_andn2_b64 vcc, exec, s[42:43]
	v_ashrrev_i32_e32 v229, 31, v228
	s_cbranch_vccnz .LBB0_294
	v_lshlrev_b64 v[64:65], 6, v[228:229]
	v_lshl_add_u64 v[64:65], s[20:21], 0, v[64:65]
	s_waitcnt lgkmcnt(0)
	flat_load_dwordx4 v[194:197], v[64:65]
	flat_load_dwordx4 v[186:189], v[64:65] offset:16
	flat_load_dwordx4 v[198:201], v[64:65] offset:32
	flat_load_dwordx4 v[190:193], v[64:65] offset:48
	v_or_b32_e32 v64, 16, v228
	v_ashrrev_i32_e32 v65, 31, v64
	v_lshlrev_b64 v[64:65], 6, v[64:65]
	v_lshl_add_u64 v[64:65], s[20:21], 0, v[64:65]
	flat_load_dwordx4 v[178:181], v[64:65]
	flat_load_dwordx4 v[170:173], v[64:65] offset:16
	flat_load_dwordx4 v[182:185], v[64:65] offset:32
	flat_load_dwordx4 v[174:177], v[64:65] offset:48
	v_or_b32_e32 v64, 32, v228
	v_ashrrev_i32_e32 v65, 31, v64
	v_lshlrev_b64 v[64:65], 6, v[64:65]
	v_lshl_add_u64 v[64:65], s[20:21], 0, v[64:65]
	flat_load_dwordx4 v[166:169], v[64:65]
	flat_load_dwordx4 v[154:157], v[64:65] offset:16
	flat_load_dwordx4 v[162:165], v[64:65] offset:32
	flat_load_dwordx4 v[158:161], v[64:65] offset:48
	v_or_b32_e32 v64, 48, v228
	v_ashrrev_i32_e32 v65, 31, v64
	v_lshlrev_b64 v[64:65], 6, v[64:65]
	v_lshl_add_u64 v[64:65], s[20:21], 0, v[64:65]
	flat_load_dwordx4 v[146:149], v[64:65]
	flat_load_dwordx4 v[138:141], v[64:65] offset:16
	flat_load_dwordx4 v[150:153], v[64:65] offset:32
	flat_load_dwordx4 v[142:145], v[64:65] offset:48

.LBB0_296:
	s_add_u32 s40, s18, s40
	s_addc_u32 s41, s19, s41
	s_ashr_i32 s29, s29, 12
	s_mul_i32 s29, s39, s29
	v_lshl_add_u64 v[72:73], v[232:233], 1, s[40:41]
	s_add_i32 s40, s29, s31
	s_ashr_i32 s41, s40, 31
	s_lshl_b64 s[40:41], s[40:41], 19
	v_cvt_pk_bf16_f32 v64, v64, v65
	v_cvt_pk_bf16_f32 v65, v66, v67
	v_cvt_pk_bf16_f32 v66, v68, v69
	v_lshlrev_b32_e32 v68, 7, v228
	v_lshl_add_u64 v[74:75], v[72:73], 0, s[40:41]
	v_and_b32_e32 v136, 0x7e780, v68
	v_cvt_pk_bf16_f32 v67, v70, v71
	v_lshl_add_u64 v[74:75], v[74:75], 0, v[136:137]
	global_store_dwordx4 v[74:75], v[64:67], off nt
	v_mov_b64_e32 v[70:71], v[54:55]
	s_and_b64 vcc, exec, s[8:9]
	v_mov_b64_e32 v[68:69], v[52:53]
	v_mov_b64_e32 v[66:67], v[50:51]
	v_mov_b64_e32 v[64:65], v[48:49]
	s_cbranch_vccnz .LBB0_298
	ds_bpermute_b32 v64, v202, v48
	ds_bpermute_b32 v65, v202, v49
	ds_bpermute_b32 v66, v202, v50
	ds_bpermute_b32 v67, v202, v51
	ds_bpermute_b32 v68, v202, v52
	ds_bpermute_b32 v69, v202, v53
	ds_bpermute_b32 v70, v202, v54
	ds_bpermute_b32 v71, v202, v55
	s_waitcnt lgkmcnt(0)
	v_mul_f32_e32 v64, v182, v64
	v_mul_f32_e32 v65, v183, v65
	v_mul_f32_e32 v66, v184, v66
	v_mul_f32_e32 v67, v185, v67
	v_mul_f32_e32 v68, v174, v68
	v_mul_f32_e32 v69, v175, v69
	v_mul_f32_e32 v70, v176, v70
	v_mul_f32_e32 v71, v177, v71
	v_cndmask_b32_e64 v64, v64, -v64, s[6:7]
	v_cndmask_b32_e64 v65, v65, -v65, s[6:7]
	v_cndmask_b32_e64 v66, v66, -v66, s[6:7]
	v_cndmask_b32_e64 v67, v67, -v67, s[6:7]
	v_cndmask_b32_e64 v68, v68, -v68, s[6:7]
	v_cndmask_b32_e64 v69, v69, -v69, s[6:7]
	v_cndmask_b32_e64 v70, v70, -v70, s[6:7]
	v_cndmask_b32_e64 v71, v71, -v71, s[6:7]
	v_fmac_f32_e32 v64, v48, v178
	v_fmac_f32_e32 v65, v179, v49
	v_fmac_f32_e32 v66, v180, v50
	v_fmac_f32_e32 v67, v181, v51
	v_fmac_f32_e32 v68, v170, v52
	v_fmac_f32_e32 v69, v171, v53
	v_fmac_f32_e32 v70, v172, v54
	v_fmac_f32_e32 v71, v173, v55
	v_cndmask_b32_e64 v64, v48, v64, s[4:5]
	v_cndmask_b32_e64 v71, v55, v71, s[4:5]
	v_cndmask_b32_e64 v70, v54, v70, s[4:5]
	v_cndmask_b32_e64 v69, v53, v69, s[4:5]
	v_cndmask_b32_e64 v68, v52, v68, s[4:5]
	v_cndmask_b32_e64 v67, v51, v67, s[4:5]
	v_cndmask_b32_e64 v66, v50, v66, s[4:5]
	v_cndmask_b32_e64 v65, v49, v65, s[4:5]
.LBB0_298:
	v_cvt_pk_bf16_f32 v64, v64, v65
	v_cvt_pk_bf16_f32 v65, v66, v67
	v_cvt_pk_bf16_f32 v66, v68, v69
	v_cvt_pk_bf16_f32 v67, v70, v71
	global_store_dwordx4 v[74:75], v[64:67], off offset:2048 nt
	v_mov_b64_e32 v[70:71], v[46:47]
	s_and_b64 vcc, exec, s[8:9]
	v_mov_b64_e32 v[68:69], v[44:45]
	v_mov_b64_e32 v[66:67], v[42:43]
	v_mov_b64_e32 v[64:65], v[40:41]
	s_cbranch_vccnz .LBB0_300
	ds_bpermute_b32 v64, v202, v40
	ds_bpermute_b32 v65, v202, v41
	ds_bpermute_b32 v66, v202, v42
	ds_bpermute_b32 v67, v202, v43
	ds_bpermute_b32 v68, v202, v44
	ds_bpermute_b32 v69, v202, v45
	ds_bpermute_b32 v70, v202, v46
	ds_bpermute_b32 v71, v202, v47
	s_waitcnt lgkmcnt(0)
	v_mul_f32_e32 v64, v162, v64
	v_mul_f32_e32 v65, v163, v65
	v_mul_f32_e32 v66, v164, v66
	v_mul_f32_e32 v67, v165, v67
	v_mul_f32_e32 v68, v158, v68
	v_mul_f32_e32 v69, v159, v69
	v_mul_f32_e32 v70, v160, v70
	v_mul_f32_e32 v71, v161, v71
	v_cndmask_b32_e64 v64, v64, -v64, s[6:7]
	v_cndmask_b32_e64 v65, v65, -v65, s[6:7]
	v_cndmask_b32_e64 v66, v66, -v66, s[6:7]
	v_cndmask_b32_e64 v67, v67, -v67, s[6:7]
	v_cndmask_b32_e64 v68, v68, -v68, s[6:7]
	v_cndmask_b32_e64 v69, v69, -v69, s[6:7]
	v_cndmask_b32_e64 v70, v70, -v70, s[6:7]
	v_cndmask_b32_e64 v71, v71, -v71, s[6:7]
	v_fmac_f32_e32 v64, v40, v166
	v_fmac_f32_e32 v65, v167, v41
	v_fmac_f32_e32 v66, v168, v42
	v_fmac_f32_e32 v67, v169, v43
	v_fmac_f32_e32 v68, v154, v44
	v_fmac_f32_e32 v69, v155, v45
	v_fmac_f32_e32 v70, v156, v46
	v_fmac_f32_e32 v71, v157, v47
	v_cndmask_b32_e64 v64, v40, v64, s[4:5]
	v_cndmask_b32_e64 v71, v47, v71, s[4:5]
	v_cndmask_b32_e64 v70, v46, v70, s[4:5]
	v_cndmask_b32_e64 v69, v45, v69, s[4:5]
	v_cndmask_b32_e64 v68, v44, v68, s[4:5]
	v_cndmask_b32_e64 v67, v43, v67, s[4:5]
	v_cndmask_b32_e64 v66, v42, v66, s[4:5]
	v_cndmask_b32_e64 v65, v41, v65, s[4:5]
.LBB0_300:
	v_cvt_pk_bf16_f32 v64, v64, v65
	v_cvt_pk_bf16_f32 v65, v66, v67
	v_cvt_pk_bf16_f32 v66, v68, v69
	v_add_co_u32_e32 v68, vcc, 0x1000, v74
	v_cvt_pk_bf16_f32 v67, v70, v71
	s_nop 0
	v_addc_co_u32_e32 v69, vcc, 0, v75, vcc
	global_store_dwordx4 v[68:69], v[64:67], off nt
	v_mov_b64_e32 v[70:71], v[38:39]
	s_and_b64 vcc, exec, s[8:9]
	v_mov_b64_e32 v[68:69], v[36:37]
	v_mov_b64_e32 v[66:67], v[34:35]
	v_mov_b64_e32 v[64:65], v[32:33]
	s_cbranch_vccnz .LBB0_302
	ds_bpermute_b32 v64, v202, v32
	ds_bpermute_b32 v65, v202, v33
	ds_bpermute_b32 v66, v202, v34
	ds_bpermute_b32 v67, v202, v35
	ds_bpermute_b32 v68, v202, v36
	ds_bpermute_b32 v69, v202, v37
	ds_bpermute_b32 v70, v202, v38
	ds_bpermute_b32 v71, v202, v39
	s_waitcnt lgkmcnt(0)
	v_mul_f32_e32 v64, v150, v64
	v_mul_f32_e32 v65, v151, v65
	v_mul_f32_e32 v66, v152, v66
	v_mul_f32_e32 v67, v153, v67
	v_mul_f32_e32 v68, v142, v68
	v_mul_f32_e32 v69, v143, v69
	v_mul_f32_e32 v70, v144, v70
	v_mul_f32_e32 v71, v145, v71
	v_cndmask_b32_e64 v64, v64, -v64, s[6:7]
	v_cndmask_b32_e64 v65, v65, -v65, s[6:7]
	v_cndmask_b32_e64 v66, v66, -v66, s[6:7]
	v_cndmask_b32_e64 v67, v67, -v67, s[6:7]
	v_cndmask_b32_e64 v68, v68, -v68, s[6:7]
	v_cndmask_b32_e64 v69, v69, -v69, s[6:7]
	v_cndmask_b32_e64 v70, v70, -v70, s[6:7]
	v_cndmask_b32_e64 v71, v71, -v71, s[6:7]
	v_fmac_f32_e32 v64, v32, v146
	v_fmac_f32_e32 v65, v147, v33
	v_fmac_f32_e32 v66, v148, v34
	v_fmac_f32_e32 v67, v149, v35
	v_fmac_f32_e32 v68, v138, v36
	v_fmac_f32_e32 v69, v139, v37
	v_fmac_f32_e32 v70, v140, v38
	v_fmac_f32_e32 v71, v141, v39
	v_cndmask_b32_e64 v64, v32, v64, s[4:5]
	v_cndmask_b32_e64 v71, v39, v71, s[4:5]
	v_cndmask_b32_e64 v70, v38, v70, s[4:5]
	v_cndmask_b32_e64 v69, v37, v69, s[4:5]
	v_cndmask_b32_e64 v68, v36, v68, s[4:5]
	v_cndmask_b32_e64 v67, v35, v67, s[4:5]
	v_cndmask_b32_e64 v66, v34, v66, s[4:5]
	v_cndmask_b32_e64 v65, v33, v65, s[4:5]
.LBB0_302:
	v_cvt_pk_bf16_f32 v64, v64, v65
	v_cvt_pk_bf16_f32 v65, v66, v67
	v_cvt_pk_bf16_f32 v66, v68, v69
	v_add_co_u32_e32 v68, vcc, 0x1000, v74
	v_cvt_pk_bf16_f32 v67, v70, v71
	s_nop 0
	v_addc_co_u32_e32 v69, vcc, 0, v75, vcc
	s_and_b64 vcc, exec, s[8:9]
	v_add_u32_e32 v74, 0x80, v228
	global_store_dwordx4 v[68:69], v[64:67], off offset:2048 nt
	s_cbranch_vccnz .LBB0_304
	v_ashrrev_i32_e32 v75, 31, v74
	v_lshlrev_b64 v[64:65], 6, v[74:75]
	v_lshl_add_u64 v[64:65], s[20:21], 0, v[64:65]
	s_waitcnt lgkmcnt(0)
	flat_load_dwordx4 v[194:197], v[64:65]
	flat_load_dwordx4 v[186:189], v[64:65] offset:16
	flat_load_dwordx4 v[198:201], v[64:65] offset:32
	flat_load_dwordx4 v[190:193], v[64:65] offset:48
	v_lshlrev_b64 v[64:65], 6, v[228:229]
	v_lshl_add_u64 v[64:65], s[20:21], 0, v[64:65]
	s_mov_b64 s[40:41], 0x2400
	v_lshl_add_u64 v[66:67], v[64:65], 0, s[40:41]
	v_add_co_u32_e32 v68, vcc, 0x2000, v64
	s_mov_b64 s[40:41], 0x2800
	s_nop 0
	v_addc_co_u32_e32 v69, vcc, 0, v65, vcc
	flat_load_dwordx4 v[170:173], v[66:67] offset:16
	flat_load_dwordx4 v[182:185], v[66:67] offset:32
	flat_load_dwordx4 v[178:181], v[68:69] offset:1024
	flat_load_dwordx4 v[174:177], v[66:67] offset:48
	v_lshl_add_u64 v[66:67], v[64:65], 0, s[40:41]
	s_mov_b64 s[40:41], 0x2c00
	flat_load_dwordx4 v[154:157], v[66:67] offset:16
	flat_load_dwordx4 v[162:165], v[66:67] offset:32
	v_lshl_add_u64 v[64:65], v[64:65], 0, s[40:41]
	flat_load_dwordx4 v[166:169], v[68:69] offset:2048
	flat_load_dwordx4 v[146:149], v[68:69] offset:3072
	flat_load_dwordx4 v[158:161], v[66:67] offset:48
	flat_load_dwordx4 v[138:141], v[64:65] offset:16
	flat_load_dwordx4 v[150:153], v[64:65] offset:32
	flat_load_dwordx4 v[142:145], v[64:65] offset:48

.LBB0_306:
	v_ashrrev_i32_e32 v75, 12, v74
	v_mov_b32_e32 v76, s31
	v_mad_i32_i24 v76, s39, v75, v76
	v_ashrrev_i32_e32 v77, 31, v76
	v_lshlrev_b64 v[76:77], 19, v[76:77]
	v_cvt_pk_bf16_f32 v64, v64, v65
	v_cvt_pk_bf16_f32 v65, v66, v67
	v_cvt_pk_bf16_f32 v66, v68, v69
	v_lshlrev_b32_e32 v68, 7, v74
	v_lshl_add_u64 v[72:73], v[72:73], 0, v[76:77]
	v_and_b32_e32 v136, 0x7e780, v68
	v_cvt_pk_bf16_f32 v67, v70, v71
	v_lshl_add_u64 v[72:73], v[72:73], 0, v[136:137]
	global_store_dwordx4 v[72:73], v[64:67], off nt
	v_mov_b64_e32 v[70:71], v[22:23]
	s_and_b64 vcc, exec, s[8:9]
	v_mov_b64_e32 v[68:69], v[20:21]
	v_mov_b64_e32 v[66:67], v[18:19]
	v_mov_b64_e32 v[64:65], v[16:17]
	s_cbranch_vccnz .LBB0_308
	ds_bpermute_b32 v64, v202, v16
	ds_bpermute_b32 v65, v202, v17
	ds_bpermute_b32 v66, v202, v18
	ds_bpermute_b32 v67, v202, v19
	ds_bpermute_b32 v68, v202, v20
	ds_bpermute_b32 v69, v202, v21
	ds_bpermute_b32 v70, v202, v22
	ds_bpermute_b32 v71, v202, v23
	s_waitcnt lgkmcnt(0)
	v_mul_f32_e32 v64, v182, v64
	v_mul_f32_e32 v65, v183, v65
	v_mul_f32_e32 v66, v184, v66
	v_mul_f32_e32 v67, v185, v67
	v_mul_f32_e32 v68, v174, v68
	v_mul_f32_e32 v69, v175, v69
	v_mul_f32_e32 v70, v176, v70
	v_mul_f32_e32 v71, v177, v71
	v_cndmask_b32_e64 v64, v64, -v64, s[6:7]
	v_cndmask_b32_e64 v65, v65, -v65, s[6:7]
	v_cndmask_b32_e64 v66, v66, -v66, s[6:7]
	v_cndmask_b32_e64 v67, v67, -v67, s[6:7]
	v_cndmask_b32_e64 v68, v68, -v68, s[6:7]
	v_cndmask_b32_e64 v69, v69, -v69, s[6:7]
	v_cndmask_b32_e64 v70, v70, -v70, s[6:7]
	v_cndmask_b32_e64 v71, v71, -v71, s[6:7]
	v_fmac_f32_e32 v64, v16, v178
	v_fmac_f32_e32 v65, v179, v17
	v_fmac_f32_e32 v66, v180, v18
	v_fmac_f32_e32 v67, v181, v19
	v_fmac_f32_e32 v68, v170, v20
	v_fmac_f32_e32 v69, v171, v21
	v_fmac_f32_e32 v70, v172, v22
	v_fmac_f32_e32 v71, v173, v23
	v_cndmask_b32_e64 v64, v16, v64, s[4:5]
	v_cndmask_b32_e64 v71, v23, v71, s[4:5]
	v_cndmask_b32_e64 v70, v22, v70, s[4:5]
	v_cndmask_b32_e64 v69, v21, v69, s[4:5]
	v_cndmask_b32_e64 v68, v20, v68, s[4:5]
	v_cndmask_b32_e64 v67, v19, v67, s[4:5]
	v_cndmask_b32_e64 v66, v18, v66, s[4:5]
	v_cndmask_b32_e64 v65, v17, v65, s[4:5]
.LBB0_308:
	v_cvt_pk_bf16_f32 v64, v64, v65
	v_cvt_pk_bf16_f32 v65, v66, v67
	v_cvt_pk_bf16_f32 v66, v68, v69
	v_cvt_pk_bf16_f32 v67, v70, v71
	global_store_dwordx4 v[72:73], v[64:67], off offset:2048 nt
	v_mov_b64_e32 v[70:71], v[14:15]
	s_and_b64 vcc, exec, s[8:9]
	v_mov_b64_e32 v[68:69], v[12:13]
	v_mov_b64_e32 v[66:67], v[10:11]
	v_mov_b64_e32 v[64:65], v[8:9]
	s_cbranch_vccnz .LBB0_310
	ds_bpermute_b32 v64, v202, v8
	ds_bpermute_b32 v65, v202, v9
	ds_bpermute_b32 v66, v202, v10
	ds_bpermute_b32 v67, v202, v11
	ds_bpermute_b32 v68, v202, v12
	ds_bpermute_b32 v69, v202, v13
	ds_bpermute_b32 v70, v202, v14
	ds_bpermute_b32 v71, v202, v15
	s_waitcnt lgkmcnt(0)
	v_mul_f32_e32 v64, v162, v64
	v_mul_f32_e32 v65, v163, v65
	v_mul_f32_e32 v66, v164, v66
	v_mul_f32_e32 v67, v165, v67
	v_mul_f32_e32 v68, v158, v68
	v_mul_f32_e32 v69, v159, v69
	v_mul_f32_e32 v70, v160, v70
	v_mul_f32_e32 v71, v161, v71
	v_cndmask_b32_e64 v64, v64, -v64, s[6:7]
	v_cndmask_b32_e64 v65, v65, -v65, s[6:7]
	v_cndmask_b32_e64 v66, v66, -v66, s[6:7]
	v_cndmask_b32_e64 v67, v67, -v67, s[6:7]
	v_cndmask_b32_e64 v68, v68, -v68, s[6:7]
	v_cndmask_b32_e64 v69, v69, -v69, s[6:7]
	v_cndmask_b32_e64 v70, v70, -v70, s[6:7]
	v_cndmask_b32_e64 v71, v71, -v71, s[6:7]
	v_fmac_f32_e32 v64, v8, v166
	v_fmac_f32_e32 v65, v167, v9
	v_fmac_f32_e32 v66, v168, v10
	v_fmac_f32_e32 v67, v169, v11
	v_fmac_f32_e32 v68, v154, v12
	v_fmac_f32_e32 v69, v155, v13
	v_fmac_f32_e32 v70, v156, v14
	v_fmac_f32_e32 v71, v157, v15
	v_cndmask_b32_e64 v64, v8, v64, s[4:5]
	v_cndmask_b32_e64 v71, v15, v71, s[4:5]
	v_cndmask_b32_e64 v70, v14, v70, s[4:5]
	v_cndmask_b32_e64 v69, v13, v69, s[4:5]
	v_cndmask_b32_e64 v68, v12, v68, s[4:5]
	v_cndmask_b32_e64 v67, v11, v67, s[4:5]
	v_cndmask_b32_e64 v66, v10, v66, s[4:5]
	v_cndmask_b32_e64 v65, v9, v65, s[4:5]
.LBB0_310:
	v_cvt_pk_bf16_f32 v64, v64, v65
	v_cvt_pk_bf16_f32 v65, v66, v67
	v_cvt_pk_bf16_f32 v66, v68, v69
	v_add_co_u32_e32 v68, vcc, 0x1000, v72
	v_cvt_pk_bf16_f32 v67, v70, v71
	s_nop 0
	v_addc_co_u32_e32 v69, vcc, 0, v73, vcc
	global_store_dwordx4 v[68:69], v[64:67], off nt
	v_mov_b64_e32 v[70:71], v[6:7]
	s_and_b64 vcc, exec, s[8:9]
	v_mov_b64_e32 v[68:69], v[4:5]
	v_mov_b64_e32 v[66:67], v[2:3]
	v_mov_b64_e32 v[64:65], v[0:1]
	s_cbranch_vccnz .LBB0_312
	ds_bpermute_b32 v64, v202, v0
	ds_bpermute_b32 v65, v202, v1
	ds_bpermute_b32 v66, v202, v2
	ds_bpermute_b32 v67, v202, v3
	ds_bpermute_b32 v68, v202, v4
	ds_bpermute_b32 v69, v202, v5
	ds_bpermute_b32 v70, v202, v6
	ds_bpermute_b32 v71, v202, v7
	s_waitcnt lgkmcnt(0)
	v_mul_f32_e32 v64, v150, v64
	v_mul_f32_e32 v65, v151, v65
	v_mul_f32_e32 v66, v152, v66
	v_mul_f32_e32 v67, v153, v67
	v_mul_f32_e32 v68, v142, v68
	v_mul_f32_e32 v69, v143, v69
	v_mul_f32_e32 v70, v144, v70
	v_mul_f32_e32 v71, v145, v71
	v_cndmask_b32_e64 v64, v64, -v64, s[6:7]
	v_cndmask_b32_e64 v65, v65, -v65, s[6:7]
	v_cndmask_b32_e64 v66, v66, -v66, s[6:7]
	v_cndmask_b32_e64 v67, v67, -v67, s[6:7]
	v_cndmask_b32_e64 v68, v68, -v68, s[6:7]
	v_cndmask_b32_e64 v69, v69, -v69, s[6:7]
	v_cndmask_b32_e64 v70, v70, -v70, s[6:7]
	v_cndmask_b32_e64 v71, v71, -v71, s[6:7]
	v_fmac_f32_e32 v64, v0, v146
	v_fmac_f32_e32 v65, v147, v1
	v_fmac_f32_e32 v66, v148, v2
	v_fmac_f32_e32 v67, v149, v3
	v_fmac_f32_e32 v68, v138, v4
	v_fmac_f32_e32 v69, v139, v5
	v_fmac_f32_e32 v70, v140, v6
	v_fmac_f32_e32 v71, v141, v7
	v_cndmask_b32_e64 v64, v0, v64, s[4:5]
	v_cndmask_b32_e64 v71, v7, v71, s[4:5]
	v_cndmask_b32_e64 v70, v6, v70, s[4:5]
	v_cndmask_b32_e64 v69, v5, v69, s[4:5]
	v_cndmask_b32_e64 v68, v4, v68, s[4:5]
	v_cndmask_b32_e64 v67, v3, v67, s[4:5]
	v_cndmask_b32_e64 v66, v2, v66, s[4:5]
	v_cndmask_b32_e64 v65, v1, v65, s[4:5]
.LBB0_312:
	v_cvt_pk_bf16_f32 v64, v64, v65
	v_cvt_pk_bf16_f32 v65, v66, v67
	v_cvt_pk_bf16_f32 v66, v68, v69
	v_add_co_u32_e32 v68, vcc, 0x1000, v72
	v_cvt_pk_bf16_f32 v67, v70, v71
	s_nop 0
	v_addc_co_u32_e32 v69, vcc, 0, v73, vcc
	s_mov_b64 s[8:9], 0
	global_store_dwordx4 v[68:69], v[64:67], off offset:2048 nt

.LBB0_318:
	s_andn2_b64 vcc, exec, s[8:9]
	s_cbranch_vccnz .LBB0_320
	v_mul_f32_e32 v60, 0xbfb8aa3b, v60
	v_exp_f32_e32 v60, v60
	v_mul_f32_e32 v61, 0xbfb8aa3b, v61
	v_exp_f32_e32 v61, v61
	v_mul_f32_e32 v56, 0xbfb8aa3b, v56
	v_mul_f32_e32 v57, 0xbfb8aa3b, v57
	v_exp_f32_e32 v56, v56
	v_exp_f32_e32 v57, v57
	v_mul_f32_e32 v58, 0xbfb8aa3b, v58
	v_mul_f32_e32 v59, 0xbfb8aa3b, v59
	v_add_f32_e32 v60, 1.0, v60
	v_exp_f32_e32 v58, v58
	v_exp_f32_e32 v59, v59
	v_rcp_f32_e32 v64, v60
	v_add_f32_e32 v60, 1.0, v61
	v_mul_f32_e32 v61, 0xbfb8aa3b, v62
	v_exp_f32_e32 v61, v61
	v_mul_f32_e32 v62, 0xbfb8aa3b, v63
	v_exp_f32_e32 v62, v62
	v_add_f32_e32 v56, 1.0, v56
	v_add_f32_e32 v57, 1.0, v57
	v_rcp_f32_e32 v56, v56
	v_rcp_f32_e32 v57, v57
	v_add_f32_e32 v58, 1.0, v58
	v_add_f32_e32 v59, 1.0, v59
	v_rcp_f32_e32 v58, v58
	v_rcp_f32_e32 v59, v59
	v_rcp_f32_e32 v63, v60
	v_add_f32_e32 v60, 1.0, v61
	v_rcp_f32_e32 v65, v60
	v_add_f32_e32 v60, 1.0, v62
	v_mul_f32_e32 v48, 0xbfb8aa3b, v48
	v_mul_f32_e32 v49, 0xbfb8aa3b, v49
	v_mul_f32_e32 v50, 0xbfb8aa3b, v50
	v_mul_f32_e32 v51, 0xbfb8aa3b, v51
	v_mul_f32_e32 v52, 0xbfb8aa3b, v52
	v_mul_f32_e32 v53, 0xbfb8aa3b, v53
	v_rcp_f32_e32 v66, v60
	v_exp_f32_e32 v48, v48
	v_exp_f32_e32 v49, v49
	v_exp_f32_e32 v50, v50
	v_exp_f32_e32 v51, v51
	v_exp_f32_e32 v52, v52
	v_exp_f32_e32 v53, v53
	v_cvt_pk_bf16_f32 v60, v56, v57
	v_mov_b64_e32 v[56:57], s[18:19]
	s_movk_i32 s8, 0x1800
	s_mov_b32 s39, s93
	v_cvt_pk_bf16_f32 v61, v58, v59
	v_mad_i64_i32 v[58:59], s[4:5], v228, s8, v[56:57]
	s_lshl_b64 s[4:5], s[38:39], 1
	v_mul_f32_e32 v54, 0xbfb8aa3b, v54
	v_mul_f32_e32 v55, 0xbfb8aa3b, v55
	v_cvt_pk_bf16_f32 v62, v64, v63
	v_cvt_pk_bf16_f32 v63, v65, v66
	v_lshl_add_u64 v[64:65], v[58:59], 0, s[4:5]
	v_lshlrev_b64 v[58:59], 1, v[230:231]
	v_add_f32_e32 v48, 1.0, v48
	v_add_f32_e32 v49, 1.0, v49
	v_add_f32_e32 v50, 1.0, v50
	v_add_f32_e32 v51, 1.0, v51
	v_add_f32_e32 v52, 1.0, v52
	v_add_f32_e32 v53, 1.0, v53
	v_exp_f32_e32 v54, v54
	v_exp_f32_e32 v55, v55
	v_lshl_add_u64 v[64:65], v[64:65], 0, v[58:59]
	s_mov_b32 s9, 0xc9fd000
	v_rcp_f32_e32 v48, v48
	v_rcp_f32_e32 v49, v49
	v_rcp_f32_e32 v50, v50
	v_rcp_f32_e32 v51, v51
	v_rcp_f32_e32 v52, v52
	v_rcp_f32_e32 v53, v53
	v_mul_f32_e32 v40, 0xbfb8aa3b, v40
	v_mul_f32_e32 v41, 0xbfb8aa3b, v41
	v_mul_f32_e32 v42, 0xbfb8aa3b, v42
	v_mul_f32_e32 v43, 0xbfb8aa3b, v43
	v_mul_f32_e32 v44, 0xbfb8aa3b, v44
	v_mul_f32_e32 v45, 0xbfb8aa3b, v45
	v_add_co_u32_e32 v64, vcc, s9, v64
	v_exp_f32_e32 v40, v40
	v_exp_f32_e32 v41, v41
	v_exp_f32_e32 v42, v42
	v_exp_f32_e32 v43, v43
	v_exp_f32_e32 v44, v44
	v_exp_f32_e32 v45, v45
	v_addc_co_u32_e32 v65, vcc, 0, v65, vcc
	global_store_dwordx4 v[64:65], v[60:63], off nt
	v_add_f32_e32 v54, 1.0, v54
	v_add_f32_e32 v55, 1.0, v55
	v_or_b32_e32 v60, 16, v228
	v_rcp_f32_e32 v54, v54
	v_rcp_f32_e32 v55, v55
	v_cvt_pk_bf16_f32 v48, v48, v49
	v_cvt_pk_bf16_f32 v49, v50, v51
	v_cvt_pk_bf16_f32 v50, v52, v53
	v_mad_i64_i32 v[52:53], s[6:7], v60, s8, v[56:57]
	v_mul_f32_e32 v46, 0xbfb8aa3b, v46
	v_mul_f32_e32 v47, 0xbfb8aa3b, v47
	v_lshl_add_u64 v[52:53], v[52:53], 0, s[4:5]
	v_add_f32_e32 v40, 1.0, v40
	v_add_f32_e32 v41, 1.0, v41
	v_add_f32_e32 v42, 1.0, v42
	v_add_f32_e32 v43, 1.0, v43
	v_add_f32_e32 v44, 1.0, v44
	v_add_f32_e32 v45, 1.0, v45
	v_exp_f32_e32 v46, v46
	v_exp_f32_e32 v47, v47
	v_lshl_add_u64 v[52:53], v[52:53], 0, v[58:59]
	v_rcp_f32_e32 v40, v40
	v_rcp_f32_e32 v41, v41
	v_rcp_f32_e32 v42, v42
	v_rcp_f32_e32 v43, v43
	v_rcp_f32_e32 v44, v44
	v_rcp_f32_e32 v45, v45
	v_mul_f32_e32 v32, 0xbfb8aa3b, v32
	v_mul_f32_e32 v33, 0xbfb8aa3b, v33
	v_mul_f32_e32 v34, 0xbfb8aa3b, v34
	v_mul_f32_e32 v35, 0xbfb8aa3b, v35
	v_mul_f32_e32 v36, 0xbfb8aa3b, v36
	v_mul_f32_e32 v37, 0xbfb8aa3b, v37
	v_add_co_u32_e32 v52, vcc, s9, v52
	v_exp_f32_e32 v32, v32
	v_exp_f32_e32 v33, v33
	v_exp_f32_e32 v34, v34
	v_exp_f32_e32 v35, v35
	v_exp_f32_e32 v36, v36
	v_exp_f32_e32 v37, v37
	v_cvt_pk_bf16_f32 v51, v54, v55
	v_addc_co_u32_e32 v53, vcc, 0, v53, vcc
	global_store_dwordx4 v[52:53], v[48:51], off nt
	v_add_f32_e32 v46, 1.0, v46
	v_add_f32_e32 v47, 1.0, v47
	v_or_b32_e32 v48, 32, v228
	v_rcp_f32_e32 v46, v46
	v_rcp_f32_e32 v47, v47
	v_cvt_pk_bf16_f32 v40, v40, v41
	v_cvt_pk_bf16_f32 v41, v42, v43
	v_cvt_pk_bf16_f32 v42, v44, v45
	v_mad_i64_i32 v[44:45], s[6:7], v48, s8, v[56:57]
	v_mul_f32_e32 v38, 0xbfb8aa3b, v38
	v_mul_f32_e32 v39, 0xbfb8aa3b, v39
	v_lshl_add_u64 v[44:45], v[44:45], 0, s[4:5]
	v_add_f32_e32 v32, 1.0, v32
	v_add_f32_e32 v33, 1.0, v33
	v_add_f32_e32 v34, 1.0, v34
	v_add_f32_e32 v35, 1.0, v35
	v_add_f32_e32 v36, 1.0, v36
	v_add_f32_e32 v37, 1.0, v37
	v_exp_f32_e32 v38, v38
	v_exp_f32_e32 v39, v39
	v_lshl_add_u64 v[44:45], v[44:45], 0, v[58:59]
	v_rcp_f32_e32 v32, v32
	v_rcp_f32_e32 v33, v33
	v_rcp_f32_e32 v34, v34
	v_rcp_f32_e32 v35, v35
	v_rcp_f32_e32 v36, v36
	v_rcp_f32_e32 v37, v37
	v_mul_f32_e32 v24, 0xbfb8aa3b, v24
	v_mul_f32_e32 v25, 0xbfb8aa3b, v25
	v_mul_f32_e32 v26, 0xbfb8aa3b, v26
	v_mul_f32_e32 v27, 0xbfb8aa3b, v27
	v_mul_f32_e32 v28, 0xbfb8aa3b, v28
	v_mul_f32_e32 v29, 0xbfb8aa3b, v29
	v_add_co_u32_e32 v44, vcc, s9, v44
	v_exp_f32_e32 v24, v24
	v_exp_f32_e32 v25, v25
	v_exp_f32_e32 v26, v26
	v_exp_f32_e32 v27, v27
	v_exp_f32_e32 v28, v28
	v_exp_f32_e32 v29, v29
	v_cvt_pk_bf16_f32 v43, v46, v47
	v_addc_co_u32_e32 v45, vcc, 0, v45, vcc
	global_store_dwordx4 v[44:45], v[40:43], off nt
	v_add_f32_e32 v38, 1.0, v38
	v_add_f32_e32 v39, 1.0, v39
	v_or_b32_e32 v40, 48, v228
	v_rcp_f32_e32 v38, v38
	v_rcp_f32_e32 v39, v39
	v_cvt_pk_bf16_f32 v32, v32, v33
	v_cvt_pk_bf16_f32 v33, v34, v35
	v_cvt_pk_bf16_f32 v34, v36, v37
	v_mad_i64_i32 v[36:37], s[6:7], v40, s8, v[56:57]
	v_mul_f32_e32 v30, 0xbfb8aa3b, v30
	v_mul_f32_e32 v31, 0xbfb8aa3b, v31
	v_lshl_add_u64 v[36:37], v[36:37], 0, s[4:5]
	v_add_f32_e32 v24, 1.0, v24
	v_add_f32_e32 v25, 1.0, v25
	v_add_f32_e32 v26, 1.0, v26
	v_add_f32_e32 v27, 1.0, v27
	v_add_f32_e32 v28, 1.0, v28
	v_add_f32_e32 v29, 1.0, v29
	v_exp_f32_e32 v30, v30
	v_exp_f32_e32 v31, v31
	v_lshl_add_u64 v[36:37], v[36:37], 0, v[58:59]
	v_rcp_f32_e32 v24, v24
	v_rcp_f32_e32 v25, v25
	v_rcp_f32_e32 v26, v26
	v_rcp_f32_e32 v27, v27
	v_rcp_f32_e32 v28, v28
	v_rcp_f32_e32 v29, v29
	v_mul_f32_e32 v16, 0xbfb8aa3b, v16
	v_mul_f32_e32 v17, 0xbfb8aa3b, v17
	v_mul_f32_e32 v18, 0xbfb8aa3b, v18
	v_mul_f32_e32 v19, 0xbfb8aa3b, v19
	v_mul_f32_e32 v20, 0xbfb8aa3b, v20
	v_mul_f32_e32 v21, 0xbfb8aa3b, v21
	v_add_co_u32_e32 v36, vcc, s9, v36
	v_exp_f32_e32 v16, v16
	v_exp_f32_e32 v17, v17
	v_exp_f32_e32 v18, v18
	v_exp_f32_e32 v19, v19
	v_exp_f32_e32 v20, v20
	v_exp_f32_e32 v21, v21
	v_cvt_pk_bf16_f32 v35, v38, v39
	v_addc_co_u32_e32 v37, vcc, 0, v37, vcc
	global_store_dwordx4 v[36:37], v[32:35], off nt
	v_add_f32_e32 v30, 1.0, v30
	v_add_f32_e32 v31, 1.0, v31
	v_add_u32_e32 v32, 0x80, v228
	v_rcp_f32_e32 v30, v30
	v_rcp_f32_e32 v31, v31
	v_cvt_pk_bf16_f32 v24, v24, v25
	v_cvt_pk_bf16_f32 v25, v26, v27
	v_cvt_pk_bf16_f32 v26, v28, v29
	v_mad_i64_i32 v[28:29], s[6:7], v32, s8, v[56:57]
	v_mul_f32_e32 v22, 0xbfb8aa3b, v22
	v_mul_f32_e32 v23, 0xbfb8aa3b, v23
	v_lshl_add_u64 v[28:29], v[28:29], 0, s[4:5]
	v_add_f32_e32 v16, 1.0, v16
	v_add_f32_e32 v17, 1.0, v17
	v_add_f32_e32 v18, 1.0, v18
	v_add_f32_e32 v19, 1.0, v19
	v_add_f32_e32 v20, 1.0, v20
	v_add_f32_e32 v21, 1.0, v21
	v_exp_f32_e32 v22, v22
	v_exp_f32_e32 v23, v23
	v_lshl_add_u64 v[28:29], v[28:29], 0, v[58:59]
	v_rcp_f32_e32 v16, v16
	v_rcp_f32_e32 v17, v17
	v_rcp_f32_e32 v18, v18
	v_rcp_f32_e32 v19, v19
	v_rcp_f32_e32 v20, v20
	v_rcp_f32_e32 v21, v21
	v_mul_f32_e32 v8, 0xbfb8aa3b, v8
	v_mul_f32_e32 v9, 0xbfb8aa3b, v9
	v_mul_f32_e32 v10, 0xbfb8aa3b, v10
	v_mul_f32_e32 v11, 0xbfb8aa3b, v11
	v_mul_f32_e32 v12, 0xbfb8aa3b, v12
	v_mul_f32_e32 v13, 0xbfb8aa3b, v13
	v_add_co_u32_e32 v28, vcc, s9, v28
	v_exp_f32_e32 v8, v8
	v_exp_f32_e32 v9, v9
	v_exp_f32_e32 v10, v10
	v_exp_f32_e32 v11, v11
	v_exp_f32_e32 v12, v12
	v_exp_f32_e32 v13, v13
	v_cvt_pk_bf16_f32 v27, v30, v31
	v_addc_co_u32_e32 v29, vcc, 0, v29, vcc
	global_store_dwordx4 v[28:29], v[24:27], off nt
	v_add_f32_e32 v22, 1.0, v22
	v_add_f32_e32 v23, 1.0, v23
	v_add_u32_e32 v24, 0x90, v228
	v_rcp_f32_e32 v22, v22
	v_rcp_f32_e32 v23, v23
	v_cvt_pk_bf16_f32 v16, v16, v17
	v_cvt_pk_bf16_f32 v17, v18, v19
	v_cvt_pk_bf16_f32 v18, v20, v21
	v_mad_i64_i32 v[20:21], s[6:7], v24, s8, v[56:57]
	v_mul_f32_e32 v14, 0xbfb8aa3b, v14
	v_mul_f32_e32 v15, 0xbfb8aa3b, v15
	v_lshl_add_u64 v[20:21], v[20:21], 0, s[4:5]
	v_add_f32_e32 v8, 1.0, v8
	v_add_f32_e32 v9, 1.0, v9
	v_add_f32_e32 v10, 1.0, v10
	v_add_f32_e32 v11, 1.0, v11
	v_add_f32_e32 v12, 1.0, v12
	v_add_f32_e32 v13, 1.0, v13
	v_exp_f32_e32 v14, v14
	v_exp_f32_e32 v15, v15
	v_lshl_add_u64 v[20:21], v[20:21], 0, v[58:59]
	v_rcp_f32_e32 v8, v8
	v_rcp_f32_e32 v9, v9
	v_rcp_f32_e32 v10, v10
	v_rcp_f32_e32 v11, v11
	v_rcp_f32_e32 v12, v12
	v_rcp_f32_e32 v13, v13
	v_mul_f32_e32 v0, 0xbfb8aa3b, v0
	v_mul_f32_e32 v1, 0xbfb8aa3b, v1
	v_mul_f32_e32 v2, 0xbfb8aa3b, v2
	v_mul_f32_e32 v3, 0xbfb8aa3b, v3
	v_mul_f32_e32 v4, 0xbfb8aa3b, v4
	v_mul_f32_e32 v5, 0xbfb8aa3b, v5
	v_add_co_u32_e32 v20, vcc, s9, v20
	v_exp_f32_e32 v0, v0
	v_exp_f32_e32 v1, v1
	v_exp_f32_e32 v2, v2
	v_exp_f32_e32 v3, v3
	v_exp_f32_e32 v4, v4
	v_exp_f32_e32 v5, v5
	v_cvt_pk_bf16_f32 v19, v22, v23
	v_addc_co_u32_e32 v21, vcc, 0, v21, vcc
	global_store_dwordx4 v[20:21], v[16:19], off nt
	v_add_f32_e32 v14, 1.0, v14
	v_add_f32_e32 v15, 1.0, v15
	v_add_u32_e32 v16, 0xa0, v228
	v_rcp_f32_e32 v14, v14
	v_rcp_f32_e32 v15, v15
	v_cvt_pk_bf16_f32 v8, v8, v9
	v_cvt_pk_bf16_f32 v9, v10, v11
	v_cvt_pk_bf16_f32 v10, v12, v13
	v_mad_i64_i32 v[12:13], s[6:7], v16, s8, v[56:57]
	v_mul_f32_e32 v6, 0xbfb8aa3b, v6
	v_mul_f32_e32 v7, 0xbfb8aa3b, v7
	v_lshl_add_u64 v[12:13], v[12:13], 0, s[4:5]
	v_add_f32_e32 v0, 1.0, v0
	v_add_f32_e32 v1, 1.0, v1
	v_add_f32_e32 v2, 1.0, v2
	v_add_f32_e32 v3, 1.0, v3
	v_add_f32_e32 v4, 1.0, v4
	v_add_f32_e32 v5, 1.0, v5
	v_exp_f32_e32 v6, v6
	v_exp_f32_e32 v7, v7
	v_lshl_add_u64 v[12:13], v[12:13], 0, v[58:59]
	v_rcp_f32_e32 v0, v0
	v_rcp_f32_e32 v1, v1
	v_rcp_f32_e32 v2, v2
	v_rcp_f32_e32 v3, v3
	v_rcp_f32_e32 v4, v4
	v_rcp_f32_e32 v5, v5
	v_add_co_u32_e32 v12, vcc, s9, v12
	v_cvt_pk_bf16_f32 v11, v14, v15
	s_nop 0
	v_addc_co_u32_e32 v13, vcc, 0, v13, vcc
	global_store_dwordx4 v[12:13], v[8:11], off nt
	v_add_f32_e32 v6, 1.0, v6
	v_add_f32_e32 v7, 1.0, v7
	v_add_u32_e32 v8, 0xb0, v228
	v_rcp_f32_e32 v6, v6
	v_rcp_f32_e32 v7, v7
	v_cvt_pk_bf16_f32 v0, v0, v1
	v_cvt_pk_bf16_f32 v1, v2, v3
	v_cvt_pk_bf16_f32 v2, v4, v5
	v_mad_i64_i32 v[4:5], s[6:7], v8, s8, v[56:57]
	v_lshl_add_u64 v[4:5], v[4:5], 0, s[4:5]
	v_lshl_add_u64 v[4:5], v[4:5], 0, v[58:59]
	v_add_co_u32_e32 v4, vcc, 0xc9fd000, v4
	v_cvt_pk_bf16_f32 v3, v6, v7
	s_nop 0
	v_addc_co_u32_e32 v5, vcc, 0, v5, vcc
	global_store_dwordx4 v[4:5], v[0:3], off nt

.LBB0_414:
	v_bfe_u32 v218, v115, 2, 2
	s_lshl_b32 s57, s69, 5
	v_and_b32_e32 v203, 3, v115
	v_or_b32_e32 v202, s68, v218
	s_sub_i32 s58, 0xfe0, s57
	v_readlane_b32 s6, v255, 24
	v_add_u32_e32 v126, s58, v202
	v_ashrrev_i32_e32 v127, 31, v126
	v_or_b32_e32 v117, s6, v203
	v_readlane_b32 s6, v255, 25
	v_readlane_b32 s7, v255, 26
	s_movk_i32 s8, 0x60
	v_mul_u32_u24_e32 v2, 3, v117
	v_lshl_add_u64 v[118:119], v[126:127], 0, s[6:7]
	v_readlane_b32 s6, v255, 27
	v_readlane_b32 s7, v255, 28
	v_lshlrev_b32_e32 v136, 2, v2
	v_ashrrev_i32_e32 v125, 4, v115
	v_mov_b64_e32 v[0:1], s[6:7]
	v_mad_u64_u32 v[0:1], s[6:7], v118, s8, v[0:1]
	v_mad_i32_i24 v1, v119, s8, v1
	v_readlane_b32 s6, v255, 50
	v_lshl_add_u64 v[6:7], v[0:1], 0, v[136:137]
	v_add_u32_e32 v10, s63, v115
	v_lshl_or_b32 v136, v117, 19, s6
	v_readlane_b32 s6, v255, 29
	v_readlane_b32 s7, v255, 30
	v_lshlrev_b64 v[2:3], 7, v[126:127]
	v_lshlrev_b32_e32 v4, 3, v125
	v_lshl_add_u64 v[0:1], s[6:7], 0, v[136:137]
	v_readlane_b32 s6, v255, 22
	v_lshl_add_u64 v[0:1], v[0:1], 0, v[2:3]
	v_ashrrev_i32_e32 v5, 31, v4
	v_lshlrev_b64 v[8:9], 6, v[118:119]
	v_readlane_b32 s7, v255, 23
	v_ashrrev_i32_e32 v120, 3, v10
	v_lshl_add_u64 v[0:1], v[4:5], 1, v[0:1]
	v_lshl_add_u64 v[8:9], s[6:7], 0, v[8:9]
	v_ashrrev_i32_e32 v121, 31, v120
	v_lshlrev_b32_e32 v10, 3, v115
	flat_load_dwordx4 v[36:39], v[0:1]
	s_nop 0
	flat_load_dwordx4 v[0:3], v[0:1] offset:64
	s_waitcnt vmcnt(0)
	flat_load_dwordx4 v[44:47], v[8:9]
	flat_load_dwordx4 v[32:35], v[8:9] offset:16
	flat_load_dwordx4 v[40:43], v[8:9] offset:32
	flat_load_dwordx4 v[28:31], v[8:9] offset:48
	v_lshlrev_b64 v[8:9], 7, v[120:121]
	v_and_b32_e32 v124, 56, v10
	v_lshl_add_u64 v[8:9], s[64:65], 0, v[8:9]
	v_lshlrev_b32_e32 v136, 1, v124
	v_readlane_b32 s6, v255, 31
	v_lshl_add_u64 v[8:9], v[8:9], 0, v[136:137]
	v_lshlrev_b64 v[122:123], 13, v[120:121]
	v_readlane_b32 s7, v255, 32
	flat_load_dwordx4 v[20:23], v[8:9]
	s_add_i32 s56, s58, s68
	v_lshl_add_u64 v[8:9], s[6:7], 0, v[122:123]
	v_lshl_add_u64 v[128:129], v[8:9], 0, v[136:137]
	flat_load_dwordx3 v[112:114], v[6:7]
	flat_load_dwordx4 v[24:27], v[128:129]
	s_sub_i32 s7, s56, 28
	s_ashr_i32 s7, s7, 8
	s_or_b32 s6, s56, 3
	s_add_i32 s7, s7, 1
	s_cmp_gt_i32 s6, 30
	v_and_b32_e32 v121, 15, v115
	s_cselect_b32 s40, s7, 0
	v_lshlrev_b32_e32 v6, 6, v121
	s_cmp_gt_i32 s40, 0
	s_cselect_b64 s[38:39], -1, 0
	s_cmp_lt_i32 s40, 1
	v_lshlrev_b32_e32 v6, 1, v6
	s_cmp_gt_i32 s40, 1
	s_cselect_b64 s[20:21], -1, 0
	s_cmp_gt_i32 s40, 2
	s_cselect_b64 s[36:37], -1, 0
	s_cmp_gt_i32 s40, 3
	s_cselect_b64 s[18:19], -1, 0
	s_cmp_gt_i32 s40, 4
	s_cselect_b64 s[34:35], -1, 0
	s_cmp_gt_i32 s40, 5
	s_cselect_b64 s[16:17], -1, 0
	s_cmp_gt_i32 s40, 6
	s_cselect_b64 s[30:31], -1, 0
	s_cmp_gt_i32 s40, 7
	s_cselect_b64 s[14:15], -1, 0
	s_cmp_gt_i32 s40, 8
	s_cselect_b64 s[28:29], -1, 0
	s_cmp_gt_i32 s40, 9
	s_cselect_b64 s[12:13], -1, 0
	s_cmp_gt_i32 s40, 10
	s_cselect_b64 s[26:27], -1, 0
	s_cmp_gt_i32 s40, 11
	s_cselect_b64 s[10:11], -1, 0
	s_cmp_gt_i32 s40, 12
	s_cselect_b64 s[24:25], -1, 0
	s_cmp_gt_i32 s40, 13
	s_cselect_b64 s[8:9], -1, 0
	s_cmp_gt_i32 s40, 14
	s_cselect_b64 s[22:23], -1, 0
	s_cmp_gt_i32 s40, 15
	s_cselect_b64 s[6:7], -1, 0
	v_mov_b32_e32 v7, v137
	v_lshl_add_u64 v[138:139], s[42:43], 0, v[6:7]
	v_lshl_add_u64 v[138:139], v[4:5], 1, v[138:139]
	v_add_co_u32_e32 v138, vcc, 0x1000, v138
	s_nop 1
	v_addc_co_u32_e32 v139, vcc, 0, v139, vcc
	s_cmp_lt_i32 s40, 1
	s_cbranch_scc1 .Lcq_issued
	global_load_dwordx4 v[48:51], v[138:139], off offset:-4096
	global_load_dwordx4 v[140:143], v[138:139], off offset:-4032
	s_cmp_lt_i32 s40, 2
	s_cbranch_scc1 .Lcq_issued
	global_load_dwordx4 v[52:55], v[138:139], off offset:-2048
	global_load_dwordx4 v[144:147], v[138:139], off offset:-1984
	s_cmp_lt_i32 s40, 3
	s_cbranch_scc1 .Lcq_issued
	global_load_dwordx4 v[56:59], v[138:139], off offset:0
	global_load_dwordx4 v[148:151], v[138:139], off offset:64
	s_cmp_lt_i32 s40, 4
	s_cbranch_scc1 .Lcq_issued
	global_load_dwordx4 v[60:63], v[138:139], off offset:2048
	global_load_dwordx4 v[152:155], v[138:139], off offset:2112
	v_add_co_u32_e32 v138, vcc, 0x2000, v138
	s_nop 1
	v_addc_co_u32_e32 v139, vcc, 0, v139, vcc
	s_cmp_lt_i32 s40, 5
	s_cbranch_scc1 .Lcq_issued
	global_load_dwordx4 v[64:67], v[138:139], off offset:-4096
	global_load_dwordx4 v[156:159], v[138:139], off offset:-4032
	s_cmp_lt_i32 s40, 6
	s_cbranch_scc1 .Lcq_issued
	global_load_dwordx4 v[68:71], v[138:139], off offset:-2048
	global_load_dwordx4 v[160:163], v[138:139], off offset:-1984
	s_cmp_lt_i32 s40, 7
	s_cbranch_scc1 .Lcq_issued
	global_load_dwordx4 v[72:75], v[138:139], off offset:0
	global_load_dwordx4 v[164:167], v[138:139], off offset:64
	s_cmp_lt_i32 s40, 8
	s_cbranch_scc1 .Lcq_issued
	global_load_dwordx4 v[76:79], v[138:139], off offset:2048
	global_load_dwordx4 v[168:171], v[138:139], off offset:2112
	v_add_co_u32_e32 v138, vcc, 0x2000, v138
	s_nop 1
	v_addc_co_u32_e32 v139, vcc, 0, v139, vcc
	s_cmp_lt_i32 s40, 9
	s_cbranch_scc1 .Lcq_issued
	global_load_dwordx4 v[80:83], v[138:139], off offset:-4096
	global_load_dwordx4 v[172:175], v[138:139], off offset:-4032
	s_cmp_lt_i32 s40, 10
	s_cbranch_scc1 .Lcq_issued
	global_load_dwordx4 v[84:87], v[138:139], off offset:-2048
	global_load_dwordx4 v[176:179], v[138:139], off offset:-1984
	s_cmp_lt_i32 s40, 11
	s_cbranch_scc1 .Lcq_issued
	global_load_dwordx4 v[88:91], v[138:139], off offset:0
	global_load_dwordx4 v[180:183], v[138:139], off offset:64
	s_cmp_lt_i32 s40, 12
	s_cbranch_scc1 .Lcq_issued
	global_load_dwordx4 v[92:95], v[138:139], off offset:2048
	global_load_dwordx4 v[184:187], v[138:139], off offset:2112
	v_add_co_u32_e32 v138, vcc, 0x2000, v138
	s_nop 1
	v_addc_co_u32_e32 v139, vcc, 0, v139, vcc
	s_cmp_lt_i32 s40, 13
	s_cbranch_scc1 .Lcq_issued
	global_load_dwordx4 v[96:99], v[138:139], off offset:-4096
	global_load_dwordx4 v[188:191], v[138:139], off offset:-4032
	s_cmp_lt_i32 s40, 14
	s_cbranch_scc1 .Lcq_issued
	global_load_dwordx4 v[100:103], v[138:139], off offset:-2048
	global_load_dwordx4 v[192:195], v[138:139], off offset:-1984
	s_cmp_lt_i32 s40, 15
	s_cbranch_scc1 .Lcq_issued
	global_load_dwordx4 v[104:107], v[138:139], off offset:0
	global_load_dwordx4 v[196:199], v[138:139], off offset:64
	s_cmp_lt_i32 s40, 16
	s_cbranch_scc1 .Lcq_issued
	global_load_dwordx4 v[108:111], v[138:139], off offset:2048
	global_load_dwordx4 v[204:207], v[138:139], off offset:2112
.Lcq_issued:
	s_cmp_gt_i32 s40, 15
	s_cbranch_scc1 .Lcq_zeroed
	v_mov_b32_e32 v108, v137
	v_mov_b32_e32 v109, v137
	v_mov_b32_e32 v110, v137
	v_mov_b32_e32 v111, v137
	s_cmp_gt_i32 s40, 14
	s_cbranch_scc1 .Lcq_zeroed
	v_mov_b32_e32 v104, v137
	v_mov_b32_e32 v105, v137
	v_mov_b32_e32 v106, v137
	v_mov_b32_e32 v107, v137
	s_cmp_gt_i32 s40, 13
	s_cbranch_scc1 .Lcq_zeroed
	v_mov_b32_e32 v100, v137
	v_mov_b32_e32 v101, v137
	v_mov_b32_e32 v102, v137
	v_mov_b32_e32 v103, v137
	s_cmp_gt_i32 s40, 12
	s_cbranch_scc1 .Lcq_zeroed
	v_mov_b32_e32 v96, v137
	v_mov_b32_e32 v97, v137
	v_mov_b32_e32 v98, v137
	v_mov_b32_e32 v99, v137
	s_cmp_gt_i32 s40, 11
	s_cbranch_scc1 .Lcq_zeroed
	v_mov_b32_e32 v92, v137
	v_mov_b32_e32 v93, v137
	v_mov_b32_e32 v94, v137
	v_mov_b32_e32 v95, v137
	s_cmp_gt_i32 s40, 10
	s_cbranch_scc1 .Lcq_zeroed
	v_mov_b32_e32 v88, v137
	v_mov_b32_e32 v89, v137
	v_mov_b32_e32 v90, v137
	v_mov_b32_e32 v91, v137
	s_cmp_gt_i32 s40, 9
	s_cbranch_scc1 .Lcq_zeroed
	v_mov_b32_e32 v84, v137
	v_mov_b32_e32 v85, v137
	v_mov_b32_e32 v86, v137
	v_mov_b32_e32 v87, v137
	s_cmp_gt_i32 s40, 8
	s_cbranch_scc1 .Lcq_zeroed
	v_mov_b32_e32 v80, v137
	v_mov_b32_e32 v81, v137
	v_mov_b32_e32 v82, v137
	v_mov_b32_e32 v83, v137
	s_cmp_gt_i32 s40, 7
	s_cbranch_scc1 .Lcq_zeroed
	v_mov_b32_e32 v76, v137
	v_mov_b32_e32 v77, v137
	v_mov_b32_e32 v78, v137
	v_mov_b32_e32 v79, v137
	s_cmp_gt_i32 s40, 6
	s_cbranch_scc1 .Lcq_zeroed
	v_mov_b32_e32 v72, v137
	v_mov_b32_e32 v73, v137
	v_mov_b32_e32 v74, v137
	v_mov_b32_e32 v75, v137
	s_cmp_gt_i32 s40, 5
	s_cbranch_scc1 .Lcq_zeroed
	v_mov_b32_e32 v68, v137
	v_mov_b32_e32 v69, v137
	v_mov_b32_e32 v70, v137
	v_mov_b32_e32 v71, v137
	s_cmp_gt_i32 s40, 4
	s_cbranch_scc1 .Lcq_zeroed
	v_mov_b32_e32 v64, v137
	v_mov_b32_e32 v65, v137
	v_mov_b32_e32 v66, v137
	v_mov_b32_e32 v67, v137
	s_cmp_gt_i32 s40, 3
	s_cbranch_scc1 .Lcq_zeroed
	v_mov_b32_e32 v60, v137
	v_mov_b32_e32 v61, v137
	v_mov_b32_e32 v62, v137
	v_mov_b32_e32 v63, v137
	s_cmp_gt_i32 s40, 2
	s_cbranch_scc1 .Lcq_zeroed
	v_mov_b32_e32 v56, v137
	v_mov_b32_e32 v57, v137
	v_mov_b32_e32 v58, v137
	v_mov_b32_e32 v59, v137
	s_cmp_gt_i32 s40, 1
	s_cbranch_scc1 .Lcq_zeroed
	v_mov_b32_e32 v52, v137
	v_mov_b32_e32 v53, v137
	v_mov_b32_e32 v54, v137
	v_mov_b32_e32 v55, v137
	s_cmp_gt_i32 s40, 0
	s_cbranch_scc1 .Lcq_zeroed
	v_mov_b32_e32 v48, v137
	v_mov_b32_e32 v49, v137
	v_mov_b32_e32 v50, v137
	v_mov_b32_e32 v51, v137
.Lcq_zeroed:
	s_waitcnt vmcnt(0) lgkmcnt(0)
	s_cmp_lt_i32 s40, 1
	s_cbranch_scc1 .Lcq_done
	v_mfma_f32_16x16x32_bf16 v[48:51], v[48:51], v[36:39], 0
	v_mfma_f32_16x16x32_bf16 v[48:51], v[140:143], v[0:3], v[48:51]
	s_cmp_lt_i32 s40, 2
	s_cbranch_scc1 .Lcq_done
	v_mfma_f32_16x16x32_bf16 v[52:55], v[52:55], v[36:39], 0
	v_mfma_f32_16x16x32_bf16 v[52:55], v[144:147], v[0:3], v[52:55]
	s_cmp_lt_i32 s40, 3
	s_cbranch_scc1 .Lcq_done
	v_mfma_f32_16x16x32_bf16 v[56:59], v[56:59], v[36:39], 0
	v_mfma_f32_16x16x32_bf16 v[56:59], v[148:151], v[0:3], v[56:59]
	s_cmp_lt_i32 s40, 4
	s_cbranch_scc1 .Lcq_done
	v_mfma_f32_16x16x32_bf16 v[60:63], v[60:63], v[36:39], 0
	v_mfma_f32_16x16x32_bf16 v[60:63], v[152:155], v[0:3], v[60:63]
	s_cmp_lt_i32 s40, 5
	s_cbranch_scc1 .Lcq_done
	v_mfma_f32_16x16x32_bf16 v[64:67], v[64:67], v[36:39], 0
	v_mfma_f32_16x16x32_bf16 v[64:67], v[156:159], v[0:3], v[64:67]
	s_cmp_lt_i32 s40, 6
	s_cbranch_scc1 .Lcq_done
	v_mfma_f32_16x16x32_bf16 v[68:71], v[68:71], v[36:39], 0
	v_mfma_f32_16x16x32_bf16 v[68:71], v[160:163], v[0:3], v[68:71]
	s_cmp_lt_i32 s40, 7
	s_cbranch_scc1 .Lcq_done
	v_mfma_f32_16x16x32_bf16 v[72:75], v[72:75], v[36:39], 0
	v_mfma_f32_16x16x32_bf16 v[72:75], v[164:167], v[0:3], v[72:75]
	s_cmp_lt_i32 s40, 8
	s_cbranch_scc1 .Lcq_done
	v_mfma_f32_16x16x32_bf16 v[76:79], v[76:79], v[36:39], 0
	v_mfma_f32_16x16x32_bf16 v[76:79], v[168:171], v[0:3], v[76:79]
	s_cmp_lt_i32 s40, 9
	s_cbranch_scc1 .Lcq_done
	v_mfma_f32_16x16x32_bf16 v[80:83], v[80:83], v[36:39], 0
	v_mfma_f32_16x16x32_bf16 v[80:83], v[172:175], v[0:3], v[80:83]
	s_cmp_lt_i32 s40, 10
	s_cbranch_scc1 .Lcq_done
	v_mfma_f32_16x16x32_bf16 v[84:87], v[84:87], v[36:39], 0
	v_mfma_f32_16x16x32_bf16 v[84:87], v[176:179], v[0:3], v[84:87]
	s_cmp_lt_i32 s40, 11
	s_cbranch_scc1 .Lcq_done
	v_mfma_f32_16x16x32_bf16 v[88:91], v[88:91], v[36:39], 0
	v_mfma_f32_16x16x32_bf16 v[88:91], v[180:183], v[0:3], v[88:91]
	s_cmp_lt_i32 s40, 12
	s_cbranch_scc1 .Lcq_done
	v_mfma_f32_16x16x32_bf16 v[92:95], v[92:95], v[36:39], 0
	v_mfma_f32_16x16x32_bf16 v[92:95], v[184:187], v[0:3], v[92:95]
	s_cmp_lt_i32 s40, 13
	s_cbranch_scc1 .Lcq_done
	v_mfma_f32_16x16x32_bf16 v[96:99], v[96:99], v[36:39], 0
	v_mfma_f32_16x16x32_bf16 v[96:99], v[188:191], v[0:3], v[96:99]
	s_cmp_lt_i32 s40, 14
	s_cbranch_scc1 .Lcq_done
	v_mfma_f32_16x16x32_bf16 v[100:103], v[100:103], v[36:39], 0
	v_mfma_f32_16x16x32_bf16 v[100:103], v[192:195], v[0:3], v[100:103]
	s_cmp_lt_i32 s40, 15
	s_cbranch_scc1 .Lcq_done
	v_mfma_f32_16x16x32_bf16 v[104:107], v[104:107], v[36:39], 0
	v_mfma_f32_16x16x32_bf16 v[104:107], v[196:199], v[0:3], v[104:107]
	s_cmp_lt_i32 s40, 16
	s_cbranch_scc1 .Lcq_done
	v_mfma_f32_16x16x32_bf16 v[108:111], v[108:111], v[36:39], 0
	v_mfma_f32_16x16x32_bf16 v[108:111], v[204:207], v[0:3], v[108:111]
.Lcq_done:
.LBB0_447:
	s_nop 6
	v_subrev_u32_e32 v6, 31, v126
	v_lshrrev_b32_e32 v6, 4, v6
	v_cmp_lt_i32_e32 vcc, 30, v126
	v_lshlrev_b32_e32 v116, 2, v125
	v_mul_f32_e32 v7, 0x3e38aa3b, v48
	v_cndmask_b32_e32 v6, -1, v6, vcc
	v_cmp_le_i32_e32 vcc, v116, v6
	v_mul_f32_e32 v9, 0x3e38aa3b, v49
	v_mul_f32_e32 v10, 0x3e38aa3b, v50
	v_cndmask_b32_e32 v7, v241, v7, vcc
	v_max_f32_e32 v8, 0xf149f2ca, v7
	v_cmp_lt_i32_e32 vcc, v116, v6
	v_cndmask_b32_e64 v8, v241, v8, s[38:39]
	v_mul_f32_e32 v11, 0x3e38aa3b, v53
	v_cndmask_b32_e32 v16, v241, v9, vcc
	v_or_b32_e32 v9, 2, v116
	v_max_f32_e32 v8, v8, v16
	v_cmp_le_i32_e32 vcc, v9, v6
	v_cndmask_b32_e64 v8, v241, v8, s[38:39]
	v_or_b32_e32 v9, 3, v116
	v_cndmask_b32_e32 v18, v241, v10, vcc
	v_max_f32_e32 v8, v8, v18
	v_mul_f32_e32 v10, 0x3e38aa3b, v51
	v_cmp_le_i32_e32 vcc, v9, v6
	v_cndmask_b32_e64 v8, v241, v8, s[38:39]
	v_add_u32_e32 v9, 16, v116
	v_cndmask_b32_e32 v131, v241, v10, vcc
	v_max_f32_e32 v8, v8, v131
	v_mul_f32_e32 v10, 0x3e38aa3b, v52
	v_cmp_le_i32_e32 vcc, v9, v6
	v_cndmask_b32_e64 v8, v241, v8, s[38:39]
	v_mul_f32_e32 v133, 0x3e38aa3b, v110
	v_cndmask_b32_e32 v140, v241, v10, vcc
	v_add_u32_e32 v10, 17, v116
	v_max_f32_e32 v9, v8, v140
	v_cmp_le_i32_e32 vcc, v10, v6
	v_cndmask_b32_e64 v9, v8, v9, s[20:21]
	v_add_u32_e32 v10, 18, v116
	v_cndmask_b32_e32 v141, v241, v11, vcc
	v_max_f32_e32 v9, v9, v141
	v_mul_f32_e32 v11, 0x3e38aa3b, v54
	v_cmp_le_i32_e32 vcc, v10, v6
	v_cndmask_b32_e64 v9, v8, v9, s[20:21]
	v_add_u32_e32 v10, 19, v116
	v_cndmask_b32_e32 v142, v241, v11, vcc
	v_max_f32_e32 v9, v9, v142
	v_mul_f32_e32 v11, 0x3e38aa3b, v55
	v_cmp_le_i32_e32 vcc, v10, v6
	v_cndmask_b32_e64 v9, v8, v9, s[20:21]
	v_mul_f32_e32 v10, 0x3e38aa3b, v56
	v_cndmask_b32_e32 v143, v241, v11, vcc
	v_max_f32_e32 v9, v9, v143
	v_cndmask_b32_e64 v8, v8, v9, s[20:21]
	v_add_u32_e32 v9, 32, v116
	v_cmp_le_i32_e32 vcc, v9, v6
	v_mul_f32_e32 v11, 0x3e38aa3b, v57
	v_mul_f32_e32 v134, 0x3e38aa3b, v111
	v_cndmask_b32_e32 v144, v241, v10, vcc
	v_add_u32_e32 v10, 33, v116
	v_max_f32_e32 v9, v8, v144
	v_cmp_le_i32_e32 vcc, v10, v6
	v_cndmask_b32_e64 v9, v8, v9, s[36:37]
	v_add_u32_e32 v10, 34, v116
	v_cndmask_b32_e32 v145, v241, v11, vcc
	v_max_f32_e32 v9, v9, v145
	v_mul_f32_e32 v11, 0x3e38aa3b, v58
	v_cmp_le_i32_e32 vcc, v10, v6
	v_cndmask_b32_e64 v9, v8, v9, s[36:37]
	v_add_u32_e32 v10, 35, v116
	v_cndmask_b32_e32 v146, v241, v11, vcc
	v_max_f32_e32 v9, v9, v146
	v_mul_f32_e32 v11, 0x3e38aa3b, v59
	v_cmp_le_i32_e32 vcc, v10, v6
	v_cndmask_b32_e64 v9, v8, v9, s[36:37]
	v_mul_f32_e32 v10, 0x3e38aa3b, v60
	v_cndmask_b32_e32 v152, v241, v11, vcc
	v_max_f32_e32 v9, v9, v152
	v_cndmask_b32_e64 v8, v8, v9, s[36:37]
	v_add_u32_e32 v9, 48, v116
	v_cmp_le_i32_e32 vcc, v9, v6
	v_mul_f32_e32 v11, 0x3e38aa3b, v61
	v_cndmask_b32_e64 v16, v49, v16, s[38:39]
	v_cndmask_b32_e32 v153, v241, v10, vcc
	v_add_u32_e32 v10, 49, v116
	v_max_f32_e32 v9, v8, v153
	v_cmp_le_i32_e32 vcc, v10, v6
	v_cndmask_b32_e64 v9, v8, v9, s[18:19]
	v_add_u32_e32 v10, 50, v116
	v_cndmask_b32_e32 v154, v241, v11, vcc
	v_max_f32_e32 v9, v9, v154
	v_mul_f32_e32 v11, 0x3e38aa3b, v62
	v_cmp_le_i32_e32 vcc, v10, v6
	v_cndmask_b32_e64 v9, v8, v9, s[18:19]
	v_add_u32_e32 v10, 51, v116
	v_cndmask_b32_e32 v155, v241, v11, vcc
	v_max_f32_e32 v9, v9, v155
	v_mul_f32_e32 v11, 0x3e38aa3b, v63
	v_cmp_le_i32_e32 vcc, v10, v6
	v_cndmask_b32_e64 v9, v8, v9, s[18:19]
	v_mul_f32_e32 v10, 0x3e38aa3b, v64
	v_cndmask_b32_e32 v156, v241, v11, vcc
	v_max_f32_e32 v9, v9, v156
	v_cndmask_b32_e64 v8, v8, v9, s[18:19]
	v_add_u32_e32 v9, 64, v116
	v_cmp_le_i32_e32 vcc, v9, v6
	v_mul_f32_e32 v11, 0x3e38aa3b, v65
	v_cndmask_b32_e64 v18, v50, v18, s[38:39]
	v_cndmask_b32_e32 v157, v241, v10, vcc
	v_max_f32_e32 v9, v8, v157
	v_add_u32_e32 v10, 0x41, v116
	v_cndmask_b32_e64 v9, v8, v9, s[34:35]
	v_cmp_le_i32_e32 vcc, v10, v6
	v_max_f32_e32 v9, v9, v9
	v_add_u32_e32 v10, 0x42, v116
	v_cndmask_b32_e32 v158, v241, v11, vcc
	v_max_f32_e32 v9, v9, v158
	v_cndmask_b32_e64 v9, v8, v9, s[34:35]
	v_mul_f32_e32 v11, 0x3e38aa3b, v66
	v_cmp_le_i32_e32 vcc, v10, v6
	v_max_f32_e32 v9, v9, v9
	v_add_u32_e32 v10, 0x43, v116
	v_cndmask_b32_e32 v159, v241, v11, vcc
	v_max_f32_e32 v9, v9, v159
	v_cndmask_b32_e64 v9, v8, v9, s[34:35]
	v_mul_f32_e32 v11, 0x3e38aa3b, v67
	v_cmp_le_i32_e32 vcc, v10, v6
	v_max_f32_e32 v9, v9, v9
	v_mul_f32_e32 v10, 0x3e38aa3b, v68
	v_cndmask_b32_e32 v160, v241, v11, vcc
	v_max_f32_e32 v9, v9, v160
	v_cndmask_b32_e64 v8, v8, v9, s[34:35]
	v_add_u32_e32 v9, 0x50, v116
	v_cmp_le_i32_e32 vcc, v9, v6
	v_max_f32_e32 v9, v8, v8
	v_mul_f32_e32 v11, 0x3e38aa3b, v69
	v_cndmask_b32_e32 v161, v241, v10, vcc
	v_max_f32_e32 v9, v9, v161
	v_add_u32_e32 v10, 0x51, v116
	v_cndmask_b32_e64 v9, v8, v9, s[16:17]
	v_cmp_le_i32_e32 vcc, v10, v6
	v_max_f32_e32 v9, v9, v9
	v_add_u32_e32 v10, 0x52, v116
	v_cndmask_b32_e32 v162, v241, v11, vcc
	v_max_f32_e32 v9, v9, v162
	v_cndmask_b32_e64 v9, v8, v9, s[16:17]
	v_mul_f32_e32 v11, 0x3e38aa3b, v70
	v_cmp_le_i32_e32 vcc, v10, v6
	v_max_f32_e32 v9, v9, v9
	v_add_u32_e32 v10, 0x53, v116
	v_cndmask_b32_e32 v163, v241, v11, vcc
	v_max_f32_e32 v9, v9, v163
	v_cndmask_b32_e64 v9, v8, v9, s[16:17]
	v_mul_f32_e32 v11, 0x3e38aa3b, v71
	v_cmp_le_i32_e32 vcc, v10, v6
	v_max_f32_e32 v9, v9, v9
	v_mul_f32_e32 v10, 0x3e38aa3b, v72
	v_cndmask_b32_e32 v164, v241, v11, vcc
	v_max_f32_e32 v9, v9, v164
	v_cndmask_b32_e64 v8, v8, v9, s[16:17]
	v_add_u32_e32 v9, 0x60, v116
	v_cmp_le_i32_e32 vcc, v9, v6
	v_max_f32_e32 v9, v8, v8
	v_mul_f32_e32 v11, 0x3e38aa3b, v73
	v_cndmask_b32_e32 v165, v241, v10, vcc
	v_max_f32_e32 v9, v9, v165
	v_add_u32_e32 v10, 0x61, v116
	v_cndmask_b32_e64 v9, v8, v9, s[30:31]
	v_cmp_le_i32_e32 vcc, v10, v6
	v_max_f32_e32 v9, v9, v9
	v_add_u32_e32 v10, 0x62, v116
	v_cndmask_b32_e32 v166, v241, v11, vcc
	v_max_f32_e32 v9, v9, v166
	v_cndmask_b32_e64 v9, v8, v9, s[30:31]
	v_mul_f32_e32 v11, 0x3e38aa3b, v74
	v_cmp_le_i32_e32 vcc, v10, v6
	v_max_f32_e32 v9, v9, v9
	v_add_u32_e32 v10, 0x63, v116
	v_cndmask_b32_e32 v167, v241, v11, vcc
	v_max_f32_e32 v9, v9, v167
	v_cndmask_b32_e64 v9, v8, v9, s[30:31]
	v_mul_f32_e32 v11, 0x3e38aa3b, v75
	v_cmp_le_i32_e32 vcc, v10, v6
	v_max_f32_e32 v9, v9, v9
	v_mul_f32_e32 v10, 0x3e38aa3b, v76
	v_cndmask_b32_e32 v168, v241, v11, vcc
	v_max_f32_e32 v9, v9, v168
	v_cndmask_b32_e64 v8, v8, v9, s[30:31]
	v_add_u32_e32 v9, 0x70, v116
	v_cmp_le_i32_e32 vcc, v9, v6
	v_max_f32_e32 v9, v8, v8
	v_mul_f32_e32 v11, 0x3e38aa3b, v77
	v_cndmask_b32_e32 v172, v241, v10, vcc
	v_max_f32_e32 v9, v9, v172
	v_add_u32_e32 v10, 0x71, v116
	v_cndmask_b32_e64 v9, v8, v9, s[14:15]
	v_cmp_le_i32_e32 vcc, v10, v6
	v_max_f32_e32 v9, v9, v9
	v_add_u32_e32 v10, 0x72, v116
	v_cndmask_b32_e32 v173, v241, v11, vcc
	v_max_f32_e32 v9, v9, v173
	v_cndmask_b32_e64 v9, v8, v9, s[14:15]
	v_mul_f32_e32 v11, 0x3e38aa3b, v78
	v_cmp_le_i32_e32 vcc, v10, v6
	v_max_f32_e32 v9, v9, v9
	v_add_u32_e32 v10, 0x73, v116
	v_cndmask_b32_e32 v174, v241, v11, vcc
	v_max_f32_e32 v9, v9, v174
	v_cndmask_b32_e64 v9, v8, v9, s[14:15]
	v_mul_f32_e32 v11, 0x3e38aa3b, v79
	v_cmp_le_i32_e32 vcc, v10, v6
	v_max_f32_e32 v9, v9, v9
	v_mul_f32_e32 v10, 0x3e38aa3b, v80
	v_cndmask_b32_e32 v175, v241, v11, vcc
	v_max_f32_e32 v9, v9, v175
	v_cndmask_b32_e64 v8, v8, v9, s[14:15]
	v_add_u32_e32 v9, 0x80, v116
	v_cmp_le_i32_e32 vcc, v9, v6
	v_max_f32_e32 v9, v8, v8
	v_mul_f32_e32 v11, 0x3e38aa3b, v81
	v_cndmask_b32_e32 v176, v241, v10, vcc
	v_max_f32_e32 v9, v9, v176
	v_add_u32_e32 v10, 0x81, v116
	v_cndmask_b32_e64 v9, v8, v9, s[28:29]
	v_cmp_le_i32_e32 vcc, v10, v6
	v_max_f32_e32 v9, v9, v9
	v_add_u32_e32 v10, 0x82, v116
	v_cndmask_b32_e32 v177, v241, v11, vcc
	v_max_f32_e32 v9, v9, v177
	v_cndmask_b32_e64 v9, v8, v9, s[28:29]
	v_mul_f32_e32 v11, 0x3e38aa3b, v82
	v_cmp_le_i32_e32 vcc, v10, v6
	v_max_f32_e32 v9, v9, v9
	v_add_u32_e32 v10, 0x83, v116
	v_cndmask_b32_e32 v178, v241, v11, vcc
	v_max_f32_e32 v9, v9, v178
	v_cndmask_b32_e64 v9, v8, v9, s[28:29]
	v_mul_f32_e32 v11, 0x3e38aa3b, v83
	v_cmp_le_i32_e32 vcc, v10, v6
	v_max_f32_e32 v9, v9, v9
	v_mul_f32_e32 v10, 0x3e38aa3b, v84
	v_cndmask_b32_e32 v179, v241, v11, vcc
	v_max_f32_e32 v9, v9, v179
	v_cndmask_b32_e64 v8, v8, v9, s[28:29]
	v_add_u32_e32 v9, 0x90, v116
	v_cmp_le_i32_e32 vcc, v9, v6
	v_max_f32_e32 v9, v8, v8
	v_mul_f32_e32 v11, 0x3e38aa3b, v85
	v_cndmask_b32_e32 v180, v241, v10, vcc
	v_max_f32_e32 v9, v9, v180
	v_add_u32_e32 v10, 0x91, v116
	v_cndmask_b32_e64 v9, v8, v9, s[12:13]
	v_cmp_le_i32_e32 vcc, v10, v6
	v_max_f32_e32 v9, v9, v9
	v_add_u32_e32 v10, 0x92, v116
	v_cndmask_b32_e32 v181, v241, v11, vcc
	v_max_f32_e32 v9, v9, v181
	v_cndmask_b32_e64 v9, v8, v9, s[12:13]
	v_mul_f32_e32 v11, 0x3e38aa3b, v86
	v_cmp_le_i32_e32 vcc, v10, v6
	v_max_f32_e32 v9, v9, v9
	v_add_u32_e32 v10, 0x93, v116
	v_cndmask_b32_e32 v182, v241, v11, vcc
	v_max_f32_e32 v9, v9, v182
	v_cndmask_b32_e64 v9, v8, v9, s[12:13]
	v_mul_f32_e32 v11, 0x3e38aa3b, v87
	v_cmp_le_i32_e32 vcc, v10, v6
	v_max_f32_e32 v9, v9, v9
	v_mul_f32_e32 v10, 0x3e38aa3b, v88
	v_cndmask_b32_e32 v183, v241, v11, vcc
	v_max_f32_e32 v9, v9, v183
	v_cndmask_b32_e64 v8, v8, v9, s[12:13]
	v_add_u32_e32 v9, 0xa0, v116
	v_cmp_le_i32_e32 vcc, v9, v6
	v_max_f32_e32 v9, v8, v8
	v_mul_f32_e32 v11, 0x3e38aa3b, v89
	v_cndmask_b32_e32 v184, v241, v10, vcc
	v_max_f32_e32 v9, v9, v184
	v_add_u32_e32 v10, 0xa1, v116
	v_cndmask_b32_e64 v9, v8, v9, s[26:27]
	v_cmp_le_i32_e32 vcc, v10, v6
	v_max_f32_e32 v9, v9, v9
	v_add_u32_e32 v10, 0xa2, v116
	v_cndmask_b32_e32 v188, v241, v11, vcc
	v_max_f32_e32 v9, v9, v188
	v_cndmask_b32_e64 v9, v8, v9, s[26:27]
	v_mul_f32_e32 v11, 0x3e38aa3b, v90
	v_cmp_le_i32_e32 vcc, v10, v6
	v_max_f32_e32 v9, v9, v9
	v_add_u32_e32 v10, 0xa3, v116
	v_cndmask_b32_e32 v189, v241, v11, vcc
	v_max_f32_e32 v9, v9, v189
	v_cndmask_b32_e64 v9, v8, v9, s[26:27]
	v_mul_f32_e32 v11, 0x3e38aa3b, v91
	v_cmp_le_i32_e32 vcc, v10, v6
	v_max_f32_e32 v9, v9, v9
	v_mul_f32_e32 v10, 0x3e38aa3b, v92
	v_cndmask_b32_e32 v190, v241, v11, vcc
	v_max_f32_e32 v9, v9, v190
	v_cndmask_b32_e64 v8, v8, v9, s[26:27]
	v_add_u32_e32 v9, 0xb0, v116
	v_cmp_le_i32_e32 vcc, v9, v6
	v_max_f32_e32 v9, v8, v8
	v_mul_f32_e32 v11, 0x3e38aa3b, v93
	v_cndmask_b32_e32 v150, v241, v10, vcc
	v_max_f32_e32 v9, v9, v150
	v_add_u32_e32 v10, 0xb1, v116
	v_cndmask_b32_e64 v9, v8, v9, s[10:11]
	v_cmp_le_i32_e32 vcc, v10, v6
	v_max_f32_e32 v9, v9, v9
	v_add_u32_e32 v10, 0xb2, v116
	v_cndmask_b32_e32 v151, v241, v11, vcc
	v_max_f32_e32 v9, v9, v151
	v_cndmask_b32_e64 v9, v8, v9, s[10:11]
	v_mul_f32_e32 v11, 0x3e38aa3b, v94
	v_cmp_le_i32_e32 vcc, v10, v6
	v_max_f32_e32 v9, v9, v9
	v_add_u32_e32 v10, 0xb3, v116
	v_cndmask_b32_e32 v148, v241, v11, vcc
	v_max_f32_e32 v9, v9, v148
	v_cndmask_b32_e64 v9, v8, v9, s[10:11]
	v_mul_f32_e32 v11, 0x3e38aa3b, v95
	v_cmp_le_i32_e32 vcc, v10, v6
	v_max_f32_e32 v9, v9, v9
	v_mul_f32_e32 v10, 0x3e38aa3b, v96
	v_cndmask_b32_e32 v149, v241, v11, vcc
	v_max_f32_e32 v9, v9, v149
	v_cndmask_b32_e64 v8, v8, v9, s[10:11]
	v_add_u32_e32 v9, 0xc0, v116
	v_cmp_le_i32_e32 vcc, v9, v6
	v_max_f32_e32 v9, v8, v8
	v_mul_f32_e32 v11, 0x3e38aa3b, v97
	v_cndmask_b32_e32 v139, v241, v10, vcc
	v_max_f32_e32 v9, v9, v139
	v_add_u32_e32 v10, 0xc1, v116
	v_cndmask_b32_e64 v9, v8, v9, s[24:25]
	v_cmp_le_i32_e32 vcc, v10, v6
	v_max_f32_e32 v9, v9, v9
	v_add_u32_e32 v10, 0xc2, v116
	v_cndmask_b32_e32 v147, v241, v11, vcc
	v_max_f32_e32 v9, v9, v147
	v_cndmask_b32_e64 v9, v8, v9, s[24:25]
	v_mul_f32_e32 v11, 0x3e38aa3b, v98
	v_cmp_le_i32_e32 vcc, v10, v6
	v_max_f32_e32 v9, v9, v9
	v_add_u32_e32 v10, 0xc3, v116
	v_cndmask_b32_e32 v135, v241, v11, vcc
	v_max_f32_e32 v9, v9, v135
	v_cndmask_b32_e64 v9, v8, v9, s[24:25]
	v_mul_f32_e32 v11, 0x3e38aa3b, v99
	v_cmp_le_i32_e32 vcc, v10, v6
	v_max_f32_e32 v9, v9, v9
	v_mul_f32_e32 v10, 0x3e38aa3b, v100
	v_cndmask_b32_e32 v138, v241, v11, vcc
	v_max_f32_e32 v9, v9, v138
	v_cndmask_b32_e64 v8, v8, v9, s[24:25]
	v_add_u32_e32 v9, 0xd0, v116
	v_cmp_le_i32_e32 vcc, v9, v6
	v_max_f32_e32 v9, v8, v8
	v_mul_f32_e32 v11, 0x3e38aa3b, v101
	v_cndmask_b32_e32 v130, v241, v10, vcc
	v_max_f32_e32 v9, v9, v130
	v_add_u32_e32 v10, 0xd1, v116
	v_cndmask_b32_e64 v9, v8, v9, s[8:9]
	v_cmp_le_i32_e32 vcc, v10, v6
	v_max_f32_e32 v9, v9, v9
	v_add_u32_e32 v10, 0xd2, v116
	v_cndmask_b32_e32 v132, v241, v11, vcc
	v_max_f32_e32 v9, v9, v132
	v_cndmask_b32_e64 v9, v8, v9, s[8:9]
	v_mul_f32_e32 v11, 0x3e38aa3b, v102
	v_cmp_le_i32_e32 vcc, v10, v6
	v_max_f32_e32 v9, v9, v9
	v_add_u32_e32 v10, 0xd3, v116
	v_cndmask_b32_e32 v17, v241, v11, vcc
	v_max_f32_e32 v9, v9, v17
	v_cndmask_b32_e64 v9, v8, v9, s[8:9]
	v_mul_f32_e32 v11, 0x3e38aa3b, v103
	v_cmp_le_i32_e32 vcc, v10, v6
	v_max_f32_e32 v9, v9, v9
	v_mul_f32_e32 v10, 0x3e38aa3b, v104
	v_cndmask_b32_e32 v19, v241, v11, vcc
	v_max_f32_e32 v9, v9, v19
	v_cndmask_b32_e64 v8, v8, v9, s[8:9]
	v_add_u32_e32 v9, 0xe0, v116
	v_cmp_le_i32_e32 vcc, v9, v6
	v_max_f32_e32 v9, v8, v8
	v_mul_f32_e32 v11, 0x3e38aa3b, v105
	v_cndmask_b32_e32 v14, v241, v10, vcc
	v_max_f32_e32 v9, v9, v14
	v_add_u32_e32 v10, 0xe1, v116
	v_cndmask_b32_e64 v9, v8, v9, s[22:23]
	v_cmp_le_i32_e32 vcc, v10, v6
	v_max_f32_e32 v9, v9, v9
	v_add_u32_e32 v10, 0xe2, v116
	v_cndmask_b32_e32 v15, v241, v11, vcc
	v_max_f32_e32 v9, v9, v15
	v_cndmask_b32_e64 v9, v8, v9, s[22:23]
	v_mul_f32_e32 v11, 0x3e38aa3b, v106
	v_cmp_le_i32_e32 vcc, v10, v6
	v_max_f32_e32 v9, v9, v9
	v_add_u32_e32 v10, 0xe3, v116
	v_cndmask_b32_e32 v12, v241, v11, vcc
	v_max_f32_e32 v9, v9, v12
	v_cndmask_b32_e64 v9, v8, v9, s[22:23]
	v_mul_f32_e32 v11, 0x3e38aa3b, v107
	v_cmp_le_i32_e32 vcc, v10, v6
	v_max_f32_e32 v9, v9, v9
	v_cndmask_b32_e64 v131, v51, v131, s[38:39]
	v_cndmask_b32_e32 v13, v241, v11, vcc
	v_max_f32_e32 v9, v9, v13
	v_cndmask_b32_e64 v127, v8, v9, s[22:23]
	v_add_u32_e32 v8, 0xf0, v116
	v_mul_f32_e32 v9, 0x3e38aa3b, v108
	v_cmp_le_i32_e32 vcc, v8, v6
	v_max_f32_e32 v8, v127, v127
	v_mul_f32_e32 v11, 0x3e38aa3b, v109
	v_cndmask_b32_e32 v10, v241, v9, vcc
	v_max_f32_e32 v8, v8, v10
	v_add_u32_e32 v9, 0xf1, v116
	v_cndmask_b32_e64 v8, v127, v8, s[6:7]
	v_cmp_le_i32_e32 vcc, v9, v6
	v_max_f32_e32 v8, v8, v8
	v_cndmask_b32_e64 v143, v55, v143, s[20:21]
	v_cndmask_b32_e32 v11, v241, v11, vcc
	v_max_f32_e32 v8, v8, v11
	v_cndmask_b32_e64 v9, v127, v8, s[6:7]
	v_add_u32_e32 v8, 0xf2, v116
	v_cmp_le_i32_e32 vcc, v8, v6
	v_max_f32_e32 v9, v9, v9
	v_cndmask_b32_e64 v150, v92, v150, s[10:11]
	v_cndmask_b32_e32 v8, v241, v133, vcc
	v_max_f32_e32 v9, v9, v8
	v_cndmask_b32_e64 v133, v127, v9, s[6:7]
	v_add_u32_e32 v9, 0xf3, v116
	v_cmp_le_i32_e32 vcc, v9, v6
	v_max_f32_e32 v6, v133, v133
	v_cndmask_b32_e64 v151, v93, v151, s[10:11]
	v_cndmask_b32_e32 v9, v241, v134, vcc
	v_max_f32_e32 v6, v6, v9
	v_cndmask_b32_e64 v6, v127, v6, s[6:7]
	v_lshlrev_b32_e32 v127, 2, v115
	v_xor_b32_e32 v216, 64, v127
	ds_bpermute_b32 v133, v216, v6
	v_max_f32_e32 v6, v6, v6
	v_xor_b32_e32 v217, 0x80, v127
	v_cndmask_b32_e64 v148, v94, v148, s[10:11]
	v_cndmask_b32_e64 v149, v95, v149, s[10:11]
	s_waitcnt lgkmcnt(0)
	v_max_f32_e32 v133, v133, v133
	v_max_f32_e32 v6, v6, v133
	ds_bpermute_b32 v133, v217, v6
	v_cndmask_b32_e64 v139, v96, v139, s[24:25]
	v_cndmask_b32_e64 v147, v97, v147, s[24:25]
	v_cndmask_b32_e64 v135, v98, v135, s[24:25]
	v_cndmask_b32_e64 v138, v99, v138, s[24:25]
	s_waitcnt lgkmcnt(0)
	v_max_f32_e32 v133, v133, v133
	v_max_f32_e32 v133, v6, v133
	v_cndmask_b32_e64 v6, v48, v7, s[38:39]
	v_sub_f32_e32 v7, v6, v133
	v_exp_f32_e32 v7, v7
	v_sub_f32_e32 v134, v16, v133
	v_exp_f32_e32 v134, v134
	v_cmp_lt_f32_e32 vcc, s89, v6
	v_cndmask_b32_e64 v130, v100, v130, s[8:9]
	v_cndmask_b32_e64 v132, v101, v132, s[8:9]
	v_cndmask_b32_e32 v6, 0, v7, vcc
	v_cmp_lt_f32_e32 vcc, s89, v16
	v_add_f32_e32 v169, 0, v6
	v_cndmask_b32_e64 v17, v102, v17, s[8:9]
	v_cndmask_b32_e32 v7, 0, v134, vcc
	v_sub_f32_e32 v134, v18, v133
	v_add_f32_e32 v16, v169, v7
	v_exp_f32_e32 v134, v134
	v_sub_f32_e32 v169, v131, v133
	v_exp_f32_e32 v169, v169
	v_cmp_lt_f32_e32 vcc, s89, v18
	v_cndmask_b32_e64 v19, v103, v19, s[8:9]
	v_cndmask_b32_e64 v14, v104, v14, s[22:23]
	v_cndmask_b32_e32 v18, 0, v134, vcc
	v_cmp_lt_f32_e32 vcc, s89, v131
	v_add_f32_e32 v16, v16, v18
	v_cndmask_b32_e64 v15, v105, v15, s[22:23]
	v_cndmask_b32_e32 v134, 0, v169, vcc
	v_add_f32_e32 v16, v16, v134
	v_cndmask_b32_e64 v169, 0, v16, s[38:39]
	v_cndmask_b32_e64 v16, v52, v140, s[20:21]
	v_sub_f32_e32 v131, v16, v133
	v_cndmask_b32_e64 v140, v53, v141, s[20:21]
	v_exp_f32_e32 v131, v131
	v_sub_f32_e32 v141, v140, v133
	v_exp_f32_e32 v141, v141
	v_cmp_lt_f32_e32 vcc, s89, v16
	v_cndmask_b32_e64 v12, v106, v12, s[22:23]
	v_cndmask_b32_e64 v13, v107, v13, s[22:23]
	v_cndmask_b32_e32 v16, 0, v131, vcc
	v_cmp_lt_f32_e32 vcc, s89, v140
	v_add_f32_e32 v170, v16, v169
	v_cndmask_b32_e64 v10, v108, v10, s[6:7]
	v_cndmask_b32_e32 v131, 0, v141, vcc
	v_cndmask_b32_e64 v141, v54, v142, s[20:21]
	v_sub_f32_e32 v142, v141, v133
	v_add_f32_e32 v140, v131, v170
	v_exp_f32_e32 v142, v142
	v_sub_f32_e32 v170, v143, v133
	v_exp_f32_e32 v170, v170
	v_cmp_lt_f32_e32 vcc, s89, v141
	v_cndmask_b32_e64 v11, v109, v11, s[6:7]
	v_cndmask_b32_e64 v8, v110, v8, s[6:7]
	v_cndmask_b32_e32 v204, 0, v142, vcc
	v_cmp_lt_f32_e32 vcc, s89, v143
	v_add_f32_e32 v140, v204, v140
	v_cndmask_b32_e64 v142, v57, v145, s[36:37]
	v_cndmask_b32_e32 v205, 0, v170, vcc
	v_add_f32_e32 v140, v205, v140
	v_cndmask_b32_e64 v169, v169, v140, s[20:21]
	v_cndmask_b32_e64 v140, v56, v144, s[36:37]
	v_sub_f32_e32 v141, v140, v133
	v_exp_f32_e32 v141, v141
	v_sub_f32_e32 v143, v142, v133
	v_exp_f32_e32 v143, v143
	v_cmp_lt_f32_e32 vcc, s89, v140
	v_cndmask_b32_e64 v145, v59, v152, s[36:37]
	v_cndmask_b32_e64 v9, v111, v9, s[6:7]
	v_cndmask_b32_e32 v140, 0, v141, vcc
	v_cmp_lt_f32_e32 vcc, s89, v142
	v_add_f32_e32 v144, v140, v169
	v_cndmask_b32_e64 v7, v49, v7, s[38:39]
	v_cndmask_b32_e32 v141, 0, v143, vcc
	v_cndmask_b32_e64 v143, v58, v146, s[36:37]
	v_add_f32_e32 v142, v141, v144
	v_sub_f32_e32 v144, v143, v133
	v_exp_f32_e32 v144, v144
	v_sub_f32_e32 v146, v145, v133
	v_exp_f32_e32 v146, v146
	v_cmp_lt_f32_e32 vcc, s89, v143
	v_cndmask_b32_e64 v6, v48, v6, s[38:39]
	s_nop 0
	v_cndmask_b32_e32 v143, 0, v144, vcc
	v_cmp_lt_f32_e32 vcc, s89, v145
	v_add_f32_e32 v144, v143, v142
	s_nop 0
	v_cndmask_b32_e32 v142, 0, v146, vcc
	v_add_f32_e32 v144, v142, v144
	v_cndmask_b32_e64 v152, v169, v144, s[36:37]
	v_cndmask_b32_e64 v144, v60, v153, s[18:19]
	v_sub_f32_e32 v145, v144, v133
	v_cndmask_b32_e64 v146, v61, v154, s[18:19]
	v_exp_f32_e32 v145, v145
	v_sub_f32_e32 v153, v146, v133
	v_exp_f32_e32 v153, v153
	v_cmp_lt_f32_e32 vcc, s89, v144
	s_nop 1
	v_cndmask_b32_e32 v144, 0, v145, vcc
	v_cmp_lt_f32_e32 vcc, s89, v146
	v_add_f32_e32 v154, v144, v152
	v_cndmask_b32_e64 v146, v62, v155, s[18:19]
	v_cndmask_b32_e32 v145, 0, v153, vcc
	v_add_f32_e32 v153, v145, v154
	v_sub_f32_e32 v154, v146, v133
	v_cndmask_b32_e64 v155, v63, v156, s[18:19]
	v_exp_f32_e32 v154, v154
	v_sub_f32_e32 v156, v155, v133
	v_exp_f32_e32 v156, v156
	v_cmp_lt_f32_e32 vcc, s89, v146
	s_nop 1
	v_cndmask_b32_e32 v146, 0, v154, vcc
	v_cmp_lt_f32_e32 vcc, s89, v155
	v_add_f32_e32 v153, v146, v153
	v_cndmask_b32_e64 v155, v65, v158, s[34:35]
	v_cndmask_b32_e32 v171, 0, v156, vcc
	v_add_f32_e32 v153, v171, v153
	v_cndmask_b32_e64 v152, v152, v153, s[18:19]
	v_cndmask_b32_e64 v153, v64, v157, s[34:35]
	v_sub_f32_e32 v154, v153, v133
	v_exp_f32_e32 v154, v154
	v_sub_f32_e32 v156, v155, v133
	v_cmp_lt_f32_e32 vcc, s89, v153
	v_exp_f32_e32 v157, v156
	v_cndmask_b32_e64 v158, v67, v160, s[34:35]
	v_cndmask_b32_e32 v156, 0, v154, vcc
	v_cndmask_b32_e64 v154, v66, v159, s[34:35]
	v_cmp_lt_f32_e32 vcc, s89, v155
	v_sub_f32_e32 v155, v154, v133
	v_exp_f32_e32 v155, v155
	v_sub_f32_e32 v159, v158, v133
	v_exp_f32_e32 v160, v159
	v_add_f32_e32 v153, v156, v152
	v_cndmask_b32_e32 v157, 0, v157, vcc
	v_cmp_lt_f32_e32 vcc, s89, v154
	v_add_f32_e32 v153, v157, v153
	s_nop 0
	v_cndmask_b32_e32 v159, 0, v155, vcc
	v_cmp_lt_f32_e32 vcc, s89, v158
	v_add_f32_e32 v153, v159, v153
	v_cndmask_b32_e64 v155, v69, v162, s[16:17]
	v_cndmask_b32_e32 v158, 0, v160, vcc
	v_add_f32_e32 v153, v158, v153
	v_cndmask_b32_e64 v152, v152, v153, s[34:35]
	v_cndmask_b32_e64 v153, v68, v161, s[16:17]
	v_sub_f32_e32 v154, v153, v133
	v_exp_f32_e32 v154, v154
	v_sub_f32_e32 v160, v155, v133
	v_cmp_lt_f32_e32 vcc, s89, v153
	v_exp_f32_e32 v161, v160
	v_cndmask_b32_e64 v162, v71, v164, s[16:17]
	v_cndmask_b32_e32 v160, 0, v154, vcc
	v_cndmask_b32_e64 v154, v70, v163, s[16:17]
	v_cmp_lt_f32_e32 vcc, s89, v155
	v_sub_f32_e32 v155, v154, v133
	v_exp_f32_e32 v155, v155
	v_sub_f32_e32 v163, v162, v133
	v_exp_f32_e32 v163, v163
	v_add_f32_e32 v153, v160, v152
	v_cndmask_b32_e32 v161, 0, v161, vcc
	v_cmp_lt_f32_e32 vcc, s89, v154
	v_add_f32_e32 v153, v161, v153
	v_cndmask_b32_e64 v164, v75, v168, s[30:31]
	v_cndmask_b32_e32 v170, 0, v155, vcc
	v_cmp_lt_f32_e32 vcc, s89, v162
	v_add_f32_e32 v153, v170, v153
	v_cndmask_b32_e64 v155, v73, v166, s[30:31]
	v_cndmask_b32_e32 v169, 0, v163, vcc
	v_add_f32_e32 v153, v169, v153
	v_cndmask_b32_e64 v152, v152, v153, s[16:17]
	v_cndmask_b32_e64 v153, v72, v165, s[30:31]
	v_sub_f32_e32 v154, v153, v133
	v_exp_f32_e32 v154, v154
	v_sub_f32_e32 v162, v155, v133
	v_cmp_lt_f32_e32 vcc, s89, v153
	v_exp_f32_e32 v163, v162
	v_sub_f32_e32 v165, v164, v133
	v_cndmask_b32_e32 v162, 0, v154, vcc
	v_cndmask_b32_e64 v154, v74, v167, s[30:31]
	v_cmp_lt_f32_e32 vcc, s89, v155
	v_sub_f32_e32 v155, v154, v133
	v_exp_f32_e32 v155, v155
	v_exp_f32_e32 v166, v165
	v_add_f32_e32 v153, v162, v152
	v_cndmask_b32_e32 v163, 0, v163, vcc
	v_cmp_lt_f32_e32 vcc, s89, v154
	v_add_f32_e32 v153, v163, v153
	s_nop 0
	v_cndmask_b32_e32 v165, 0, v155, vcc
	v_cmp_lt_f32_e32 vcc, s89, v164
	v_add_f32_e32 v153, v165, v153
	v_cndmask_b32_e64 v155, v77, v173, s[14:15]
	v_cndmask_b32_e32 v164, 0, v166, vcc
	v_add_f32_e32 v153, v164, v153
	v_cndmask_b32_e64 v152, v152, v153, s[30:31]
	v_cndmask_b32_e64 v153, v76, v172, s[14:15]
	v_sub_f32_e32 v154, v153, v133
	v_exp_f32_e32 v154, v154
	v_sub_f32_e32 v166, v155, v133
	v_cmp_lt_f32_e32 vcc, s89, v153
	v_exp_f32_e32 v167, v166
	v_cndmask_b32_e64 v172, v79, v175, s[14:15]
	v_cndmask_b32_e32 v166, 0, v154, vcc
	v_cndmask_b32_e64 v154, v78, v174, s[14:15]
	v_cmp_lt_f32_e32 vcc, s89, v155
	v_sub_f32_e32 v155, v154, v133
	v_exp_f32_e32 v155, v155
	v_sub_f32_e32 v168, v172, v133
	v_exp_f32_e32 v173, v168
	v_add_f32_e32 v153, v166, v152
	v_cndmask_b32_e32 v167, 0, v167, vcc
	v_cmp_lt_f32_e32 vcc, s89, v154
	v_add_f32_e32 v153, v167, v153
	v_cndmask_b32_e64 v174, v83, v179, s[28:29]
	v_cndmask_b32_e32 v168, 0, v155, vcc
	v_cmp_lt_f32_e32 vcc, s89, v172
	v_add_f32_e32 v153, v168, v153
	v_cndmask_b32_e64 v155, v81, v177, s[28:29]
	v_cndmask_b32_e32 v187, 0, v173, vcc
	v_add_f32_e32 v153, v187, v153
	v_cndmask_b32_e64 v152, v152, v153, s[14:15]
	v_cndmask_b32_e64 v153, v80, v176, s[28:29]
	v_sub_f32_e32 v154, v153, v133
	v_exp_f32_e32 v154, v154
	v_sub_f32_e32 v172, v155, v133
	v_cmp_lt_f32_e32 vcc, s89, v153
	v_exp_f32_e32 v173, v172
	v_sub_f32_e32 v175, v174, v133
	v_cndmask_b32_e32 v172, 0, v154, vcc
	v_cndmask_b32_e64 v154, v82, v178, s[28:29]
	v_cmp_lt_f32_e32 vcc, s89, v155
	v_sub_f32_e32 v155, v154, v133
	v_exp_f32_e32 v155, v155
	v_exp_f32_e32 v176, v175
	v_add_f32_e32 v153, v172, v152
	v_cndmask_b32_e32 v173, 0, v173, vcc
	v_cmp_lt_f32_e32 vcc, s89, v154
	v_add_f32_e32 v153, v173, v153
	v_cndmask_b32_e64 v178, v87, v183, s[12:13]
	v_cndmask_b32_e32 v175, 0, v155, vcc
	v_cmp_lt_f32_e32 vcc, s89, v174
	v_add_f32_e32 v153, v175, v153
	v_cndmask_b32_e64 v155, v85, v181, s[12:13]
	v_cndmask_b32_e32 v174, 0, v176, vcc
	v_add_f32_e32 v153, v174, v153
	v_cndmask_b32_e64 v152, v152, v153, s[28:29]
	v_cndmask_b32_e64 v153, v84, v180, s[12:13]
	v_sub_f32_e32 v154, v153, v133
	v_exp_f32_e32 v154, v154
	v_sub_f32_e32 v176, v155, v133
	v_cmp_lt_f32_e32 vcc, s89, v153
	v_exp_f32_e32 v177, v176
	v_sub_f32_e32 v179, v178, v133
	v_cndmask_b32_e32 v176, 0, v154, vcc
	v_cndmask_b32_e64 v154, v86, v182, s[12:13]
	v_cmp_lt_f32_e32 vcc, s89, v155
	v_sub_f32_e32 v155, v154, v133
	v_exp_f32_e32 v155, v155
	v_exp_f32_e32 v179, v179
	v_add_f32_e32 v153, v176, v152
	v_cndmask_b32_e32 v177, 0, v177, vcc
	v_cmp_lt_f32_e32 vcc, s89, v154
	v_add_f32_e32 v153, v177, v153
	v_cndmask_b32_e64 v180, v91, v190, s[26:27]
	v_cndmask_b32_e32 v186, 0, v155, vcc
	v_cmp_lt_f32_e32 vcc, s89, v178
	v_add_f32_e32 v153, v186, v153
	v_cndmask_b32_e64 v155, v89, v188, s[26:27]
	v_cndmask_b32_e32 v185, 0, v179, vcc
	v_add_f32_e32 v153, v185, v153
	v_cndmask_b32_e64 v152, v152, v153, s[12:13]
	v_cndmask_b32_e64 v153, v88, v184, s[26:27]
	v_sub_f32_e32 v154, v153, v133
	v_exp_f32_e32 v154, v154
	v_sub_f32_e32 v178, v155, v133
	v_cmp_lt_f32_e32 vcc, s89, v153
	v_exp_f32_e32 v179, v178
	v_sub_f32_e32 v181, v180, v133
	v_cndmask_b32_e32 v178, 0, v154, vcc
	v_cndmask_b32_e64 v154, v90, v189, s[26:27]
	v_cmp_lt_f32_e32 vcc, s89, v155
	v_sub_f32_e32 v155, v154, v133
	v_exp_f32_e32 v155, v155
	v_exp_f32_e32 v182, v181
	v_add_f32_e32 v153, v178, v152
	v_cndmask_b32_e32 v179, 0, v179, vcc
	v_cmp_lt_f32_e32 vcc, s89, v154
	v_add_f32_e32 v153, v179, v153
	v_sub_f32_e32 v154, v151, v133
	v_cndmask_b32_e32 v181, 0, v155, vcc
	v_cmp_lt_f32_e32 vcc, s89, v180
	v_add_f32_e32 v153, v181, v153
	v_exp_f32_e32 v154, v154
	v_cndmask_b32_e32 v180, 0, v182, vcc
	v_add_f32_e32 v153, v180, v153
	v_cndmask_b32_e64 v152, v152, v153, s[26:27]
	v_sub_f32_e32 v153, v150, v133
	v_exp_f32_e32 v153, v153
	v_cmp_lt_f32_e32 vcc, s89, v150
	s_nop 1
	v_cndmask_b32_e32 v182, 0, v153, vcc
	v_cmp_lt_f32_e32 vcc, s89, v151
	v_sub_f32_e32 v151, v148, v133
	v_exp_f32_e32 v151, v151
	v_cndmask_b32_e32 v183, 0, v154, vcc
	v_sub_f32_e32 v153, v149, v133
	v_cmp_lt_f32_e32 vcc, s89, v148
	v_exp_f32_e32 v153, v153
	v_add_f32_e32 v150, v182, v152
	v_cndmask_b32_e32 v184, 0, v151, vcc
	v_cmp_lt_f32_e32 vcc, s89, v149
	v_sub_f32_e32 v149, v139, v133
	v_exp_f32_e32 v149, v149
	v_add_f32_e32 v150, v183, v150
	v_add_f32_e32 v148, v184, v150
	v_cndmask_b32_e32 v223, 0, v153, vcc
	v_sub_f32_e32 v150, v147, v133
	v_cmp_lt_f32_e32 vcc, s89, v139
	v_exp_f32_e32 v150, v150
	v_add_f32_e32 v148, v223, v148
	v_cndmask_b32_e32 v188, 0, v149, vcc
	v_cmp_lt_f32_e32 vcc, s89, v147
	v_sub_f32_e32 v147, v135, v133
	v_exp_f32_e32 v147, v147
	v_cndmask_b32_e32 v189, 0, v150, vcc
	v_sub_f32_e32 v149, v138, v133
	v_cmp_lt_f32_e32 vcc, s89, v135
	v_exp_f32_e32 v149, v149
	v_cndmask_b32_e64 v148, v152, v148, s[10:11]
	v_cndmask_b32_e32 v191, 0, v147, vcc
	v_cmp_lt_f32_e32 vcc, s89, v138
	v_sub_f32_e32 v138, v130, v133
	v_exp_f32_e32 v138, v138
	v_add_f32_e32 v139, v188, v148
	v_add_f32_e32 v139, v189, v139
	v_add_f32_e32 v135, v191, v139
	v_cndmask_b32_e32 v190, 0, v149, vcc
	v_sub_f32_e32 v139, v132, v133
	v_cmp_lt_f32_e32 vcc, s89, v130
	v_exp_f32_e32 v139, v139
	v_add_f32_e32 v135, v190, v135
	v_cndmask_b32_e32 v192, 0, v138, vcc
	v_cmp_lt_f32_e32 vcc, s89, v132
	v_sub_f32_e32 v132, v17, v133
	v_exp_f32_e32 v132, v132
	v_cndmask_b32_e32 v193, 0, v139, vcc
	v_sub_f32_e32 v138, v19, v133
	v_cmp_lt_f32_e32 vcc, s89, v17
	v_exp_f32_e32 v138, v138
	v_cndmask_b32_e64 v135, v148, v135, s[24:25]
	v_cndmask_b32_e32 v222, 0, v132, vcc
	v_cmp_lt_f32_e32 vcc, s89, v19
	v_sub_f32_e32 v19, v14, v133
	v_exp_f32_e32 v19, v19
	v_add_f32_e32 v130, v192, v135
	v_add_f32_e32 v130, v193, v130
	v_add_f32_e32 v17, v222, v130
	v_cndmask_b32_e32 v221, 0, v138, vcc
	v_sub_f32_e32 v130, v15, v133
	v_cmp_lt_f32_e32 vcc, s89, v14
	v_exp_f32_e32 v130, v130
	v_add_f32_e32 v17, v221, v17
	v_cndmask_b32_e32 v194, 0, v19, vcc
	v_cmp_lt_f32_e32 vcc, s89, v15
	v_sub_f32_e32 v15, v12, v133
	v_exp_f32_e32 v15, v15
	v_cndmask_b32_e32 v195, 0, v130, vcc
	v_sub_f32_e32 v19, v13, v133
	v_cmp_lt_f32_e32 vcc, s89, v12
	v_exp_f32_e32 v19, v19
	v_cndmask_b32_e64 v17, v135, v17, s[8:9]
	v_cndmask_b32_e32 v197, 0, v15, vcc
	v_cmp_lt_f32_e32 vcc, s89, v13
	v_sub_f32_e32 v13, v10, v133
	v_exp_f32_e32 v13, v13
	v_add_f32_e32 v14, v194, v17
	v_add_f32_e32 v14, v195, v14
	v_add_f32_e32 v12, v197, v14
	v_cndmask_b32_e32 v196, 0, v19, vcc
	v_sub_f32_e32 v14, v11, v133
	v_cmp_lt_f32_e32 vcc, s89, v10
	v_exp_f32_e32 v14, v14
	v_add_f32_e32 v12, v196, v12
	v_cndmask_b32_e32 v198, 0, v13, vcc
	v_cmp_lt_f32_e32 vcc, s89, v11
	v_sub_f32_e32 v11, v8, v133
	v_exp_f32_e32 v11, v11
	v_sub_f32_e32 v13, v9, v133
	v_exp_f32_e32 v13, v13
	v_cndmask_b32_e64 v12, v17, v12, s[22:23]
	v_add_f32_e32 v10, v198, v12
	v_cndmask_b32_e32 v199, 0, v14, vcc
	v_cmp_lt_f32_e32 vcc, s89, v8
	v_add_f32_e32 v10, v199, v10
	s_nop 0
	v_cndmask_b32_e32 v220, 0, v11, vcc
	v_cmp_lt_f32_e32 vcc, s89, v9
	v_add_f32_e32 v8, v220, v10
	s_nop 0
	v_cndmask_b32_e32 v219, 0, v13, vcc
	v_add_f32_e32 v8, v219, v8
	v_cndmask_b32_e64 v8, v12, v8, s[6:7]
	ds_bpermute_b32 v9, v216, v8
	s_waitcnt lgkmcnt(0)
	v_add_f32_e32 v8, v8, v9
	ds_bpermute_b32 v9, v217, v8
	s_waitcnt lgkmcnt(0)
	v_add_f32_e32 v8, v8, v9
	v_div_scale_f32 v9, s[40:41], v8, v8, 1.0
	v_rcp_f32_e32 v10, v9
	v_readlane_b32 s40, v255, 33
	v_readlane_b32 s41, v255, 34
	v_fma_f32 v11, -v9, v10, 1.0
	v_fmac_f32_e32 v10, v11, v10
	v_div_scale_f32 v11, vcc, 1.0, v8, 1.0
	v_mul_f32_e32 v12, v11, v10
	v_fma_f32 v13, -v9, v12, v11
	v_fmac_f32_e32 v12, v13, v10
	v_fma_f32 v9, -v9, v12, v11
	v_div_fmas_f32 v9, v9, v10, v12
	v_div_fixup_f32 v9, v9, v8, 1.0
	v_cmp_lt_f32_e32 vcc, 0, v8
	v_cndmask_b32_e64 v8, v50, v18, s[38:39]
	v_lshl_add_u64 v[148:149], v[4:5], 1, s[40:41]
	v_cndmask_b32_e32 v152, 0, v9, vcc
	v_cndmask_b32_e64 v9, v51, v134, s[38:39]
	v_pk_mul_f32 v[6:7], v[152:153], v[6:7] op_sel_hi:[0,1]
	v_pk_mul_f32 v[8:9], v[152:153], v[8:9] op_sel_hi:[0,1]
	v_cndmask_b32_e64 v135, v51, v9, s[38:39]
	v_cndmask_b32_e64 v134, v50, v8, s[38:39]
	v_cndmask_b32_e64 v139, v49, v7, s[38:39]
	v_cndmask_b32_e64 v138, v48, v6, s[38:39]
	v_cndmask_b32_e64 v7, v55, v205, s[20:21]
	v_cndmask_b32_e64 v6, v54, v204, s[20:21]
	v_cndmask_b32_e64 v9, v53, v131, s[20:21]
	v_cndmask_b32_e64 v8, v52, v16, s[20:21]
	v_pk_mul_f32 v[8:9], v[152:153], v[8:9] op_sel_hi:[0,1]
	v_pk_mul_f32 v[6:7], v[152:153], v[6:7] op_sel_hi:[0,1]
	v_lshlrev_b32_e32 v4, 8, v121
	v_cndmask_b32_e64 v5, 0, 1, s[38:39]
	v_cndmask_b32_e64 v131, v55, v7, s[20:21]
	v_cndmask_b32_e64 v130, v54, v6, s[20:21]
	v_cndmask_b32_e64 v133, v53, v9, s[20:21]
	v_cndmask_b32_e64 v132, v52, v8, s[20:21]
	v_cmp_ne_u32_e64 s[40:41], 1, v5
	s_andn2_b64 vcc, exec, s[38:39]
	v_lshlrev_b32_e32 v150, 1, v4
	s_cbranch_vccnz .LBB0_449
	v_mov_b32_e32 v151, v137
	v_lshl_add_u64 v[154:155], v[148:149], 0, v[150:151]
	v_add_co_u32_e32 v8, vcc, s83, v154
	flat_load_dwordx4 v[4:7], v[154:155]
	s_nop 0
	v_addc_co_u32_e32 v9, vcc, 0, v155, vcc
	v_add_co_u32_e32 v12, vcc, 0x4000, v154
	flat_load_dwordx4 v[8:11], v[8:9]
	s_nop 0
	v_addc_co_u32_e32 v13, vcc, 0, v155, vcc
	v_add_co_u32_e32 v154, vcc, 0x6000, v154
	flat_load_dwordx4 v[12:15], v[12:13]
	s_nop 0
	v_addc_co_u32_e32 v155, vcc, 0, v155, vcc
	flat_load_dwordx4 v[224:227], v[154:155]
	v_cvt_pk_bf16_f32 v16, v138, v139
	v_cvt_pk_bf16_f32 v17, v134, v135
	v_cvt_pk_bf16_f32 v18, v132, v133
	v_cvt_pk_bf16_f32 v19, v130, v131
	s_waitcnt vmcnt(0) lgkmcnt(0)
	s_nop 0
	v_mfma_f32_16x16x32_bf16 v[4:7], v[4:7], v[16:19], 0
	v_mfma_f32_16x16x32_bf16 v[8:11], v[8:11], v[16:19], 0
	v_mfma_f32_16x16x32_bf16 v[12:15], v[12:15], v[16:19], 0
	v_mfma_f32_16x16x32_bf16 v[16:19], v[224:227], v[16:19], 0
	s_branch .LBB0_450

.LBB0_450:
	v_cndmask_b32_e64 v141, v57, v141, s[36:37]
	v_cndmask_b32_e64 v140, v56, v140, s[36:37]
	v_mov_b32_e32 v153, v152
	v_cndmask_b32_e64 v141, v57, v141, s[36:37]
	v_cndmask_b32_e64 v140, v56, v140, s[36:37]
	v_cndmask_b32_e64 v154, v58, v143, s[36:37]
	v_cndmask_b32_e64 v224, v62, v146, s[18:19]
	v_cndmask_b32_e64 v143, v61, v145, s[18:19]
	v_cndmask_b32_e64 v226, v60, v144, s[18:19]
	v_pk_mul_f32 v[140:141], v[152:153], v[140:141]
	v_cndmask_b32_e64 v145, v59, v142, s[36:37]
	v_cndmask_b32_e64 v144, v58, v154, s[36:37]
	v_mov_b32_e32 v154, v152
	v_mov_b32_e32 v155, v152
	v_cndmask_b32_e64 v147, v57, v141, s[36:37]
	v_cndmask_b32_e64 v146, v56, v140, s[36:37]
	v_cndmask_b32_e64 v141, v63, v171, s[18:19]
	v_cndmask_b32_e64 v140, v62, v224, s[18:19]
	v_cndmask_b32_e64 v143, v61, v143, s[18:19]
	v_cndmask_b32_e64 v142, v60, v226, s[18:19]
	v_pk_mul_f32 v[144:145], v[154:155], v[144:145]
	v_pk_mul_f32 v[142:143], v[152:153], v[142:143]
	v_pk_mul_f32 v[140:141], v[154:155], v[140:141]
	v_cndmask_b32_e64 v151, 0, 1, s[36:37]
	v_cndmask_b32_e64 v145, v59, v145, s[36:37]
	v_cndmask_b32_e64 v144, v58, v144, s[36:37]
	v_cndmask_b32_e64 v141, v63, v141, s[18:19]
	v_cndmask_b32_e64 v140, v62, v140, s[18:19]
	v_cndmask_b32_e64 v143, v61, v143, s[18:19]
	v_cmp_ne_u32_e64 s[38:39], 1, v151
	s_andn2_b64 vcc, exec, s[36:37]
	v_cndmask_b32_e64 v142, v60, v142, s[18:19]
	s_cbranch_vccnz .LBB0_452
	v_mov_b32_e32 v151, v137
	v_lshl_add_u64 v[204:205], v[148:149], 0, v[150:151]
	global_load_dwordx4 v[228:231], v[204:205], off offset:64
	v_add_co_u32_e32 v236, vcc, 0x2000, v204
	s_nop 1
	v_addc_co_u32_e32 v237, vcc, 0, v205, vcc
	global_load_dwordx4 v[208:211], v[236:237], off offset:64
	v_add_co_u32_e32 v236, vcc, 0x4000, v204
	s_nop 1
	v_addc_co_u32_e32 v237, vcc, 0, v205, vcc
	global_load_dwordx4 v[212:215], v[236:237], off offset:64
	v_add_co_u32_e32 v236, vcc, 0x6000, v204
	s_nop 1
	v_addc_co_u32_e32 v237, vcc, 0, v205, vcc
	global_load_dwordx4 v[232:235], v[236:237], off offset:64
	v_cvt_pk_bf16_f32 v224, v146, v147
	v_cvt_pk_bf16_f32 v225, v144, v145
	v_cvt_pk_bf16_f32 v226, v142, v143
	v_cvt_pk_bf16_f32 v227, v140, v141
	s_waitcnt vmcnt(0) lgkmcnt(0)
	s_nop 0
	v_mfma_f32_16x16x32_bf16 v[4:7], v[228:231], v[224:227], v[4:7]
	v_mfma_f32_16x16x32_bf16 v[8:11], v[208:211], v[224:227], v[8:11]
	v_mfma_f32_16x16x32_bf16 v[12:15], v[212:215], v[224:227], v[12:15]
	v_mfma_f32_16x16x32_bf16 v[16:19], v[232:235], v[224:227], v[16:19]
.LBB0_452:
	v_cndmask_b32_e64 v224, v66, v159, s[34:35]
	v_cndmask_b32_e64 v151, v65, v157, s[34:35]
	v_cndmask_b32_e64 v156, v64, v156, s[34:35]
	v_cndmask_b32_e64 v170, v70, v170, s[16:17]
	v_cndmask_b32_e64 v157, v69, v161, s[16:17]
	v_cndmask_b32_e64 v226, v68, v160, s[16:17]
	v_cndmask_b32_e64 v159, v67, v158, s[34:35]
	v_cndmask_b32_e64 v158, v66, v224, s[34:35]
	v_cndmask_b32_e64 v161, v65, v151, s[34:35]
	v_cndmask_b32_e64 v160, v64, v156, s[34:35]
	v_cndmask_b32_e64 v171, v71, v169, s[16:17]
	v_cndmask_b32_e64 v170, v70, v170, s[16:17]
	v_cndmask_b32_e64 v157, v69, v157, s[16:17]
	v_cndmask_b32_e64 v156, v68, v226, s[16:17]
	v_pk_mul_f32 v[160:161], v[152:153], v[160:161]
	v_pk_mul_f32 v[158:159], v[154:155], v[158:159]
	v_pk_mul_f32 v[156:157], v[152:153], v[156:157]
	v_pk_mul_f32 v[154:155], v[154:155], v[170:171]
	v_cndmask_b32_e64 v151, 0, 1, s[34:35]
	v_cndmask_b32_e64 v159, v67, v159, s[34:35]
	v_cndmask_b32_e64 v158, v66, v158, s[34:35]
	v_cndmask_b32_e64 v161, v65, v161, s[34:35]
	v_cndmask_b32_e64 v160, v64, v160, s[34:35]
	v_cndmask_b32_e64 v155, v71, v155, s[16:17]
	v_cndmask_b32_e64 v154, v70, v154, s[16:17]
	v_cndmask_b32_e64 v157, v69, v157, s[16:17]
	v_cmp_ne_u32_e64 s[36:37], 1, v151
	s_andn2_b64 vcc, exec, s[34:35]
	v_cndmask_b32_e64 v156, v68, v156, s[16:17]
	s_cbranch_vccnz .LBB0_454
	v_mov_b32_e32 v151, v137
	v_lshl_add_u64 v[170:171], v[148:149], 0, v[150:151]
	global_load_dwordx4 v[228:231], v[170:171], off offset:128
	v_add_co_u32_e32 v236, vcc, 0x2000, v170
	s_nop 1
	v_addc_co_u32_e32 v237, vcc, 0, v171, vcc
	global_load_dwordx4 v[208:211], v[236:237], off offset:128
	v_add_co_u32_e32 v236, vcc, 0x4000, v170
	s_nop 1
	v_addc_co_u32_e32 v237, vcc, 0, v171, vcc
	global_load_dwordx4 v[212:215], v[236:237], off offset:128
	v_add_co_u32_e32 v236, vcc, 0x6000, v170
	s_nop 1
	v_addc_co_u32_e32 v237, vcc, 0, v171, vcc
	global_load_dwordx4 v[232:235], v[236:237], off offset:128
	v_cvt_pk_bf16_f32 v224, v160, v161
	v_cvt_pk_bf16_f32 v225, v158, v159
	v_cvt_pk_bf16_f32 v226, v156, v157
	v_cvt_pk_bf16_f32 v227, v154, v155
	s_waitcnt vmcnt(0) lgkmcnt(0)
	s_nop 0
	v_mfma_f32_16x16x32_bf16 v[4:7], v[228:231], v[224:227], v[4:7]
	v_mfma_f32_16x16x32_bf16 v[8:11], v[208:211], v[224:227], v[8:11]
	v_mfma_f32_16x16x32_bf16 v[12:15], v[212:215], v[224:227], v[12:15]
	v_mfma_f32_16x16x32_bf16 v[16:19], v[232:235], v[224:227], v[16:19]
.LBB0_454:
	v_cndmask_b32_e64 v170, v74, v165, s[30:31]
	v_cndmask_b32_e64 v151, v73, v163, s[30:31]
	v_cndmask_b32_e64 v162, v72, v162, s[30:31]
	v_cndmask_b32_e64 v165, v75, v164, s[30:31]
	v_cndmask_b32_e64 v164, v74, v170, s[30:31]
	v_mov_b32_e32 v170, v152
	v_mov_b32_e32 v171, v152
	v_cndmask_b32_e64 v224, v78, v168, s[14:15]
	v_cndmask_b32_e64 v163, v77, v167, s[14:15]
	v_cndmask_b32_e64 v226, v76, v166, s[14:15]
	v_cndmask_b32_e64 v167, v73, v151, s[30:31]
	v_cndmask_b32_e64 v166, v72, v162, s[30:31]
	v_pk_mul_f32 v[164:165], v[170:171], v[164:165]
	v_pk_mul_f32 v[168:169], v[152:153], v[166:167]
	v_cndmask_b32_e64 v167, v75, v165, s[30:31]
	v_cndmask_b32_e64 v166, v74, v164, s[30:31]
	v_cndmask_b32_e64 v165, v79, v187, s[14:15]
	v_cndmask_b32_e64 v164, v78, v224, s[14:15]
	v_cndmask_b32_e64 v163, v77, v163, s[14:15]
	v_cndmask_b32_e64 v162, v76, v226, s[14:15]
	v_pk_mul_f32 v[204:205], v[152:153], v[162:163]
	v_pk_mul_f32 v[162:163], v[170:171], v[164:165]
	v_cndmask_b32_e64 v151, 0, 1, s[30:31]
	v_cndmask_b32_e64 v169, v73, v169, s[30:31]
	v_cndmask_b32_e64 v168, v72, v168, s[30:31]
	v_cndmask_b32_e64 v163, v79, v163, s[14:15]
	v_cndmask_b32_e64 v162, v78, v162, s[14:15]
	v_cndmask_b32_e64 v165, v77, v205, s[14:15]
	v_cmp_ne_u32_e64 s[34:35], 1, v151
	s_andn2_b64 vcc, exec, s[30:31]
	v_cndmask_b32_e64 v164, v76, v204, s[14:15]
	s_cbranch_vccnz .LBB0_456
	v_mov_b32_e32 v151, v137
	v_lshl_add_u64 v[204:205], v[148:149], 0, v[150:151]
	global_load_dwordx4 v[228:231], v[204:205], off offset:192
	v_add_co_u32_e32 v236, vcc, 0x2000, v204
	s_nop 1
	v_addc_co_u32_e32 v237, vcc, 0, v205, vcc
	global_load_dwordx4 v[208:211], v[236:237], off offset:192
	v_add_co_u32_e32 v236, vcc, 0x4000, v204
	s_nop 1
	v_addc_co_u32_e32 v237, vcc, 0, v205, vcc
	global_load_dwordx4 v[212:215], v[236:237], off offset:192
	v_add_co_u32_e32 v236, vcc, 0x6000, v204
	s_nop 1
	v_addc_co_u32_e32 v237, vcc, 0, v205, vcc
	global_load_dwordx4 v[232:235], v[236:237], off offset:192
	v_cvt_pk_bf16_f32 v224, v168, v169
	v_cvt_pk_bf16_f32 v225, v166, v167
	v_cvt_pk_bf16_f32 v226, v164, v165
	v_cvt_pk_bf16_f32 v227, v162, v163
	s_waitcnt vmcnt(0) lgkmcnt(0)
	s_nop 0
	v_mfma_f32_16x16x32_bf16 v[4:7], v[228:231], v[224:227], v[4:7]
	v_mfma_f32_16x16x32_bf16 v[8:11], v[208:211], v[224:227], v[8:11]
	v_mfma_f32_16x16x32_bf16 v[12:15], v[212:215], v[224:227], v[12:15]
	v_mfma_f32_16x16x32_bf16 v[16:19], v[232:235], v[224:227], v[16:19]
.LBB0_456:
	v_cndmask_b32_e64 v224, v82, v175, s[28:29]
	v_cndmask_b32_e64 v151, v81, v173, s[28:29]
	v_cndmask_b32_e64 v172, v80, v172, s[28:29]
	v_cndmask_b32_e64 v186, v86, v186, s[12:13]
	v_cndmask_b32_e64 v173, v85, v177, s[12:13]
	v_cndmask_b32_e64 v226, v84, v176, s[12:13]
	v_cndmask_b32_e64 v175, v83, v174, s[28:29]
	v_cndmask_b32_e64 v174, v82, v224, s[28:29]
	v_cndmask_b32_e64 v177, v81, v151, s[28:29]
	v_cndmask_b32_e64 v176, v80, v172, s[28:29]
	v_cndmask_b32_e64 v187, v87, v185, s[12:13]
	v_cndmask_b32_e64 v186, v86, v186, s[12:13]
	v_cndmask_b32_e64 v173, v85, v173, s[12:13]
	v_cndmask_b32_e64 v172, v84, v226, s[12:13]
	v_pk_mul_f32 v[176:177], v[152:153], v[176:177]
	v_pk_mul_f32 v[174:175], v[170:171], v[174:175]
	v_pk_mul_f32 v[172:173], v[152:153], v[172:173]
	v_pk_mul_f32 v[170:171], v[170:171], v[186:187]
	v_cndmask_b32_e64 v151, 0, 1, s[28:29]
	v_cndmask_b32_e64 v175, v83, v175, s[28:29]
	v_cndmask_b32_e64 v174, v82, v174, s[28:29]
	v_cndmask_b32_e64 v177, v81, v177, s[28:29]
	v_cndmask_b32_e64 v176, v80, v176, s[28:29]
	v_cndmask_b32_e64 v171, v87, v171, s[12:13]
	v_cndmask_b32_e64 v170, v86, v170, s[12:13]
	v_cndmask_b32_e64 v173, v85, v173, s[12:13]
	v_cmp_ne_u32_e64 s[30:31], 1, v151
	s_andn2_b64 vcc, exec, s[28:29]
	v_cndmask_b32_e64 v172, v84, v172, s[12:13]
	s_cbranch_vccnz .LBB0_458
	v_mov_b32_e32 v151, v137
	v_lshl_add_u64 v[186:187], v[148:149], 0, v[150:151]
	global_load_dwordx4 v[228:231], v[186:187], off offset:256
	v_add_co_u32_e32 v236, vcc, 0x2000, v186
	s_nop 1
	v_addc_co_u32_e32 v237, vcc, 0, v187, vcc
	global_load_dwordx4 v[208:211], v[236:237], off offset:256
	v_add_co_u32_e32 v236, vcc, 0x4000, v186
	s_nop 1
	v_addc_co_u32_e32 v237, vcc, 0, v187, vcc
	global_load_dwordx4 v[212:215], v[236:237], off offset:256
	v_add_co_u32_e32 v236, vcc, 0x6000, v186
	s_nop 1
	v_addc_co_u32_e32 v237, vcc, 0, v187, vcc
	global_load_dwordx4 v[232:235], v[236:237], off offset:256
	v_cvt_pk_bf16_f32 v224, v176, v177
	v_cvt_pk_bf16_f32 v225, v174, v175
	v_cvt_pk_bf16_f32 v226, v172, v173
	v_cvt_pk_bf16_f32 v227, v170, v171
	s_waitcnt vmcnt(0) lgkmcnt(0)
	s_nop 0
	v_mfma_f32_16x16x32_bf16 v[4:7], v[228:231], v[224:227], v[4:7]
	v_mfma_f32_16x16x32_bf16 v[8:11], v[208:211], v[224:227], v[8:11]
	v_mfma_f32_16x16x32_bf16 v[12:15], v[212:215], v[224:227], v[12:15]
	v_mfma_f32_16x16x32_bf16 v[16:19], v[232:235], v[224:227], v[16:19]
.LBB0_458:
	v_cndmask_b32_e64 v186, v90, v181, s[26:27]
	v_cndmask_b32_e64 v151, v89, v179, s[26:27]
	v_cndmask_b32_e64 v178, v88, v178, s[26:27]
	v_cndmask_b32_e64 v181, v91, v180, s[26:27]
	v_cndmask_b32_e64 v180, v90, v186, s[26:27]
	v_mov_b32_e32 v186, v152
	v_mov_b32_e32 v187, v152
	v_cndmask_b32_e64 v224, v94, v184, s[10:11]
	v_cndmask_b32_e64 v179, v93, v183, s[10:11]
	v_cndmask_b32_e64 v226, v92, v182, s[10:11]
	v_cndmask_b32_e64 v183, v89, v151, s[26:27]
	v_cndmask_b32_e64 v182, v88, v178, s[26:27]
	v_pk_mul_f32 v[180:181], v[186:187], v[180:181]
	v_pk_mul_f32 v[184:185], v[152:153], v[182:183]
	v_cndmask_b32_e64 v183, v91, v181, s[26:27]
	v_cndmask_b32_e64 v182, v90, v180, s[26:27]
	v_cndmask_b32_e64 v181, v95, v223, s[10:11]
	v_cndmask_b32_e64 v180, v94, v224, s[10:11]
	v_cndmask_b32_e64 v179, v93, v179, s[10:11]
	v_cndmask_b32_e64 v178, v92, v226, s[10:11]
	v_pk_mul_f32 v[204:205], v[152:153], v[178:179]
	v_pk_mul_f32 v[178:179], v[186:187], v[180:181]
	v_cndmask_b32_e64 v151, 0, 1, s[26:27]
	v_cndmask_b32_e64 v185, v89, v185, s[26:27]
	v_cndmask_b32_e64 v184, v88, v184, s[26:27]
	v_cndmask_b32_e64 v179, v95, v179, s[10:11]
	v_cndmask_b32_e64 v178, v94, v178, s[10:11]
	v_cndmask_b32_e64 v181, v93, v205, s[10:11]
	v_cmp_ne_u32_e64 s[28:29], 1, v151
	s_andn2_b64 vcc, exec, s[26:27]
	v_cndmask_b32_e64 v180, v92, v204, s[10:11]
	s_cbranch_vccnz .LBB0_460
	v_mov_b32_e32 v151, v137
	v_lshl_add_u64 v[204:205], v[148:149], 0, v[150:151]
	global_load_dwordx4 v[228:231], v[204:205], off offset:320
	v_add_co_u32_e32 v236, vcc, 0x2000, v204
	s_nop 1
	v_addc_co_u32_e32 v237, vcc, 0, v205, vcc
	global_load_dwordx4 v[208:211], v[236:237], off offset:320
	v_add_co_u32_e32 v236, vcc, 0x4000, v204
	s_nop 1
	v_addc_co_u32_e32 v237, vcc, 0, v205, vcc
	global_load_dwordx4 v[212:215], v[236:237], off offset:320
	v_add_co_u32_e32 v236, vcc, 0x6000, v204
	s_nop 1
	v_addc_co_u32_e32 v237, vcc, 0, v205, vcc
	global_load_dwordx4 v[232:235], v[236:237], off offset:320
	v_cvt_pk_bf16_f32 v224, v184, v185
	v_cvt_pk_bf16_f32 v225, v182, v183
	v_cvt_pk_bf16_f32 v226, v180, v181
	v_cvt_pk_bf16_f32 v227, v178, v179
	s_waitcnt vmcnt(0) lgkmcnt(0)
	s_nop 0
	v_mfma_f32_16x16x32_bf16 v[4:7], v[228:231], v[224:227], v[4:7]
	v_mfma_f32_16x16x32_bf16 v[8:11], v[208:211], v[224:227], v[8:11]
	v_mfma_f32_16x16x32_bf16 v[12:15], v[212:215], v[224:227], v[12:15]
	v_mfma_f32_16x16x32_bf16 v[16:19], v[232:235], v[224:227], v[16:19]
.LBB0_460:
	v_cndmask_b32_e64 v224, v98, v191, s[24:25]
	v_cndmask_b32_e64 v151, v97, v189, s[24:25]
	v_cndmask_b32_e64 v188, v96, v188, s[24:25]
	v_cndmask_b32_e64 v222, v102, v222, s[8:9]
	v_cndmask_b32_e64 v189, v101, v193, s[8:9]
	v_cndmask_b32_e64 v226, v100, v192, s[8:9]
	v_cndmask_b32_e64 v191, v99, v190, s[24:25]
	v_cndmask_b32_e64 v190, v98, v224, s[24:25]
	v_cndmask_b32_e64 v193, v97, v151, s[24:25]
	v_cndmask_b32_e64 v192, v96, v188, s[24:25]
	v_cndmask_b32_e64 v205, v103, v221, s[8:9]
	v_cndmask_b32_e64 v204, v102, v222, s[8:9]
	v_cndmask_b32_e64 v189, v101, v189, s[8:9]
	v_cndmask_b32_e64 v188, v100, v226, s[8:9]
	v_pk_mul_f32 v[192:193], v[152:153], v[192:193]
	v_pk_mul_f32 v[190:191], v[186:187], v[190:191]
	v_pk_mul_f32 v[188:189], v[152:153], v[188:189]
	v_pk_mul_f32 v[186:187], v[186:187], v[204:205]
	v_cndmask_b32_e64 v151, 0, 1, s[24:25]
	v_cndmask_b32_e64 v191, v99, v191, s[24:25]
	v_cndmask_b32_e64 v190, v98, v190, s[24:25]
	v_cndmask_b32_e64 v193, v97, v193, s[24:25]
	v_cndmask_b32_e64 v192, v96, v192, s[24:25]
	v_cndmask_b32_e64 v187, v103, v187, s[8:9]
	v_cndmask_b32_e64 v186, v102, v186, s[8:9]
	v_cndmask_b32_e64 v189, v101, v189, s[8:9]
	v_cmp_ne_u32_e64 s[26:27], 1, v151
	s_andn2_b64 vcc, exec, s[24:25]
	v_cndmask_b32_e64 v188, v100, v188, s[8:9]
	s_cbranch_vccnz .LBB0_462
	v_mov_b32_e32 v151, v137
	v_lshl_add_u64 v[204:205], v[148:149], 0, v[150:151]
	global_load_dwordx4 v[226:229], v[204:205], off offset:384
	v_add_co_u32_e32 v236, vcc, 0x2000, v204
	s_nop 1
	v_addc_co_u32_e32 v237, vcc, 0, v205, vcc
	global_load_dwordx4 v[208:211], v[236:237], off offset:384
	v_add_co_u32_e32 v236, vcc, 0x4000, v204
	s_nop 1
	v_addc_co_u32_e32 v237, vcc, 0, v205, vcc
	global_load_dwordx4 v[212:215], v[236:237], off offset:384
	v_add_co_u32_e32 v236, vcc, 0x6000, v204
	s_nop 1
	v_addc_co_u32_e32 v237, vcc, 0, v205, vcc
	global_load_dwordx4 v[232:235], v[236:237], off offset:384
	v_cvt_pk_bf16_f32 v222, v192, v193
	v_cvt_pk_bf16_f32 v223, v190, v191
	v_cvt_pk_bf16_f32 v224, v188, v189
	v_cvt_pk_bf16_f32 v225, v186, v187
	s_waitcnt vmcnt(0) lgkmcnt(0)
	s_nop 0
	v_mfma_f32_16x16x32_bf16 v[4:7], v[226:229], v[222:225], v[4:7]
	v_mfma_f32_16x16x32_bf16 v[8:11], v[208:211], v[222:225], v[8:11]
	v_mfma_f32_16x16x32_bf16 v[12:15], v[212:215], v[222:225], v[12:15]
	v_mfma_f32_16x16x32_bf16 v[16:19], v[232:235], v[222:225], v[16:19]
.LBB0_462:
	v_cndmask_b32_e64 v222, v106, v197, s[22:23]
	v_cndmask_b32_e64 v151, v105, v195, s[22:23]
	v_cndmask_b32_e64 v194, v104, v194, s[22:23]
	v_cndmask_b32_e64 v220, v110, v220, s[6:7]
	v_cndmask_b32_e64 v195, v109, v199, s[6:7]
	v_cndmask_b32_e64 v224, v108, v198, s[6:7]
	v_cndmask_b32_e64 v197, v107, v196, s[22:23]
	v_cndmask_b32_e64 v196, v106, v222, s[22:23]
	v_cndmask_b32_e64 v199, v105, v151, s[22:23]
	v_cndmask_b32_e64 v198, v104, v194, s[22:23]
	v_mov_b32_e32 v204, v152
	v_mov_b32_e32 v205, v152
	v_cndmask_b32_e64 v207, v111, v219, s[6:7]
	v_cndmask_b32_e64 v206, v110, v220, s[6:7]
	v_cndmask_b32_e64 v195, v109, v195, s[6:7]
	v_cndmask_b32_e64 v194, v108, v224, s[6:7]
	v_pk_mul_f32 v[198:199], v[152:153], v[198:199]
	v_pk_mul_f32 v[196:197], v[204:205], v[196:197]
	v_pk_mul_f32 v[194:195], v[152:153], v[194:195]
	v_pk_mul_f32 v[152:153], v[204:205], v[206:207]
	v_cndmask_b32_e64 v151, 0, 1, s[22:23]
	v_cndmask_b32_e64 v197, v107, v197, s[22:23]
	v_cndmask_b32_e64 v196, v106, v196, s[22:23]
	v_cndmask_b32_e64 v199, v105, v199, s[22:23]
	v_cndmask_b32_e64 v198, v104, v198, s[22:23]
	v_cndmask_b32_e64 v153, v111, v153, s[6:7]
	v_cndmask_b32_e64 v152, v110, v152, s[6:7]
	v_cndmask_b32_e64 v195, v109, v195, s[6:7]
	v_cmp_ne_u32_e64 s[24:25], 1, v151
	s_andn2_b64 vcc, exec, s[22:23]
	v_cndmask_b32_e64 v194, v108, v194, s[6:7]
	s_cbranch_vccnz .LBB0_464
	v_mov_b32_e32 v151, v137
	v_lshl_add_u64 v[204:205], v[148:149], 0, v[150:151]
	global_load_dwordx4 v[148:151], v[204:205], off offset:448
	v_add_co_u32_e32 v236, vcc, 0x2000, v204
	s_nop 1
	v_addc_co_u32_e32 v237, vcc, 0, v205, vcc
	global_load_dwordx4 v[208:211], v[236:237], off offset:448
	v_add_co_u32_e32 v236, vcc, 0x4000, v204
	s_nop 1
	v_addc_co_u32_e32 v237, vcc, 0, v205, vcc
	global_load_dwordx4 v[212:215], v[236:237], off offset:448
	v_add_co_u32_e32 v236, vcc, 0x6000, v204
	s_nop 1
	v_addc_co_u32_e32 v237, vcc, 0, v205, vcc
	global_load_dwordx4 v[232:235], v[236:237], off offset:448
	v_cvt_pk_bf16_f32 v220, v198, v199
	v_cvt_pk_bf16_f32 v221, v196, v197
	v_cvt_pk_bf16_f32 v222, v194, v195
	v_cvt_pk_bf16_f32 v223, v152, v153
	s_waitcnt vmcnt(0) lgkmcnt(0)
	s_nop 0
	v_mfma_f32_16x16x32_bf16 v[4:7], v[148:151], v[220:223], v[4:7]
	v_mfma_f32_16x16x32_bf16 v[8:11], v[208:211], v[220:223], v[8:11]
	v_mfma_f32_16x16x32_bf16 v[12:15], v[212:215], v[220:223], v[12:15]
	v_mfma_f32_16x16x32_bf16 v[16:19], v[232:235], v[220:223], v[16:19]

.LBB0_484:
	s_or_b64 exec, exec, s[6:7]
	s_ashr_i32 s22, s56, 6
	v_cmp_eq_u32_e64 s[14:15], 0, v115
	v_cmp_eq_u32_e32 vcc, s22, v115
	s_add_i32 s8, s22, -1
	s_or_b64 s[6:7], s[14:15], vcc
	v_cmp_eq_u32_e32 vcc, s8, v115
	s_or_b64 s[12:13], s[6:7], vcc
	s_cmp_gt_i32 s22, -1
	v_readlane_b32 s6, v255, 35
	v_cmp_lt_i32_e64 s[16:17], s22, v115
	s_cselect_b64 s[10:11], -1, 0
	s_cmp_lt_i32 s22, 0
	v_lshl_add_u32 v48, v115, 2, s6
	s_mov_b64 s[6:7], -1
	s_waitcnt lgkmcnt(0)
	s_barrier
	s_cbranch_scc1 .Ltk_skip
	ds_read_b32 v209, v48
	ds_read_b32 v211, v48 offset:256
	ds_read_b32 v213, v48 offset:512
	ds_read_b32 v215, v48 offset:768
	v_mov_b32_e32 v232, 0x461c4000
	v_sub_u32_e32 v208, 63, v115
	s_add_i32 s24, s22, 1
	s_mov_b32 s23, 0
	s_waitcnt lgkmcnt(0)
	v_cndmask_b32_e64 v209, v209, -1.0, s[16:17]
	v_cndmask_b32_e64 v209, v209, v232, s[12:13]
	v_cndmask_b32_e64 v211, v211, -1.0, s[16:17]
	v_cndmask_b32_e64 v211, v211, v232, s[12:13]
	v_cndmask_b32_e64 v213, v213, -1.0, s[16:17]
	v_cndmask_b32_e64 v213, v213, v232, s[12:13]
	v_cndmask_b32_e64 v215, v215, -1.0, s[16:17]
	v_cndmask_b32_e64 v215, v215, v232, s[12:13]
	v_ashrrev_i32_e32 v233, 31, v209
	v_or_b32_e32 v233, 0x80000000, v233
	v_xor_b32_e32 v209, v209, v233
	v_ashrrev_i32_e32 v234, 31, v211
	v_or_b32_e32 v234, 0x80000000, v234
	v_xor_b32_e32 v211, v211, v234
	v_ashrrev_i32_e32 v233, 31, v213
	v_or_b32_e32 v233, 0x80000000, v233
	v_xor_b32_e32 v213, v213, v233
	v_ashrrev_i32_e32 v234, 31, v215
	v_or_b32_e32 v234, 0x80000000, v234
	v_xor_b32_e32 v215, v215, v234
	v_mov_b32_e32 v210, v208
	v_mov_b32_e32 v212, v208
	v_mov_b32_e32 v214, v208
	v_mov_b32_e32 v232, 0
	v_mov_b32_e32 v233, 0
	v_mov_b32_e32 v234, 0
	v_mov_b32_e32 v235, 0
.Ltk_loop:
	v_readlane_b32 s9, v209, s23
	v_readlane_b32 s11, v211, s23
	v_readlane_b32 s19, v213, s23
	v_readlane_b32 s21, v215, s23
	s_sub_i32 s8, 63, s23
	s_mov_b32 s10, s8
	s_mov_b32 s18, s8
	s_mov_b32 s20, s8
	s_add_i32 s23, s23, 1
	v_cmp_gt_u64_e64 s[6:7], s[8:9], v[208:209]
	v_cmp_gt_u64_e32 vcc, s[10:11], v[210:211]
	s_nop 0
	v_addc_co_u32_e64 v232, s[6:7], 0, v232, s[6:7]
	v_addc_co_u32_e32 v233, vcc, 0, v233, vcc
	v_cmp_gt_u64_e64 s[6:7], s[18:19], v[212:213]
	v_cmp_gt_u64_e32 vcc, s[20:21], v[214:215]
	s_cmp_lg_u32 s24, s23
	v_addc_co_u32_e64 v234, s[6:7], 0, v234, s[6:7]
	v_addc_co_u32_e32 v235, vcc, 0, v235, vcc
	s_cbranch_scc1 .Ltk_loop
	v_cmp_gt_u32_e64 s[6:7], 16, v232
	v_cmp_gt_u32_e64 s[8:9], 16, v233
	v_cmp_gt_u32_e64 s[10:11], 16, v234
	v_cmp_gt_u32_e64 s[12:13], 16, v235
	s_branch .Ltk_join
.Ltk_skip:
	s_mov_b64 s[6:7], -1
	s_mov_b64 s[8:9], -1
	s_mov_b64 s[10:11], -1
	s_mov_b64 s[12:13], -1
.Ltk_join:
	s_or_b64 s[16:17], s[8:9], s[6:7]
	s_or_b64 s[16:17], s[16:17], s[10:11]
	s_and_saveexec_b64 s[18:19], s[14:15]
	s_cbranch_execz .LBB0_502
	s_or_b64 s[14:15], s[12:13], s[16:17]
	v_readlane_b32 s20, v255, 36
	v_mov_b64_e32 v[50:51], s[14:15]
	s_nop 0
	v_mov_b32_e32 v48, s20
	ds_write_b64 v48, v[50:51] offset:8192

.LBB0_587:
	s_lshl_b64 s[6:7], 1, s22
	s_and_b64 s[8:9], s[6:7], s[38:39]
	s_cmp_eq_u64 s[8:9], 0
	s_cbranch_scc1 .LBB0_597
	s_add_i32 s8, 0, 0x4000
	s_cmp_eq_u32 s45, 0
	s_cselect_b32 s8, s8, s91
	v_add3_u32 v64, s8, v148, v150
	ds_read_b128 v[24:27], v64
	ds_read_b128 v[28:31], v64 offset:64
	ds_read_b128 v[32:35], v64 offset:2304
	ds_read_b128 v[36:39], v64 offset:2368
	s_cselect_b32 s8, s77, s46
	s_cmp_eq_u32 s22, 0
	s_waitcnt lgkmcnt(0)
	v_mfma_f32_16x16x32_bf16 v[24:27], v[24:27], v[20:23], 0
	v_mfma_f32_16x16x32_bf16 v[32:35], v[32:35], v[20:23], 0
	v_mfma_f32_16x16x32_bf16 v[108:111], v[28:31], v[0:3], v[24:27]
	s_nop 5
	ds_read_b128 v[24:27], v64 offset:4608
	ds_read_b128 v[28:31], v64 offset:4672
	v_mfma_f32_16x16x32_bf16 v[104:107], v[36:39], v[0:3], v[32:35]
	s_nop 2
	ds_read_b128 v[32:35], v64 offset:6912
	ds_read_b128 v[36:39], v64 offset:6976
	v_add3_u32 v64, s8, v149, v148
	ds_read_b128 v[92:95], v64
	ds_read_b128 v[88:91], v64 offset:64
	s_waitcnt lgkmcnt(0)
	v_mfma_f32_16x16x32_bf16 v[24:27], v[24:27], v[20:23], 0
	ds_read_b128 v[84:87], v64 offset:2304
	ds_read_b128 v[80:83], v64 offset:2368
	ds_read_b128 v[76:79], v64 offset:4608
	ds_read_b128 v[72:75], v64 offset:4672
	ds_read_b128 v[68:71], v64 offset:6912
	ds_read_b128 v[64:67], v64 offset:6976
	s_cselect_b64 s[8:9], -1, 0
	v_mfma_f32_16x16x32_bf16 v[100:103], v[28:31], v[0:3], v[24:27]
	s_and_b64 vcc, exec, s[8:9]
	v_mfma_f32_16x16x32_bf16 v[24:27], v[32:35], v[20:23], 0
	v_mfma_f32_16x16x32_bf16 v[96:99], v[36:39], v[0:3], v[24:27]
	s_cbranch_vccnz .LBB0_591
	s_lshl_b32 s8, s22, 6
	s_or_b32 s8, s8, 63
	s_cmp_le_i32 s8, s56
	s_mov_b64 s[8:9], -1
	s_cbranch_scc0 .LBB0_592
	s_nop 0
	v_and_b32_e32 v25, s7, v115
	v_and_b32_e32 v24, s6, v134
	v_cmp_eq_u64_e32 vcc, 0, v[24:25]
	s_mov_b64 s[8:9], 0
	s_nop 0
	v_cndmask_b32_e32 v24, 0, v241, vcc
	v_fmamk_f32 v25, v108, 0x3e38aa3b, v24
	v_fmamk_f32 v26, v109, 0x3e38aa3b, v24
	v_max3_f32 v27, v25, s71, v26
	v_fmamk_f32 v28, v110, 0x3e38aa3b, v24
	v_fmamk_f32 v29, v111, 0x3e38aa3b, v24
	v_max3_f32 v27, v27, v28, v29
	v_fmamk_f32 v30, v104, 0x3e38aa3b, v24
	v_fmamk_f32 v31, v105, 0x3e38aa3b, v24
	v_max3_f32 v27, v27, v30, v31
	v_fmamk_f32 v32, v106, 0x3e38aa3b, v24
	v_fmamk_f32 v33, v107, 0x3e38aa3b, v24
	v_max3_f32 v27, v27, v32, v33
	v_fmamk_f32 v34, v100, 0x3e38aa3b, v24
	v_fmamk_f32 v35, v101, 0x3e38aa3b, v24
	v_max3_f32 v27, v27, v34, v35
	v_fmamk_f32 v36, v102, 0x3e38aa3b, v24
	v_fmamk_f32 v37, v103, 0x3e38aa3b, v24
	v_max3_f32 v27, v27, v36, v37
	v_fmamk_f32 v38, v96, 0x3e38aa3b, v24
	v_fmamk_f32 v39, v97, 0x3e38aa3b, v24
	v_max3_f32 v27, v27, v38, v39
	v_fmamk_f32 v131, v98, 0x3e38aa3b, v24
	v_fmac_f32_e32 v24, 0x3e38aa3b, v99
	v_max3_f32 v27, v27, v131, v24
	v_mov_b32_e32 v127, v27
	s_nop 1
	v_permlane16_swap_b32_e32 v27, v127
	v_max_f32_e32 v27, v27, v127
	v_mov_b32_e32 v127, v27
	s_nop 1
	v_permlane32_swap_b32_e32 v27, v127
	v_max3_f32 v127, v125, v27, v127
	v_sub_f32_e32 v25, v25, v127
	v_exp_f32_e32 v25, v25
	v_sub_f32_e32 v26, v26, v127
	v_exp_f32_e32 v26, v26
	v_sub_f32_e32 v28, v28, v127
	v_exp_f32_e32 v28, v28
	v_sub_f32_e32 v29, v29, v127
	v_exp_f32_e32 v29, v29
	v_sub_f32_e32 v30, v30, v127
	v_add_f32_e32 v138, 0, v25
	v_exp_f32_e32 v30, v30
	v_sub_f32_e32 v31, v31, v127
	v_add_f32_e32 v138, v26, v138
	v_exp_f32_e32 v31, v31
	v_sub_f32_e32 v32, v32, v127
	v_add_f32_e32 v138, v28, v138
	v_exp_f32_e32 v32, v32
	v_sub_f32_e32 v33, v33, v127
	v_add_f32_e32 v138, v29, v138
	v_exp_f32_e32 v33, v33
	v_sub_f32_e32 v34, v34, v127
	v_add_f32_e32 v138, v30, v138
	v_exp_f32_e32 v34, v34
	v_sub_f32_e32 v35, v35, v127
	v_add_f32_e32 v138, v31, v138
	v_exp_f32_e32 v35, v35
	v_sub_f32_e32 v36, v36, v127
	v_add_f32_e32 v138, v32, v138
	v_exp_f32_e32 v139, v36
	v_sub_f32_e32 v37, v37, v127
	v_add_f32_e32 v138, v33, v138
	v_exp_f32_e32 v140, v37
	v_sub_f32_e32 v37, v38, v127
	v_add_f32_e32 v138, v34, v138
	v_exp_f32_e32 v141, v37
	v_sub_f32_e32 v37, v39, v127
	v_add_f32_e32 v138, v35, v138
	v_exp_f32_e32 v143, v37
	v_sub_f32_e32 v37, v131, v127
	v_add_f32_e32 v36, v139, v138
	v_exp_f32_e32 v144, v37
	v_sub_f32_e32 v24, v24, v127
	v_sub_f32_e32 v27, v125, v127
	v_add_f32_e32 v36, v140, v36
	v_exp_f32_e32 v24, v24
	v_add_f32_e32 v36, v141, v36
	v_exp_f32_e32 v142, v27
	v_add_f32_e32 v36, v143, v36
	v_add_f32_e32 v36, v144, v36
	v_add_f32_e32 v131, v24, v36
	v_fmac_f32_e32 v131, v121, v142
	v_cvt_pk_bf16_f32 v36, v25, v26
	v_cvt_pk_bf16_f32 v37, v28, v29
	v_cvt_pk_bf16_f32 v38, v30, v31
	v_cvt_pk_bf16_f32 v39, v32, v33
	v_cvt_pk_bf16_f32 v138, v34, v35
	v_cvt_pk_bf16_f32 v139, v139, v140
	v_cvt_pk_bf16_f32 v140, v141, v143
	v_cvt_pk_bf16_f32 v141, v144, v24
	v_pk_mul_f32 v[26:27], v[62:63], v[142:143] op_sel_hi:[1,0]
	v_pk_mul_f32 v[24:25], v[60:61], v[142:143] op_sel_hi:[1,0]
	v_pk_mul_f32 v[30:31], v[58:59], v[142:143] op_sel_hi:[1,0]
	v_pk_mul_f32 v[28:29], v[56:57], v[142:143] op_sel_hi:[1,0]
	v_pk_mul_f32 v[34:35], v[54:55], v[142:143] op_sel_hi:[1,0]
	v_pk_mul_f32 v[32:33], v[52:53], v[142:143] op_sel_hi:[1,0]
	v_pk_mul_f32 v[144:145], v[50:51], v[142:143] op_sel_hi:[1,0]
	v_pk_mul_f32 v[142:143], v[48:49], v[142:143] op_sel_hi:[1,0]
	s_waitcnt lgkmcnt(0)
	v_mfma_f32_16x16x32_bf16 v[24:27], v[92:95], v[36:39], v[24:27]
	v_mfma_f32_16x16x32_bf16 v[28:31], v[84:87], v[36:39], v[28:31]
	v_mfma_f32_16x16x32_bf16 v[32:35], v[76:79], v[36:39], v[32:35]
	v_mfma_f32_16x16x32_bf16 v[36:39], v[68:71], v[36:39], v[142:145]
	v_mfma_f32_16x16x32_bf16 v[24:27], v[88:91], v[138:141], v[24:27]
	v_mfma_f32_16x16x32_bf16 v[28:31], v[80:83], v[138:141], v[28:31]
	v_mfma_f32_16x16x32_bf16 v[32:35], v[72:75], v[138:141], v[32:35]
	v_mfma_f32_16x16x32_bf16 v[36:39], v[64:67], v[138:141], v[36:39]
	s_branch .LBB0_592

.LBB0_595:
	s_or_b64 exec, exec, s[6:7]
	v_and_b32_e32 v25, 1, v24
	v_and_b32_e32 v26, 2, v24
	v_cmp_eq_u32_e64 s[34:35], 0, v25
	v_mul_f32_e32 v25, 0x3e38aa3b, v108
	v_cmp_eq_u32_e64 s[36:37], 0, v26
	v_mul_f32_e32 v26, 0x3e38aa3b, v109
	v_and_b32_e32 v28, 4, v24
	v_and_b32_e32 v29, 8, v24
	v_cndmask_b32_e64 v25, v25, v241, s[34:35]
	v_cndmask_b32_e64 v26, v26, v241, s[36:37]
	v_cmp_eq_u32_e64 s[28:29], 0, v28
	v_mul_f32_e32 v28, 0x3e38aa3b, v110
	v_cmp_eq_u32_e64 s[30:31], 0, v29
	v_mul_f32_e32 v29, 0x3e38aa3b, v111
	v_and_b32_e32 v30, 16, v24
	v_and_b32_e32 v31, 32, v24
	v_max3_f32 v27, v25, s71, v26
	v_cndmask_b32_e64 v28, v28, v241, s[28:29]
	v_cndmask_b32_e64 v29, v29, v241, s[30:31]
	v_cmp_eq_u32_e64 s[22:23], 0, v30
	v_mul_f32_e32 v30, 0x3e38aa3b, v104
	v_cmp_eq_u32_e64 s[26:27], 0, v31
	v_mul_f32_e32 v31, 0x3e38aa3b, v105
	v_and_b32_e32 v32, 64, v24
	v_and_b32_e32 v33, 0x80, v24
	v_max3_f32 v27, v27, v28, v29
	v_cndmask_b32_e64 v30, v30, v241, s[22:23]
	v_cndmask_b32_e64 v31, v31, v241, s[26:27]
	v_cmp_eq_u32_e64 s[24:25], 0, v32
	v_mul_f32_e32 v32, 0x3e38aa3b, v106
	v_cmp_eq_u32_e64 s[14:15], 0, v33
	v_mul_f32_e32 v33, 0x3e38aa3b, v107
	v_and_b32_e32 v34, 0x100, v24
	v_and_b32_e32 v35, 0x200, v24
	v_max3_f32 v27, v27, v30, v31
	v_cndmask_b32_e64 v32, v32, v241, s[24:25]
	v_cndmask_b32_e64 v33, v33, v241, s[14:15]
	v_cmp_eq_u32_e64 s[20:21], 0, v34
	v_mul_f32_e32 v34, 0x3e38aa3b, v100
	v_cmp_eq_u32_e64 s[18:19], 0, v35
	v_mul_f32_e32 v35, 0x3e38aa3b, v101
	v_and_b32_e32 v36, 0x400, v24
	v_and_b32_e32 v37, 0x800, v24
	v_max3_f32 v27, v27, v32, v33
	v_cndmask_b32_e64 v34, v34, v241, s[20:21]
	v_cndmask_b32_e64 v35, v35, v241, s[18:19]
	v_cmp_eq_u32_e64 s[16:17], 0, v36
	v_mul_f32_e32 v36, 0x3e38aa3b, v102
	v_cmp_eq_u32_e64 s[6:7], 0, v37
	v_mul_f32_e32 v37, 0x3e38aa3b, v103
	v_and_b32_e32 v38, 0x1000, v24
	v_and_b32_e32 v39, 0x2000, v24
	v_max3_f32 v27, v27, v34, v35
	v_cndmask_b32_e64 v36, v36, v241, s[16:17]
	v_cndmask_b32_e64 v37, v37, v241, s[6:7]
	v_cmp_eq_u32_e64 s[12:13], 0, v38
	v_mul_f32_e32 v38, 0x3e38aa3b, v96
	v_cmp_eq_u32_e64 s[10:11], 0, v39
	v_mul_f32_e32 v39, 0x3e38aa3b, v97
	v_and_b32_e32 v96, 0x4000, v24
	v_and_b32_e32 v24, 0x8000, v24
	v_max3_f32 v27, v27, v36, v37
	v_cndmask_b32_e64 v38, v38, v241, s[12:13]
	v_cndmask_b32_e64 v39, v39, v241, s[10:11]
	v_cmp_eq_u32_e64 s[8:9], 0, v96
	v_mul_f32_e32 v96, 0x3e38aa3b, v98
	v_cmp_eq_u32_e32 vcc, 0, v24
	v_mul_f32_e32 v24, 0x3e38aa3b, v99
	v_max3_f32 v27, v27, v38, v39
	v_cndmask_b32_e64 v96, v96, v241, s[8:9]
	v_cndmask_b32_e32 v24, v24, v241, vcc
	v_max3_f32 v27, v27, v96, v24
	v_mov_b32_e32 v97, v27
	s_nop 1
	v_permlane16_swap_b32_e32 v27, v97
	v_max_f32_e32 v27, v27, v97
	v_mov_b32_e32 v97, v27
	s_nop 1
	v_permlane32_swap_b32_e32 v27, v97
	v_max3_f32 v127, v125, v27, v97
	v_sub_f32_e32 v25, v25, v127
	v_exp_f32_e32 v25, v25
	v_sub_f32_e32 v26, v26, v127
	v_exp_f32_e32 v26, v26
	v_sub_f32_e32 v28, v28, v127
	v_exp_f32_e32 v28, v28
	v_sub_f32_e32 v29, v29, v127
	v_exp_f32_e32 v29, v29
	v_sub_f32_e32 v30, v30, v127
	v_cndmask_b32_e64 v25, v25, 0, s[34:35]
	v_exp_f32_e32 v30, v30
	v_sub_f32_e32 v31, v31, v127
	v_add_f32_e32 v97, 0, v25
	v_cndmask_b32_e64 v26, v26, 0, s[36:37]
	v_exp_f32_e32 v31, v31
	v_sub_f32_e32 v32, v32, v127
	v_add_f32_e32 v97, v26, v97
	v_cndmask_b32_e64 v28, v28, 0, s[28:29]
	v_exp_f32_e32 v32, v32
	v_sub_f32_e32 v33, v33, v127
	v_add_f32_e32 v97, v28, v97
	v_cndmask_b32_e64 v29, v29, 0, s[30:31]
	v_exp_f32_e32 v33, v33
	v_sub_f32_e32 v34, v34, v127
	v_add_f32_e32 v97, v29, v97
	v_cndmask_b32_e64 v30, v30, 0, s[22:23]
	v_exp_f32_e32 v34, v34
	v_sub_f32_e32 v35, v35, v127
	v_add_f32_e32 v97, v30, v97
	v_cndmask_b32_e64 v31, v31, 0, s[26:27]
	v_exp_f32_e32 v35, v35
	v_sub_f32_e32 v36, v36, v127
	v_add_f32_e32 v97, v31, v97
	v_cndmask_b32_e64 v32, v32, 0, s[24:25]
	v_exp_f32_e32 v36, v36
	v_sub_f32_e32 v37, v37, v127
	v_add_f32_e32 v97, v32, v97
	v_cndmask_b32_e64 v33, v33, 0, s[14:15]
	v_exp_f32_e32 v37, v37
	v_add_f32_e32 v97, v33, v97
	v_cndmask_b32_e64 v34, v34, 0, s[20:21]
	v_add_f32_e32 v97, v34, v97
	v_cndmask_b32_e64 v35, v35, 0, s[18:19]
	v_add_f32_e32 v97, v35, v97
	v_cndmask_b32_e64 v98, v36, 0, s[16:17]
	v_add_f32_e32 v36, v98, v97
	v_cndmask_b32_e64 v97, v37, 0, s[6:7]
	v_sub_f32_e32 v37, v38, v127
	v_exp_f32_e32 v37, v37
	v_sub_f32_e32 v24, v24, v127
	v_sub_f32_e32 v27, v125, v127
	v_exp_f32_e32 v24, v24
	v_cndmask_b32_e64 v99, v37, 0, s[12:13]
	v_sub_f32_e32 v37, v39, v127
	v_exp_f32_e32 v37, v37
	v_add_f32_e32 v36, v97, v36
	v_exp_f32_e32 v100, v27
	v_add_f32_e32 v36, v99, v36
	v_cndmask_b32_e64 v101, v37, 0, s[10:11]
	v_sub_f32_e32 v37, v96, v127
	v_exp_f32_e32 v37, v37
	v_add_f32_e32 v36, v101, v36
	v_cndmask_b32_e64 v24, v24, 0, vcc
	v_cvt_pk_bf16_f32 v38, v30, v31
	v_cndmask_b32_e64 v102, v37, 0, s[8:9]
	v_add_f32_e32 v36, v102, v36
	v_add_f32_e32 v131, v24, v36
	v_cvt_pk_bf16_f32 v36, v25, v26
	v_cvt_pk_bf16_f32 v37, v28, v29
	v_cvt_pk_bf16_f32 v39, v32, v33
	v_cvt_pk_bf16_f32 v96, v34, v35
	v_cvt_pk_bf16_f32 v97, v98, v97
	v_cvt_pk_bf16_f32 v98, v99, v101
	v_cvt_pk_bf16_f32 v99, v102, v24
	v_pk_mul_f32 v[26:27], v[62:63], v[100:101] op_sel_hi:[1,0]
	v_pk_mul_f32 v[24:25], v[60:61], v[100:101] op_sel_hi:[1,0]
	v_pk_mul_f32 v[30:31], v[58:59], v[100:101] op_sel_hi:[1,0]
	v_pk_mul_f32 v[28:29], v[56:57], v[100:101] op_sel_hi:[1,0]
	v_pk_mul_f32 v[34:35], v[54:55], v[100:101] op_sel_hi:[1,0]
	v_pk_mul_f32 v[32:33], v[52:53], v[100:101] op_sel_hi:[1,0]
	v_pk_mul_f32 v[50:51], v[50:51], v[100:101] op_sel_hi:[1,0]
	v_pk_mul_f32 v[48:49], v[48:49], v[100:101] op_sel_hi:[1,0]
	s_waitcnt lgkmcnt(0)
	v_mfma_f32_16x16x32_bf16 v[24:27], v[92:95], v[36:39], v[24:27]
	v_fmac_f32_e32 v131, v121, v100
	v_mfma_f32_16x16x32_bf16 v[28:31], v[84:87], v[36:39], v[28:31]
	v_mfma_f32_16x16x32_bf16 v[32:35], v[76:79], v[36:39], v[32:35]
	v_mfma_f32_16x16x32_bf16 v[36:39], v[68:71], v[36:39], v[48:51]
	v_mfma_f32_16x16x32_bf16 v[24:27], v[88:91], v[96:99], v[24:27]
	v_mfma_f32_16x16x32_bf16 v[28:31], v[80:83], v[96:99], v[28:31]
	v_mfma_f32_16x16x32_bf16 v[32:35], v[72:75], v[96:99], v[32:35]
	v_mfma_f32_16x16x32_bf16 v[36:39], v[64:67], v[96:99], v[36:39]

.LBB0_613:
	v_fma_f32 v80, v100, s87, 0
	v_fma_f32 v81, v101, s87, 0
	v_max3_f32 v82, v80, s71, v81
	v_fma_f32 v83, v102, s87, 0
	v_fma_f32 v92, v103, s87, 0
	v_max3_f32 v82, v82, v83, v92
	v_fma_f32 v93, v96, s87, 0
	v_fma_f32 v94, v97, s87, 0
	v_max3_f32 v82, v82, v93, v94
	v_fma_f32 v95, v98, s87, 0
	v_fma_f32 v104, v99, s87, 0
	v_max3_f32 v82, v82, v95, v104
	v_fma_f32 v105, v88, s87, 0
	v_fma_f32 v106, v89, s87, 0
	v_max3_f32 v82, v82, v105, v106
	v_fma_f32 v107, v90, s87, 0
	v_fma_f32 v108, v91, s87, 0
	v_max3_f32 v82, v82, v107, v108
	v_fma_f32 v109, v84, s87, 0
	v_fma_f32 v110, v85, s87, 0
	v_max3_f32 v82, v82, v109, v110
	v_fma_f32 v111, v86, s87, 0
	v_fma_f32 v151, v87, s87, 0
	v_max3_f32 v82, v82, v111, v151
	v_mov_b32_e32 v131, v82
	s_nop 1
	v_permlane16_swap_b32_e32 v82, v131
	v_max_f32_e32 v82, v82, v131
	v_mov_b32_e32 v131, v82
	s_nop 1
	v_permlane32_swap_b32_e32 v82, v131
	v_max3_f32 v131, v136, v82, v131
	v_sub_f32_e32 v80, v80, v131
	v_exp_f32_e32 v80, v80
	v_sub_f32_e32 v81, v81, v131
	v_exp_f32_e32 v81, v81
	v_sub_f32_e32 v83, v83, v131
	v_exp_f32_e32 v83, v83
	v_sub_f32_e32 v92, v92, v131
	v_exp_f32_e32 v92, v92
	v_sub_f32_e32 v93, v93, v131
	v_add_f32_e32 v152, 0, v80
	v_exp_f32_e32 v93, v93
	v_sub_f32_e32 v94, v94, v131
	v_add_f32_e32 v152, v81, v152
	v_exp_f32_e32 v94, v94
	v_sub_f32_e32 v95, v95, v131
	v_add_f32_e32 v152, v83, v152
	v_exp_f32_e32 v95, v95
	v_sub_f32_e32 v104, v104, v131
	v_add_f32_e32 v152, v92, v152
	v_exp_f32_e32 v104, v104
	v_sub_f32_e32 v105, v105, v131
	v_add_f32_e32 v152, v93, v152
	v_exp_f32_e32 v105, v105
	v_sub_f32_e32 v106, v106, v131
	v_add_f32_e32 v152, v94, v152
	v_exp_f32_e32 v106, v106
	v_sub_f32_e32 v107, v107, v131
	v_add_f32_e32 v152, v95, v152
	v_exp_f32_e32 v107, v107
	v_sub_f32_e32 v108, v108, v131
	v_add_f32_e32 v152, v104, v152
	v_exp_f32_e32 v153, v108
	v_sub_f32_e32 v109, v109, v131
	v_add_f32_e32 v152, v105, v152
	v_exp_f32_e32 v154, v109
	v_sub_f32_e32 v109, v110, v131
	v_add_f32_e32 v152, v106, v152
	v_exp_f32_e32 v155, v109
	v_sub_f32_e32 v109, v111, v131
	v_add_f32_e32 v152, v107, v152
	v_exp_f32_e32 v157, v109
	v_sub_f32_e32 v109, v151, v131
	v_sub_f32_e32 v82, v136, v131
	v_add_f32_e32 v108, v153, v152
	v_exp_f32_e32 v158, v109
	v_add_f32_e32 v108, v154, v108
	v_exp_f32_e32 v156, v82
	v_add_f32_e32 v108, v155, v108
	v_add_f32_e32 v108, v157, v108
	v_add_f32_e32 v151, v158, v108
	v_fmac_f32_e32 v151, v124, v156
	v_cvt_pk_bf16_f32 v108, v80, v81
	v_cvt_pk_bf16_f32 v109, v83, v92
	v_cvt_pk_bf16_f32 v110, v93, v94
	v_cvt_pk_bf16_f32 v111, v95, v104
	v_cvt_pk_bf16_f32 v152, v105, v106
	v_cvt_pk_bf16_f32 v153, v107, v153
	v_cvt_pk_bf16_f32 v154, v154, v155
	v_cvt_pk_bf16_f32 v155, v157, v158
	v_pk_mul_f32 v[82:83], v[146:147], v[156:157] op_sel_hi:[1,0]
	v_pk_mul_f32 v[80:81], v[144:145], v[156:157] op_sel_hi:[1,0]
	v_pk_mul_f32 v[94:95], v[142:143], v[156:157] op_sel_hi:[1,0]
	v_pk_mul_f32 v[92:93], v[140:141], v[156:157] op_sel_hi:[1,0]
	v_pk_mul_f32 v[106:107], v[138:139], v[156:157] op_sel_hi:[1,0]
	v_pk_mul_f32 v[104:105], v[134:135], v[156:157] op_sel_hi:[1,0]
	v_pk_mul_f32 v[158:159], v[132:133], v[156:157] op_sel_hi:[1,0]
	v_pk_mul_f32 v[156:157], v[128:129], v[156:157] op_sel_hi:[1,0]
	s_waitcnt lgkmcnt(0)
	v_mfma_f32_16x16x32_bf16 v[80:83], v[76:79], v[108:111], v[80:83]
	v_mfma_f32_16x16x32_bf16 v[92:95], v[68:71], v[108:111], v[92:95]
	v_mfma_f32_16x16x32_bf16 v[104:107], v[60:63], v[108:111], v[104:107]
	v_mfma_f32_16x16x32_bf16 v[108:111], v[52:55], v[108:111], v[156:159]
	v_mfma_f32_16x16x32_bf16 v[80:83], v[72:75], v[152:155], v[80:83]
	v_mfma_f32_16x16x32_bf16 v[92:95], v[64:67], v[152:155], v[92:95]
	v_mfma_f32_16x16x32_bf16 v[104:107], v[56:59], v[152:155], v[104:107]
	v_mfma_f32_16x16x32_bf16 v[108:111], v[48:51], v[152:155], v[108:111]
	s_cbranch_execnz .LBB0_609
.LBB0_614:
	s_nop 3
	v_add_u32_e32 v80, 51, v120
	v_cmp_gt_u32_e64 s[36:37], s86, v80
	v_add_u32_e32 v80, 50, v120
	v_add_u32_e32 v93, 33, v120
	v_add_u32_e32 v94, 32, v120
	v_cmp_lt_u32_e64 s[34:35], s81, v80
	v_add_u32_e32 v81, 49, v120
	v_add_u32_e32 v82, 48, v120
	v_cmp_lt_u32_e64 s[20:21], s81, v93
	v_cmp_lt_u32_e64 s[8:9], s81, v94
	v_cndmask_b32_e64 v80, 2, 0, s[34:35]
	v_cmp_lt_u32_e64 s[30:31], s81, v81
	v_cmp_lt_u32_e64 s[28:29], s81, v82
	v_cndmask_b32_e64 v93, 64, 0, s[20:21]
	v_cndmask_b32_e64 v94, v244, 0, s[8:9]
	v_cndmask_b32_e64 v81, 4, 0, s[30:31]
	v_cndmask_b32_e64 v82, 8, 0, s[28:29]
	v_add_u32_e32 v83, 35, v120
	v_add_u32_e32 v92, 34, v120
	v_or3_b32 v80, v80, v93, v94
	v_cmp_lt_u32_e64 s[26:27], s81, v83
	v_cmp_lt_u32_e64 s[22:23], s81, v92
	v_or3_b32 v80, v81, v82, v80
	v_add_u32_e32 v81, 19, v120
	v_add_u32_e32 v82, 18, v120
	v_cndmask_b32_e64 v83, 16, 0, s[26:27]
	v_cndmask_b32_e64 v92, 32, 0, s[22:23]
	v_cmp_gt_u32_e64 s[6:7], s86, v81
	v_cmp_gt_u32_e32 vcc, s86, v82
	v_or3_b32 v80, v83, v92, v80
	v_cndmask_b32_e64 v81, 0, v245, s[6:7]
	v_cndmask_b32_e32 v82, 0, v240, vcc
	v_or3_b32 v80, v81, v80, v82
	v_add_u32_e32 v81, 17, v120
	v_cmp_gt_u32_e64 s[10:11], s86, v81
	v_add_u32_e32 v82, 16, v120
	v_add_u32_e32 v83, 3, v120
	v_cndmask_b32_e64 v81, 0, v246, s[10:11]
	v_cmp_gt_u32_e64 s[10:11], s86, v82
	v_add_u32_e32 v92, 2, v120
	v_add_u32_e32 v93, 1, v120
	v_cndmask_b32_e64 v82, 0, v247, s[10:11]
	v_cmp_gt_u32_e64 s[10:11], s86, v83
	v_mul_f32_e32 v95, 0x3e38aa3b, v101
	v_cndmask_b32_e64 v95, v95, v241, s[34:35]
	v_cndmask_b32_e64 v83, 0, v248, s[10:11]
	v_cmp_gt_u32_e64 s[10:11], s86, v92
	v_mul_f32_e32 v101, 0x3e38aa3b, v102
	v_mul_f32_e32 v102, 0x3e38aa3b, v103
	v_cndmask_b32_e64 v92, 0, v249, s[10:11]
	v_cmp_gt_u32_e64 s[10:11], s86, v93
	v_cndmask_b32_e64 v101, v101, v241, s[30:31]
	v_cndmask_b32_e64 v102, v102, v241, s[28:29]
	v_cndmask_b32_e64 v93, 0, v250, s[10:11]
	v_cmp_gt_u32_e64 s[10:11], s86, v120
	v_mul_f32_e32 v96, 0x3e38aa3b, v96
	v_mul_f32_e32 v97, 0x3e38aa3b, v97
	v_cndmask_b32_e64 v94, 0, v251, s[10:11]
	v_or_b32_e32 v93, v93, v94
	v_mul_f32_e32 v94, 0x3e38aa3b, v100
	v_cndmask_b32_e64 v94, v241, v94, s[36:37]
	v_max3_f32 v100, v94, s71, v95
	v_or_b32_e32 v81, v81, v82
	v_max3_f32 v100, v100, v101, v102
	v_cndmask_b32_e64 v96, v96, v241, s[26:27]
	v_cndmask_b32_e64 v97, v97, v241, s[22:23]
	v_mul_f32_e32 v98, 0x3e38aa3b, v98
	v_mul_f32_e32 v99, 0x3e38aa3b, v99
	v_or_b32_e32 v82, v81, v80
	v_or_b32_e32 v83, v83, v92
	v_max3_f32 v100, v100, v96, v97
	v_cndmask_b32_e64 v98, v98, v241, s[20:21]
	v_cndmask_b32_e64 v99, v99, v241, s[8:9]
	v_mul_f32_e32 v88, 0x3e38aa3b, v88
	v_mul_f32_e32 v89, 0x3e38aa3b, v89
	v_bitop3_b32 v103, v81, s95, v80 bitop3:0xc8
	v_bitop3_b32 v80, v81, s48, v80 bitop3:0xc8
	v_or_b32_e32 v92, v83, v82
	v_max3_f32 v100, v100, v98, v99
	v_cndmask_b32_e64 v88, v241, v88, s[6:7]
	v_cndmask_b32_e32 v89, v241, v89, vcc
	v_cmp_eq_u32_e64 s[24:25], 0, v103
	v_mul_f32_e32 v90, 0x3e38aa3b, v90
	v_cmp_eq_u32_e64 s[12:13], 0, v80
	v_mul_f32_e32 v80, 0x3e38aa3b, v91
	v_bitop3_b32 v91, v83, s90, v82 bitop3:0xc8
	v_bitop3_b32 v82, v83, s83, v82 bitop3:0xc8
	v_max3_f32 v100, v100, v88, v89
	v_cndmask_b32_e64 v90, v90, v241, s[24:25]
	v_cndmask_b32_e64 v80, v80, v241, s[12:13]
	v_cmp_eq_u32_e64 s[18:19], 0, v91
	v_mul_f32_e32 v84, 0x3e38aa3b, v84
	v_cmp_eq_u32_e64 s[16:17], 0, v82
	v_mul_f32_e32 v82, 0x3e38aa3b, v85
	v_bitop3_b32 v83, v93, s50, v92 bitop3:0xc8
	v_bitop3_b32 v85, v93, s82, v92 bitop3:0xc8
	v_max3_f32 v81, v100, v90, v80
	v_cndmask_b32_e64 v84, v84, v241, s[18:19]
	v_cndmask_b32_e64 v82, v82, v241, s[16:17]
	v_cmp_eq_u32_e64 s[14:15], 0, v83
	v_mul_f32_e32 v83, 0x3e38aa3b, v86
	v_cmp_eq_u32_e64 s[10:11], 0, v85
	v_mul_f32_e32 v85, 0x3e38aa3b, v87
	v_max3_f32 v81, v81, v84, v82
	v_cndmask_b32_e64 v83, v83, v241, s[14:15]
	v_cndmask_b32_e64 v85, v85, v241, s[10:11]
	v_max3_f32 v81, v81, v83, v85
	v_mov_b32_e32 v86, v81
	s_nop 1
	v_permlane16_swap_b32_e32 v81, v86
	v_max_f32_e32 v81, v81, v86
	v_mov_b32_e32 v86, v81
	s_nop 1
	v_permlane32_swap_b32_e32 v81, v86
	v_max3_f32 v131, v136, v81, v86
	v_sub_f32_e32 v86, v94, v131
	v_exp_f32_e32 v86, v86
	v_sub_f32_e32 v91, v95, v131
	v_exp_f32_e32 v91, v91
	v_sub_f32_e32 v92, v101, v131
	v_sub_f32_e32 v94, v96, v131
	v_sub_f32_e32 v96, v98, v131
	v_exp_f32_e32 v92, v92
	v_sub_f32_e32 v93, v102, v131
	v_exp_f32_e32 v96, v96
	v_exp_f32_e32 v93, v93
	v_cndmask_b32_e64 v86, 0, v86, s[36:37]
	v_exp_f32_e32 v94, v94
	v_sub_f32_e32 v95, v97, v131
	v_add_f32_e32 v87, 0, v86
	v_cndmask_b32_e64 v91, v91, 0, s[34:35]
	v_exp_f32_e32 v95, v95
	v_add_f32_e32 v87, v91, v87
	v_cndmask_b32_e64 v92, v92, 0, s[30:31]
	v_cndmask_b32_e64 v97, v96, 0, s[20:21]
	v_sub_f32_e32 v96, v99, v131
	v_add_f32_e32 v87, v92, v87
	v_cndmask_b32_e64 v93, v93, 0, s[28:29]
	v_exp_f32_e32 v96, v96
	v_sub_f32_e32 v88, v88, v131
	v_add_f32_e32 v87, v93, v87
	v_cndmask_b32_e64 v94, v94, 0, s[26:27]
	v_exp_f32_e32 v88, v88
	v_sub_f32_e32 v89, v89, v131
	v_add_f32_e32 v87, v94, v87
	v_cndmask_b32_e64 v95, v95, 0, s[22:23]
	v_exp_f32_e32 v89, v89
	v_sub_f32_e32 v90, v90, v131
	v_add_f32_e32 v87, v95, v87
	v_exp_f32_e32 v90, v90
	v_sub_f32_e32 v80, v80, v131
	v_add_f32_e32 v87, v97, v87
	v_cndmask_b32_e64 v98, v96, 0, s[8:9]
	v_exp_f32_e32 v80, v80
	v_sub_f32_e32 v84, v84, v131
	v_add_f32_e32 v87, v98, v87
	v_cndmask_b32_e64 v88, 0, v88, s[6:7]
	v_exp_f32_e32 v84, v84
	v_sub_f32_e32 v82, v82, v131
	v_add_f32_e32 v87, v88, v87
	v_cndmask_b32_e32 v89, 0, v89, vcc
	v_exp_f32_e32 v82, v82
	v_sub_f32_e32 v83, v83, v131
	v_add_f32_e32 v87, v89, v87
	v_cndmask_b32_e64 v90, v90, 0, s[24:25]
	v_exp_f32_e32 v83, v83
	v_sub_f32_e32 v85, v85, v131
	v_sub_f32_e32 v81, v136, v131
	v_add_f32_e32 v87, v90, v87
	v_cndmask_b32_e64 v80, v80, 0, s[12:13]
	v_exp_f32_e32 v85, v85
	v_add_f32_e32 v87, v80, v87
	v_cndmask_b32_e64 v99, v84, 0, s[18:19]
	v_exp_f32_e32 v96, v81
	v_add_f32_e32 v84, v99, v87
	v_cndmask_b32_e64 v82, v82, 0, s[16:17]
	v_add_f32_e32 v84, v82, v84
	v_cndmask_b32_e64 v83, v83, 0, s[14:15]
	v_add_f32_e32 v84, v83, v84
	v_cndmask_b32_e64 v100, v85, 0, s[10:11]
	v_add_f32_e32 v151, v100, v84
	v_cvt_pk_bf16_f32 v84, v86, v91
	v_cvt_pk_bf16_f32 v85, v92, v93
	v_cvt_pk_bf16_f32 v86, v94, v95
	v_cvt_pk_bf16_f32 v87, v97, v98
	v_cvt_pk_bf16_f32 v88, v88, v89
	v_cvt_pk_bf16_f32 v89, v90, v80
	v_cvt_pk_bf16_f32 v90, v99, v82
	v_cvt_pk_bf16_f32 v91, v83, v100
	v_pk_mul_f32 v[82:83], v[146:147], v[96:97] op_sel_hi:[1,0]
	v_pk_mul_f32 v[80:81], v[144:145], v[96:97] op_sel_hi:[1,0]
	v_fmac_f32_e32 v151, v124, v96
	s_nop 0
	s_waitcnt lgkmcnt(0)
	v_mfma_f32_16x16x32_bf16 v[76:79], v[76:79], v[84:87], v[80:83]
	v_mfma_f32_16x16x32_bf16 v[80:83], v[72:75], v[88:91], v[76:79]
	v_mul_f32_e64 v74, v142, v96
	v_mul_f32_e64 v75, v143, v96
	v_pk_mul_f32 v[72:73], v[140:141], v[96:97] op_sel_hi:[1,0]
	s_nop 1
	v_mfma_f32_16x16x32_bf16 v[68:71], v[68:71], v[84:87], v[72:75]
	v_mfma_f32_16x16x32_bf16 v[92:95], v[64:67], v[88:91], v[68:71]
	v_mul_f32_e64 v66, v138, v96
	v_mul_f32_e64 v67, v139, v96
	v_pk_mul_f32 v[64:65], v[134:135], v[96:97] op_sel_hi:[1,0]
	s_nop 1
	v_mfma_f32_16x16x32_bf16 v[60:63], v[60:63], v[84:87], v[64:67]
	v_mfma_f32_16x16x32_bf16 v[104:107], v[56:59], v[88:91], v[60:63]
	v_mul_f32_e64 v58, v132, v96
	v_mul_f32_e64 v59, v133, v96
	v_pk_mul_f32 v[56:57], v[128:129], v[96:97] op_sel_hi:[1,0]
	s_nop 1
	v_mfma_f32_16x16x32_bf16 v[52:55], v[52:55], v[84:87], v[56:59]
	v_mfma_f32_16x16x32_bf16 v[108:111], v[48:51], v[88:91], v[52:55]
	s_andn2_b64 vcc, exec, s[40:41]
	s_cbranch_vccz .LBB0_610
	s_branch .LBB0_611
